# v66 with one static s_setprio 1 for waves 4-7 at entry and all 192 per-phase priority flips removed (section 6.3 lever)
# speedup vs baseline: 1.0044x; 1.0005x over previous
; __device__ __forceinline__ void p0_prologue(Frame& F) {
;     ...
;     transpose_f8_matrix<1, true>(F, F.in[I_F1IN], D, NFF, F.ws + WS_WFI, I8_W);
; __global__ void __launch_bounds__(512, 2) fwd_kernel(Params P) {
;     ...
;     F.tid = threadIdx.x; F.lane = F.tid & 63; F.wave = __builtin_amdgcn_readfirstlane(F.tid >> 6);
;     F.G = gridDim.x; F.gw = blockIdx.x * 8 + F.wave; F.NGW = F.G * 8;
.LBB0_11:
	s_or_b64 exec, exec, s[0:1]
	s_lshr_b32 s0, s86, 6
	s_cmp_ge_u32 s0, 4
	s_cbranch_scc0 .Lprio_done
	s_setprio 1
.Lprio_done:
	s_lshl_b32 s79, s2, 3
	s_add_i32 s94, s0, s79
	s_lshl_b32 s92, s96, 3
	s_cmp_lt_i32 s94, 0xac00
	v_and_b32_e32 v178, 63, v0
	v_writelane_b32 v240, s0, 2
	s_cselect_b64 s[0:1], -1, 0
	v_writelane_b32 v240, s0, 3
	s_cmp_gt_i32 s94, 0xabff
	v_lshrrev_b32_e32 v162, 5, v178
	v_and_b32_e32 v164, 31, v0
	v_lshrrev_b32_e32 v163, 2, v178
	v_lshlrev_b32_e32 v167, 4, v0
	v_and_b32_e32 v165, 60, v178
	v_writelane_b32 v240, s1, 4
	s_cbranch_scc1 .LBB0_20
	s_barrier
	s_load_dwordx2 s[50:51], s[74:75], 0x38
	v_readlane_b32 s16, v240, 2
	v_lshlrev_b32_e32 v212, 4, v178
	v_mov_b32_e32 v216, 0x42fe0000
	s_mov_b32 s36, 0x44fe0000
	s_mov_b32 s37, 0
	s_mov_b32 s38, 0x4b400000
	s_mov_b32 s39, 0
	s_mov_b32 s40, 0xc2fe0000
	s_mov_b32 s41, 0x0c0c0400
	s_mov_b32 s42, 0x05040100
	s_lshl_b32 s17, s16, 5
	s_and_b32 s18, s16, 4
	s_lshl_b32 s18, s18, 5
	s_add_i32 s17, s17, s18
	v_mul_u32_u24_e32 v213, 0x240, v178
	s_lshl_b32 s18, s16, 4
	v_add_u32_e32 v213, s18, v213
	v_lshrrev_b32_e32 v204, 3, v178
	v_and_b32_e32 v205, 7, v178
	s_lshl_b32 s18, s16, 5
	v_add_u32_e32 v206, s18, v204
	v_mul_u32_u24_e32 v214, 0x90, v206
	v_lshl_add_u32 v214, v205, 4, v214
	v_mul_u32_u24_e32 v215, 0x1000, v204
	v_lshl_add_u32 v215, v205, 4, v215
	s_lshl_b32 s16, s16, 4
	s_waitcnt lgkmcnt(0)
	s_add_u32 s44, s90, 0x8300000
	s_addc_u32 s45, s91, 0
	s_mov_b32 s19, s2
	s_cmp_lt_u32 s19, 0xac0
	s_cbranch_scc0 .Lf8t_f1in0_end
	s_mul_hi_u32 s20, s19, 0x2fa0be9
	s_mul_i32 s21, s20, 86
	s_sub_i32 s21, s19, s21
	s_lshl_b32 s60, s20, 7
	s_lshl_b32 s61, s21, 8
	s_add_i32 s24, s60, s16
	s_mul_i32 s24, s24, 0x15800
	s_lshl_b32 s25, s61, 2
	s_add_u32 s24, s24, s25
	s_add_u32 s52, s50, s24
	s_addc_u32 s53, s51, 0
	global_load_dwordx4 v[80:83], v212, s[52:53]
	s_add_u32 s52, s52, 0x15800
	s_addc_u32 s53, s53, 0
	global_load_dwordx4 v[84:87], v212, s[52:53]
	s_add_u32 s52, s52, 0x15800
	s_addc_u32 s53, s53, 0
	global_load_dwordx4 v[88:91], v212, s[52:53]
	s_add_u32 s52, s52, 0x15800
	s_addc_u32 s53, s53, 0
	global_load_dwordx4 v[92:95], v212, s[52:53]
	s_add_u32 s52, s52, 0x15800
	s_addc_u32 s53, s53, 0
	global_load_dwordx4 v[96:99], v212, s[52:53]
	s_add_u32 s52, s52, 0x15800
	s_addc_u32 s53, s53, 0
	global_load_dwordx4 v[100:103], v212, s[52:53]
	s_add_u32 s52, s52, 0x15800
	s_addc_u32 s53, s53, 0
	global_load_dwordx4 v[104:107], v212, s[52:53]
	s_add_u32 s52, s52, 0x15800
	s_addc_u32 s53, s53, 0
	global_load_dwordx4 v[108:111], v212, s[52:53]
	s_add_u32 s52, s52, 0x15800
	s_addc_u32 s53, s53, 0
	global_load_dwordx4 v[112:115], v212, s[52:53]
	s_add_u32 s52, s52, 0x15800
	s_addc_u32 s53, s53, 0
	global_load_dwordx4 v[116:119], v212, s[52:53]
	s_add_u32 s52, s52, 0x15800
	s_addc_u32 s53, s53, 0
	global_load_dwordx4 v[120:123], v212, s[52:53]
	s_add_u32 s52, s52, 0x15800
	s_addc_u32 s53, s53, 0
	global_load_dwordx4 v[124:127], v212, s[52:53]
	s_add_u32 s52, s52, 0x15800
	s_addc_u32 s53, s53, 0
	global_load_dwordx4 v[128:131], v212, s[52:53]
	s_add_u32 s52, s52, 0x15800
	s_addc_u32 s53, s53, 0
	global_load_dwordx4 v[132:135], v212, s[52:53]
	s_add_u32 s52, s52, 0x15800
	s_addc_u32 s53, s53, 0
	global_load_dwordx4 v[136:139], v212, s[52:53]
	s_add_u32 s52, s52, 0x15800
	s_addc_u32 s53, s53, 0
	global_load_dwordx4 v[140:143], v212, s[52:53]
	s_mov_b32 s58, 1

; #define PG8_STAGE(bufoff, gbase, X) do { _Pragma("unroll") for (int _i = 0; _i < 2; ++_i) { \
;         const char* gp_ = (const char*)(gbase) + (_i ? rs##X : (size_t)0); const unsigned la_ = (unsigned)(size_t)(lds + (bufoff) + ldsw + _i * 8192); \
;         asm volatile("s_mov_b32 m0, %2\n\ts_nop 0\n\tglobal_load_lds_dwordx4 %0, %1" :: "v"(voff##X), "s"(gp_), "s"(la_) : "memory", "m0"); } } while (0)
; #define PG8_LDA(dst, b, h) do { _Pragma("unroll") for (int m = 0; m < 4; ++m) _Pragma("unroll") for (int k = 0; k < 2; ++k) dst[m][k] = *(const LAS bf16x8*)(lds + PG8_SA(b, h) + aoff + m * 2048 + k * 1024); } while (0)
; #define PG8_LDB(dst, b, h) do { _Pragma("unroll") for (int n = 0; n < 2; ++n) _Pragma("unroll") for (int k = 0; k < 2; ++k) dst[n][k] = *(const LAS bf16x8*)(lds + PG8_SB(b, h) + boff + n * 2048 + k * 1024); } while (0)
; #define PG8_WAIT_V(n) asm volatile("s_waitcnt vmcnt(" #n ")" ::: "memory")
; #define PG8_WAIT_L(n) asm volatile("s_waitcnt lgkmcnt(" #n ")" ::: "memory")
; #define PG8_BAR __builtin_amdgcn_s_barrier()
; #define PG8_SCHED __builtin_amdgcn_sched_barrier(0)
; template <class Epi>
; __device__ __forceinline__ void gemm_phase(LAS unsigned char* lds, const Gemm g_in, const StaticOrder& S, const Epi& E) {
;     ...
;             PG8_LDB(B0, 0, 0); PG8_LDB(B1, 0, 1); PG8_SCHED; PG8_LDA(At, 0, 0); PG8_STAGE(PG8_SA(1, 1), a1 + hsA, A);
;             PG8_WAIT_V(8); PG8_WAIT_L(0); PG8_BAR; PG8_MMA(0, 0, At, B0); PG8_MMA(0, 1, At, B1); PG8_BAR; PG8_SCHED;
;             PG8_LDA(At, 0, 1); PG8_STAGE(PG8_SB(0, 0), b2, B); PG8_STAGE(PG8_SB(0, 1), b2 + hsB, B); PG8_STAGE(PG8_SA(0, 0), a2, A);
;             PG8_WAIT_V(8); PG8_WAIT_L(0); PG8_BAR; PG8_MMA(1, 0, At, B0); PG8_MMA(1, 1, At, B1); PG8_BAR; PG8_SCHED;
.LBB0_156:
	v_add_u32_e32 v139, 0x10000, v137
	ds_read_b128 v[140:143], v139
	ds_read_b128 v[144:147], v139 offset:1024
	ds_read_b128 v[148:151], v139 offset:2048
	ds_read_b128 v[152:155], v139 offset:3072
	v_add_u32_e32 v139, 0x14000, v137
	ds_read_b128 v[156:159], v139
	ds_read_b128 v[172:175], v139 offset:1024
	ds_read_b128 v[182:185], v139 offset:2048
	ds_read_b128 v[186:189], v139 offset:3072
	s_add_i32 s63, s8, 2
	s_add_u32 s26, s4, 0xfff40080
	s_addc_u32 s9, s5, -1
	s_cmp_eq_u32 s55, s8
	s_cselect_b32 s8, s21, s26
	s_cselect_b32 s9, s19, s9
	s_cselect_b32 s28, s60, s61
	s_cselect_b32 s29, s59, s62
	s_add_u32 s26, s8, 0x80
	s_addc_u32 s27, s9, 0
	ds_read_b128 v[190:193], v138
	ds_read_b128 v[194:197], v138 offset:1024
	ds_read_b128 v[198:201], v138 offset:2048
	ds_read_b128 v[202:205], v138 offset:3072
	ds_read_b128 v[206:209], v138 offset:4096
	ds_read_b128 v[210:213], v138 offset:5120
	ds_read_b128 v[214:217], v138 offset:6144
	ds_read_b128 v[218:221], v138 offset:7168
	s_add_u32 s64, s4, 0xfffc0000
	s_addc_u32 s65, s5, -1
	s_mov_b32 m0, s56
	s_nop 0
	global_load_lds_dwordx4 v1, s[64:65]
	s_nop 0
	s_mov_b32 m0, s57
	s_nop 0
	global_load_lds_dwordx4 v1, s[4:5]
	s_waitcnt vmcnt(8)
	s_waitcnt lgkmcnt(0)
	s_barrier
	s_waitcnt lgkmcnt(7)
	v_mfma_i32_16x16x64_i8 v[126:129], v[140:143], v[190:193], v[126:129]
	v_mfma_i32_16x16x64_i8 v[118:121], v[148:151], v[190:193], v[118:121]
	s_waitcnt lgkmcnt(5)
	v_mfma_i32_16x16x64_i8 v[110:113], v[140:143], v[198:201], v[110:113]
	v_mfma_i32_16x16x64_i8 v[102:105], v[148:151], v[198:201], v[102:105]
	s_waitcnt lgkmcnt(3)
	v_mfma_i32_16x16x64_i8 v[94:97], v[140:143], v[206:209], v[94:97]
	v_mfma_i32_16x16x64_i8 v[86:89], v[148:151], v[206:209], v[86:89]
	s_waitcnt lgkmcnt(1)
	v_mfma_i32_16x16x64_i8 v[78:81], v[140:143], v[214:217], v[78:81]
	v_mfma_i32_16x16x64_i8 v[70:73], v[148:151], v[214:217], v[70:73]
	v_mfma_i32_16x16x64_i8 v[126:129], v[144:147], v[194:197], v[126:129]
	v_mfma_i32_16x16x64_i8 v[118:121], v[152:155], v[194:197], v[118:121]
	v_mfma_i32_16x16x64_i8 v[110:113], v[144:147], v[202:205], v[110:113]
	v_mfma_i32_16x16x64_i8 v[102:105], v[152:155], v[202:205], v[102:105]
	v_mfma_i32_16x16x64_i8 v[94:97], v[144:147], v[210:213], v[94:97]
	v_mfma_i32_16x16x64_i8 v[86:89], v[152:155], v[210:213], v[86:89]
	s_waitcnt lgkmcnt(0)
	v_mfma_i32_16x16x64_i8 v[78:81], v[144:147], v[218:221], v[78:81]
	v_mfma_i32_16x16x64_i8 v[70:73], v[152:155], v[218:221], v[70:73]
	v_mfma_i32_16x16x64_i8 v[122:125], v[156:159], v[190:193], v[122:125]
	v_mfma_i32_16x16x64_i8 v[114:117], v[182:185], v[190:193], v[114:117]
	v_mfma_i32_16x16x64_i8 v[106:109], v[156:159], v[198:201], v[106:109]
	v_mfma_i32_16x16x64_i8 v[98:101], v[182:185], v[198:201], v[98:101]
	v_mfma_i32_16x16x64_i8 v[90:93], v[156:159], v[206:209], v[90:93]
	v_mfma_i32_16x16x64_i8 v[82:85], v[182:185], v[206:209], v[82:85]
	v_mfma_i32_16x16x64_i8 v[74:77], v[156:159], v[214:217], v[74:77]
	v_mfma_i32_16x16x64_i8 v[66:69], v[182:185], v[214:217], v[66:69]
	v_mfma_i32_16x16x64_i8 v[122:125], v[172:175], v[194:197], v[122:125]
	v_mfma_i32_16x16x64_i8 v[114:117], v[186:189], v[194:197], v[114:117]
	v_mfma_i32_16x16x64_i8 v[106:109], v[172:175], v[202:205], v[106:109]
	v_mfma_i32_16x16x64_i8 v[98:101], v[186:189], v[202:205], v[98:101]
	v_mfma_i32_16x16x64_i8 v[90:93], v[172:175], v[210:213], v[90:93]
	v_mfma_i32_16x16x64_i8 v[82:85], v[186:189], v[210:213], v[82:85]
	v_mfma_i32_16x16x64_i8 v[74:77], v[172:175], v[218:221], v[74:77]
	v_mfma_i32_16x16x64_i8 v[66:69], v[186:189], v[218:221], v[66:69]
	s_barrier
	s_add_u32 s64, s28, 0x40000
	ds_read_b128 v[190:193], v138 offset:16384
	ds_read_b128 v[194:197], v138 offset:17408
	ds_read_b128 v[198:201], v138 offset:18432
	ds_read_b128 v[202:205], v138 offset:19456
	ds_read_b128 v[206:209], v138 offset:20480
	ds_read_b128 v[210:213], v138 offset:21504
	ds_read_b128 v[214:217], v138 offset:22528
	ds_read_b128 v[218:221], v138 offset:23552
	s_mov_b32 m0, s38
	s_nop 0
	global_load_lds_dwordx4 v134, s[28:29]
	s_addc_u32 s65, s29, 0
	s_mov_b32 m0, s39
	s_nop 0
	global_load_lds_dwordx4 v134, s[64:65]
	s_add_u32 s64, s28, 0x80000
	s_addc_u32 s65, s29, 0
	s_mov_b32 m0, s40
	s_nop 0
	global_load_lds_dwordx4 v134, s[64:65]
	s_add_u32 s64, s28, 0xc0000
	s_addc_u32 s65, s29, 0
	s_mov_b32 m0, s41
	s_nop 0
	global_load_lds_dwordx4 v134, s[64:65]
	s_add_u32 s64, s8, 0x40000
	s_mov_b32 m0, s37
	s_nop 0
	global_load_lds_dwordx4 v1, s[8:9]
	s_addc_u32 s65, s9, 0
	s_mov_b32 m0, s42
	s_nop 0
	global_load_lds_dwordx4 v1, s[64:65]
	s_waitcnt vmcnt(8)
	s_waitcnt lgkmcnt(0)
	s_barrier
; #define PG8_STAGE(bufoff, gbase, X) do { _Pragma("unroll") for (int _i = 0; _i < 2; ++_i) { \
;         const char* gp_ = (const char*)(gbase) + (_i ? rs##X : (size_t)0); const unsigned la_ = (unsigned)(size_t)(lds + (bufoff) + ldsw + _i * 8192); \
;         asm volatile("s_mov_b32 m0, %2\n\ts_nop 0\n\tglobal_load_lds_dwordx4 %0, %1" :: "v"(voff##X), "s"(gp_), "s"(la_) : "memory", "m0"); } } while (0)
; #define PG8_LDA(dst, b, h) do { _Pragma("unroll") for (int m = 0; m < 4; ++m) _Pragma("unroll") for (int k = 0; k < 2; ++k) dst[m][k] = *(const LAS bf16x8*)(lds + PG8_SA(b, h) + aoff + m * 2048 + k * 1024); } while (0)
; #define PG8_LDB(dst, b, h) do { _Pragma("unroll") for (int n = 0; n < 2; ++n) _Pragma("unroll") for (int k = 0; k < 2; ++k) dst[n][k] = *(const LAS bf16x8*)(lds + PG8_SB(b, h) + boff + n * 2048 + k * 1024); } while (0)
; #define PG8_WAIT_V(n) asm volatile("s_waitcnt vmcnt(" #n ")" ::: "memory")
; #define PG8_WAIT_L(n) asm volatile("s_waitcnt lgkmcnt(" #n ")" ::: "memory")
; #define PG8_BAR __builtin_amdgcn_s_barrier()
; #define PG8_SCHED __builtin_amdgcn_sched_barrier(0)
; template <class Epi>
; __device__ __forceinline__ void gemm_phase(LAS unsigned char* lds, const Gemm g_in, const StaticOrder& S, const Epi& E) {
;     ...
;             PG8_WAIT_V(8); PG8_WAIT_L(0); PG8_BAR; PG8_MMA(0, 0, At, B0); PG8_MMA(0, 1, At, B1); PG8_BAR; PG8_SCHED;
;             PG8_LDA(At, 0, 1); PG8_STAGE(PG8_SB(0, 0), b2, B); PG8_STAGE(PG8_SB(0, 1), b2 + hsB, B); PG8_STAGE(PG8_SA(0, 0), a2, A);
;             PG8_WAIT_V(8); PG8_WAIT_L(0); PG8_BAR; PG8_MMA(1, 0, At, B0); PG8_MMA(1, 1, At, B1); PG8_BAR; PG8_SCHED;
;             PG8_LDB(B0, 1, 0); PG8_LDB(B1, 1, 1); PG8_SCHED; PG8_LDA(At, 1, 0); PG8_STAGE(PG8_SA(0, 1), a2 + hsA, A);
;             PG8_WAIT_V(8); PG8_WAIT_L(0); PG8_BAR; PG8_MMA(0, 0, At, B0); PG8_MMA(0, 1, At, B1); PG8_BAR; PG8_SCHED;
;             PG8_LDA(At, 1, 1); PG8_STAGE(PG8_SB(1, 0), b3, B); PG8_STAGE(PG8_SB(1, 1), b3 + hsB, B); PG8_STAGE(PG8_SA(1, 0), a3, A);
	s_waitcnt lgkmcnt(7)
	v_mfma_i32_16x16x64_i8 v[62:65], v[140:143], v[190:193], v[62:65]
	v_mfma_i32_16x16x64_i8 v[54:57], v[148:151], v[190:193], v[54:57]
	s_waitcnt lgkmcnt(5)
	v_mfma_i32_16x16x64_i8 v[46:49], v[140:143], v[198:201], v[46:49]
	v_mfma_i32_16x16x64_i8 v[38:41], v[148:151], v[198:201], v[38:41]
	s_waitcnt lgkmcnt(3)
	v_mfma_i32_16x16x64_i8 v[30:33], v[140:143], v[206:209], v[30:33]
	v_mfma_i32_16x16x64_i8 v[22:25], v[148:151], v[206:209], v[22:25]
	s_waitcnt lgkmcnt(1)
	v_mfma_i32_16x16x64_i8 v[14:17], v[140:143], v[214:217], v[14:17]
	v_mfma_i32_16x16x64_i8 v[6:9], v[148:151], v[214:217], v[6:9]
	v_mfma_i32_16x16x64_i8 v[62:65], v[144:147], v[194:197], v[62:65]
	v_mfma_i32_16x16x64_i8 v[54:57], v[152:155], v[194:197], v[54:57]
	v_mfma_i32_16x16x64_i8 v[46:49], v[144:147], v[202:205], v[46:49]
	v_mfma_i32_16x16x64_i8 v[38:41], v[152:155], v[202:205], v[38:41]
	v_mfma_i32_16x16x64_i8 v[30:33], v[144:147], v[210:213], v[30:33]
	v_mfma_i32_16x16x64_i8 v[22:25], v[152:155], v[210:213], v[22:25]
	s_waitcnt lgkmcnt(0)
	v_mfma_i32_16x16x64_i8 v[14:17], v[144:147], v[218:221], v[14:17]
	v_mfma_i32_16x16x64_i8 v[6:9], v[152:155], v[218:221], v[6:9]
	v_mfma_i32_16x16x64_i8 v[58:61], v[156:159], v[190:193], v[58:61]
	v_mfma_i32_16x16x64_i8 v[50:53], v[182:185], v[190:193], v[50:53]
	v_mfma_i32_16x16x64_i8 v[42:45], v[156:159], v[198:201], v[42:45]
	v_mfma_i32_16x16x64_i8 v[34:37], v[182:185], v[198:201], v[34:37]
	v_mfma_i32_16x16x64_i8 v[26:29], v[156:159], v[206:209], v[26:29]
	v_mfma_i32_16x16x64_i8 v[18:21], v[182:185], v[206:209], v[18:21]
	v_mfma_i32_16x16x64_i8 v[10:13], v[156:159], v[214:217], v[10:13]
	v_mfma_i32_16x16x64_i8 v[2:5], v[182:185], v[214:217], v[2:5]
	v_mfma_i32_16x16x64_i8 v[58:61], v[172:175], v[194:197], v[58:61]
	v_mfma_i32_16x16x64_i8 v[50:53], v[186:189], v[194:197], v[50:53]
	v_mfma_i32_16x16x64_i8 v[42:45], v[172:175], v[202:205], v[42:45]
	v_mfma_i32_16x16x64_i8 v[34:37], v[186:189], v[202:205], v[34:37]
	v_mfma_i32_16x16x64_i8 v[26:29], v[172:175], v[210:213], v[26:29]
	v_mfma_i32_16x16x64_i8 v[18:21], v[186:189], v[210:213], v[18:21]
	v_mfma_i32_16x16x64_i8 v[10:13], v[172:175], v[218:221], v[10:13]
	v_mfma_i32_16x16x64_i8 v[2:5], v[186:189], v[218:221], v[2:5]
	s_barrier
	v_add_u32_e32 v139, 0x18000, v137
	ds_read_b128 v[140:143], v139
	ds_read_b128 v[144:147], v139 offset:1024
	ds_read_b128 v[148:151], v139 offset:2048
	ds_read_b128 v[152:155], v139 offset:3072
	v_add_u32_e32 v139, 0x1c000, v137
	ds_read_b128 v[156:159], v139
	ds_read_b128 v[172:175], v139 offset:1024
	ds_read_b128 v[182:185], v139 offset:2048
	ds_read_b128 v[186:189], v139 offset:3072
	ds_read_b128 v[190:193], v138 offset:32768
	ds_read_b128 v[194:197], v138 offset:33792
	ds_read_b128 v[198:201], v138 offset:34816
	ds_read_b128 v[202:205], v138 offset:35840
	ds_read_b128 v[206:209], v138 offset:36864
	ds_read_b128 v[210:213], v138 offset:37888
	ds_read_b128 v[214:217], v138 offset:38912
	ds_read_b128 v[218:221], v138 offset:39936
	s_add_u32 s64, s8, 0x80000
	s_addc_u32 s65, s9, 0
	s_mov_b32 m0, s43
	s_nop 0
	global_load_lds_dwordx4 v1, s[64:65]
	s_add_u32 s64, s8, 0xc0000
	s_addc_u32 s65, s9, 0
	s_mov_b32 m0, s44
	s_nop 0
	global_load_lds_dwordx4 v1, s[64:65]
	s_waitcnt vmcnt(8)
	s_waitcnt lgkmcnt(0)
	s_barrier
	s_waitcnt lgkmcnt(7)
	v_mfma_i32_16x16x64_i8 v[126:129], v[140:143], v[190:193], v[126:129]
	v_mfma_i32_16x16x64_i8 v[118:121], v[148:151], v[190:193], v[118:121]
	s_waitcnt lgkmcnt(5)
	v_mfma_i32_16x16x64_i8 v[110:113], v[140:143], v[198:201], v[110:113]
	v_mfma_i32_16x16x64_i8 v[102:105], v[148:151], v[198:201], v[102:105]
	s_waitcnt lgkmcnt(3)
	v_mfma_i32_16x16x64_i8 v[94:97], v[140:143], v[206:209], v[94:97]
	v_mfma_i32_16x16x64_i8 v[86:89], v[148:151], v[206:209], v[86:89]
	s_waitcnt lgkmcnt(1)
	v_mfma_i32_16x16x64_i8 v[78:81], v[140:143], v[214:217], v[78:81]
	v_mfma_i32_16x16x64_i8 v[70:73], v[148:151], v[214:217], v[70:73]
	v_mfma_i32_16x16x64_i8 v[126:129], v[144:147], v[194:197], v[126:129]
	v_mfma_i32_16x16x64_i8 v[118:121], v[152:155], v[194:197], v[118:121]
	v_mfma_i32_16x16x64_i8 v[110:113], v[144:147], v[202:205], v[110:113]
	v_mfma_i32_16x16x64_i8 v[102:105], v[152:155], v[202:205], v[102:105]
	v_mfma_i32_16x16x64_i8 v[94:97], v[144:147], v[210:213], v[94:97]
	v_mfma_i32_16x16x64_i8 v[86:89], v[152:155], v[210:213], v[86:89]
	s_waitcnt lgkmcnt(0)
	v_mfma_i32_16x16x64_i8 v[78:81], v[144:147], v[218:221], v[78:81]
	v_mfma_i32_16x16x64_i8 v[70:73], v[152:155], v[218:221], v[70:73]
	v_mfma_i32_16x16x64_i8 v[122:125], v[156:159], v[190:193], v[122:125]
	v_mfma_i32_16x16x64_i8 v[114:117], v[182:185], v[190:193], v[114:117]
	v_mfma_i32_16x16x64_i8 v[106:109], v[156:159], v[198:201], v[106:109]
	v_mfma_i32_16x16x64_i8 v[98:101], v[182:185], v[198:201], v[98:101]
	v_mfma_i32_16x16x64_i8 v[90:93], v[156:159], v[206:209], v[90:93]
	v_mfma_i32_16x16x64_i8 v[82:85], v[182:185], v[206:209], v[82:85]
	v_mfma_i32_16x16x64_i8 v[74:77], v[156:159], v[214:217], v[74:77]
	v_mfma_i32_16x16x64_i8 v[66:69], v[182:185], v[214:217], v[66:69]
	v_mfma_i32_16x16x64_i8 v[122:125], v[172:175], v[194:197], v[122:125]
	v_mfma_i32_16x16x64_i8 v[114:117], v[186:189], v[194:197], v[114:117]
	v_mfma_i32_16x16x64_i8 v[106:109], v[172:175], v[202:205], v[106:109]
	v_mfma_i32_16x16x64_i8 v[98:101], v[186:189], v[202:205], v[98:101]
	v_mfma_i32_16x16x64_i8 v[90:93], v[172:175], v[210:213], v[90:93]
	v_mfma_i32_16x16x64_i8 v[82:85], v[186:189], v[210:213], v[82:85]
	v_mfma_i32_16x16x64_i8 v[74:77], v[172:175], v[218:221], v[74:77]
	v_mfma_i32_16x16x64_i8 v[66:69], v[186:189], v[218:221], v[66:69]
	s_barrier
; #define PG8_STAGE(bufoff, gbase, X) do { _Pragma("unroll") for (int _i = 0; _i < 2; ++_i) { \
;         const char* gp_ = (const char*)(gbase) + (_i ? rs##X : (size_t)0); const unsigned la_ = (unsigned)(size_t)(lds + (bufoff) + ldsw + _i * 8192); \
;         asm volatile("s_mov_b32 m0, %2\n\ts_nop 0\n\tglobal_load_lds_dwordx4 %0, %1" :: "v"(voff##X), "s"(gp_), "s"(la_) : "memory", "m0"); } } while (0)
; #define PG8_LDA(dst, b, h) do { _Pragma("unroll") for (int m = 0; m < 4; ++m) _Pragma("unroll") for (int k = 0; k < 2; ++k) dst[m][k] = *(const LAS bf16x8*)(lds + PG8_SA(b, h) + aoff + m * 2048 + k * 1024); } while (0)
; #define PG8_LDB(dst, b, h) do { _Pragma("unroll") for (int n = 0; n < 2; ++n) _Pragma("unroll") for (int k = 0; k < 2; ++k) dst[n][k] = *(const LAS bf16x8*)(lds + PG8_SB(b, h) + boff + n * 2048 + k * 1024); } while (0)
; #define PG8_WAIT_V(n) asm volatile("s_waitcnt vmcnt(" #n ")" ::: "memory")
; #define PG8_WAIT_L(n) asm volatile("s_waitcnt lgkmcnt(" #n ")" ::: "memory")
; #define PG8_BAR __builtin_amdgcn_s_barrier()
; #define PG8_SCHED __builtin_amdgcn_sched_barrier(0)
; template <class Epi>
; __device__ __forceinline__ void gemm_phase(LAS unsigned char* lds, const Gemm g_in, const StaticOrder& S, const Epi& E) {
;     ...
;             PG8_LDB(B0, 1, 0); PG8_LDB(B1, 1, 1); PG8_SCHED; PG8_LDA(At, 1, 0); PG8_STAGE(PG8_SA(0, 1), a2 + hsA, A);
;             PG8_WAIT_V(8); PG8_WAIT_L(0); PG8_BAR; PG8_MMA(0, 0, At, B0); PG8_MMA(0, 1, At, B1); PG8_BAR; PG8_SCHED;
;             PG8_LDA(At, 1, 1); PG8_STAGE(PG8_SB(1, 0), b3, B); PG8_STAGE(PG8_SB(1, 1), b3 + hsB, B); PG8_STAGE(PG8_SA(1, 0), a3, A);
;             PG8_WAIT_V(8); PG8_WAIT_L(0); PG8_BAR; PG8_MMA(1, 0, At, B0); PG8_MMA(1, 1, At, B1); PG8_BAR; PG8_SCHED;
;         }
	s_add_u32 s64, s28, 0x80
	s_addc_u32 s65, s29, 0
	ds_read_b128 v[190:193], v138 offset:49152
	ds_read_b128 v[194:197], v138 offset:50176
	ds_read_b128 v[198:201], v138 offset:51200
	ds_read_b128 v[202:205], v138 offset:52224
	ds_read_b128 v[206:209], v138 offset:53248
	ds_read_b128 v[210:213], v138 offset:54272
	ds_read_b128 v[214:217], v138 offset:55296
	ds_read_b128 v[218:221], v138 offset:56320
	s_mov_b32 m0, s47
	s_nop 0
	global_load_lds_dwordx4 v134, s[64:65]
	s_add_u32 s64, s28, 0x40080
	s_addc_u32 s65, s29, 0
	s_mov_b32 m0, s50
	s_nop 0
	global_load_lds_dwordx4 v134, s[64:65]
	s_add_u32 s64, s28, 0x80080
	s_addc_u32 s65, s29, 0
	s_mov_b32 m0, s53
	s_nop 0
	global_load_lds_dwordx4 v134, s[64:65]
	s_add_u32 s28, s28, 0xc0080
	s_addc_u32 s29, s29, 0
	s_mov_b32 m0, s54
	s_nop 0
	global_load_lds_dwordx4 v134, s[28:29]
	s_add_u32 s8, s8, 0x40080
	s_mov_b32 m0, s51
	s_nop 0
	global_load_lds_dwordx4 v1, s[26:27]
	s_addc_u32 s9, s9, 0
	s_mov_b32 m0, s52
	s_nop 0
	global_load_lds_dwordx4 v1, s[8:9]
	s_waitcnt vmcnt(8)
	s_waitcnt lgkmcnt(0)
	s_barrier
	s_waitcnt lgkmcnt(7)
	v_mfma_i32_16x16x64_i8 v[62:65], v[140:143], v[190:193], v[62:65]
	v_mfma_i32_16x16x64_i8 v[54:57], v[148:151], v[190:193], v[54:57]
	s_waitcnt lgkmcnt(5)
	v_mfma_i32_16x16x64_i8 v[46:49], v[140:143], v[198:201], v[46:49]
	v_mfma_i32_16x16x64_i8 v[38:41], v[148:151], v[198:201], v[38:41]
	s_waitcnt lgkmcnt(3)
	v_mfma_i32_16x16x64_i8 v[30:33], v[140:143], v[206:209], v[30:33]
	v_mfma_i32_16x16x64_i8 v[22:25], v[148:151], v[206:209], v[22:25]
	s_waitcnt lgkmcnt(1)
	v_mfma_i32_16x16x64_i8 v[14:17], v[140:143], v[214:217], v[14:17]
	v_mfma_i32_16x16x64_i8 v[6:9], v[148:151], v[214:217], v[6:9]
	v_mfma_i32_16x16x64_i8 v[62:65], v[144:147], v[194:197], v[62:65]
	v_mfma_i32_16x16x64_i8 v[54:57], v[152:155], v[194:197], v[54:57]
	v_mfma_i32_16x16x64_i8 v[46:49], v[144:147], v[202:205], v[46:49]
	v_mfma_i32_16x16x64_i8 v[38:41], v[152:155], v[202:205], v[38:41]
	v_mfma_i32_16x16x64_i8 v[30:33], v[144:147], v[210:213], v[30:33]
	v_mfma_i32_16x16x64_i8 v[22:25], v[152:155], v[210:213], v[22:25]
	s_waitcnt lgkmcnt(0)
	v_mfma_i32_16x16x64_i8 v[14:17], v[144:147], v[218:221], v[14:17]
	v_mfma_i32_16x16x64_i8 v[6:9], v[152:155], v[218:221], v[6:9]
	v_mfma_i32_16x16x64_i8 v[58:61], v[156:159], v[190:193], v[58:61]
	v_mfma_i32_16x16x64_i8 v[50:53], v[182:185], v[190:193], v[50:53]
	v_mfma_i32_16x16x64_i8 v[42:45], v[156:159], v[198:201], v[42:45]
	v_mfma_i32_16x16x64_i8 v[34:37], v[182:185], v[198:201], v[34:37]
	v_mfma_i32_16x16x64_i8 v[26:29], v[156:159], v[206:209], v[26:29]
	v_mfma_i32_16x16x64_i8 v[18:21], v[182:185], v[206:209], v[18:21]
	v_mfma_i32_16x16x64_i8 v[10:13], v[156:159], v[214:217], v[10:13]
	v_mfma_i32_16x16x64_i8 v[2:5], v[182:185], v[214:217], v[2:5]
	v_mfma_i32_16x16x64_i8 v[58:61], v[172:175], v[194:197], v[58:61]
	v_mfma_i32_16x16x64_i8 v[50:53], v[186:189], v[194:197], v[50:53]
	v_mfma_i32_16x16x64_i8 v[42:45], v[172:175], v[202:205], v[42:45]
	v_mfma_i32_16x16x64_i8 v[34:37], v[186:189], v[202:205], v[34:37]
	v_mfma_i32_16x16x64_i8 v[26:29], v[172:175], v[210:213], v[26:29]
	v_mfma_i32_16x16x64_i8 v[18:21], v[186:189], v[210:213], v[18:21]
	v_mfma_i32_16x16x64_i8 v[10:13], v[172:175], v[218:221], v[10:13]
	v_mfma_i32_16x16x64_i8 v[2:5], v[186:189], v[218:221], v[2:5]
	s_barrier
	s_add_u32 s61, s61, 0x100
	s_addc_u32 s62, s62, 0
	s_add_u32 s4, s4, 0x100
	s_addc_u32 s5, s5, 0
	s_cmp_ge_i32 s63, s34
	s_mov_b32 s8, s63
	s_cbranch_scc0 .LBB0_156
	s_and_b64 vcc, exec, s[14:15]
	s_cbranch_vccz .LBB0_159

; #define PG8_STAGE(bufoff, gbase, X) do { _Pragma("unroll") for (int _i = 0; _i < 2; ++_i) { \
;         const char* gp_ = (const char*)(gbase) + (_i ? rs##X : (size_t)0); const unsigned la_ = (unsigned)(size_t)(lds + (bufoff) + ldsw + _i * 8192); \
;         asm volatile("s_mov_b32 m0, %2\n\ts_nop 0\n\tglobal_load_lds_dwordx4 %0, %1" :: "v"(voff##X), "s"(gp_), "s"(la_) : "memory", "m0"); } } while (0)
; #define PG8_LDA(dst, b, h) do { _Pragma("unroll") for (int m = 0; m < 4; ++m) _Pragma("unroll") for (int k = 0; k < 2; ++k) dst[m][k] = *(const LAS bf16x8*)(lds + PG8_SA(b, h) + aoff + m * 2048 + k * 1024); } while (0)
; #define PG8_LDB(dst, b, h) do { _Pragma("unroll") for (int n = 0; n < 2; ++n) _Pragma("unroll") for (int k = 0; k < 2; ++k) dst[n][k] = *(const LAS bf16x8*)(lds + PG8_SB(b, h) + boff + n * 2048 + k * 1024); } while (0)
; #define PG8_WAIT_V(n) asm volatile("s_waitcnt vmcnt(" #n ")" ::: "memory")
; #define PG8_WAIT_L(n) asm volatile("s_waitcnt lgkmcnt(" #n ")" ::: "memory")
; #define PG8_BAR __builtin_amdgcn_s_barrier()
; #define PG8_SCHED __builtin_amdgcn_sched_barrier(0)
; template <class Epi>
; __device__ __forceinline__ void gemm_phase(LAS unsigned char* lds, const Gemm g_in, const StaticOrder& S, const Epi& E) {
;     ...
;             PG8_LDB(B0, 0, 0); PG8_LDB(B1, 0, 1); PG8_SCHED; PG8_LDA(At, 0, 0); PG8_STAGE(PG8_SA(1, 1), a1 + hsA, A);
;             PG8_WAIT_V(8); PG8_WAIT_L(0); PG8_BAR; PG8_MMA(0, 0, At, B0); PG8_MMA(0, 1, At, B1); PG8_BAR; PG8_SCHED;
;             PG8_LDA(At, 0, 1); PG8_STAGE(PG8_SB(0, 0), b2, B); PG8_STAGE(PG8_SB(0, 1), b2 + hsB, B); PG8_STAGE(PG8_SA(0, 0), a2, A);
;             PG8_WAIT_V(8); PG8_WAIT_L(0); PG8_BAR; PG8_MMA(1, 0, At, B0); PG8_MMA(1, 1, At, B1); PG8_BAR; PG8_SCHED;
;             PG8_LDB(B0, 1, 0); PG8_LDB(B1, 1, 1); PG8_SCHED; PG8_LDA(At, 1, 0); PG8_STAGE(PG8_SA(0, 1), a2 + hsA, A);
;             PG8_WAIT_V(8); PG8_WAIT_L(0); PG8_BAR; PG8_MMA(0, 0, At, B0); PG8_MMA(0, 1, At, B1); PG8_BAR; PG8_SCHED;
.LBB0_238:
	ds_read_b128 v[26:29], v235
	ds_read_b128 v[30:33], v235 offset:1024
	ds_read_b128 v[18:21], v235 offset:2048
	ds_read_b128 v[22:25], v235 offset:3072
	ds_read_b128 v[10:13], v236
	ds_read_b128 v[14:17], v236 offset:1024
	ds_read_b128 v[2:5], v236 offset:2048
	ds_read_b128 v[6:9], v236 offset:3072
	s_add_i32 s68, s4, 2
	s_add_u32 s8, s0, 0xffdfc080
	s_addc_u32 s5, s1, -1
	s_cmp_eq_u32 s54, s4
	s_cselect_b32 s4, s12, s8
	s_cselect_b32 s5, s13, s5
	s_cselect_b32 s30, s28, s66
	s_cselect_b32 s31, s29, s67
	s_add_u32 s8, s4, 0x80
	s_addc_u32 s9, s5, 0
	ds_read_b128 v[182:185], v237
	ds_read_b128 v[186:189], v237 offset:1024
	ds_read_b128 v[190:193], v237 offset:2048
	ds_read_b128 v[194:197], v237 offset:3072
	ds_read_b128 v[198:201], v237 offset:4096
	ds_read_b128 v[202:205], v237 offset:5120
	ds_read_b128 v[206:209], v237 offset:6144
	ds_read_b128 v[210:213], v237 offset:7168
	s_add_u32 s70, s0, 0xfff54000
	s_addc_u32 s71, s1, -1
	s_mov_b32 m0, s55
	s_nop 0
	global_load_lds_dwordx4 v1, s[70:71]
	s_nop 0
	s_mov_b32 m0, s56
	s_nop 0
	global_load_lds_dwordx4 v1, s[0:1]
	s_waitcnt vmcnt(8)
	s_waitcnt lgkmcnt(0)
	s_barrier
	s_waitcnt lgkmcnt(0)
	v_mfma_f32_16x16x128_f8f6f4 v[82:85], v[26:33], v[182:189], v[82:85]
	v_mfma_f32_16x16x128_f8f6f4 v[110:113], v[18:25], v[182:189], v[110:113]
	v_mfma_f32_16x16x128_f8f6f4 v[78:81], v[26:33], v[190:197], v[78:81]
	v_mfma_f32_16x16x128_f8f6f4 v[74:77], v[18:25], v[190:197], v[74:77]
	v_mfma_f32_16x16x128_f8f6f4 v[62:65], v[26:33], v[198:205], v[62:65]
	v_mfma_f32_16x16x128_f8f6f4 v[58:61], v[18:25], v[198:205], v[58:61]
	v_mfma_f32_16x16x128_f8f6f4 v[46:49], v[26:33], v[206:213], v[46:49]
	v_mfma_f32_16x16x128_f8f6f4 v[42:45], v[18:25], v[206:213], v[42:45]
	v_mfma_f32_16x16x128_f8f6f4 v[158:161], v[10:17], v[182:189], v[158:161]
	v_mfma_f32_16x16x128_f8f6f4 v[154:157], v[2:9], v[182:189], v[154:157]
	v_mfma_f32_16x16x128_f8f6f4 v[142:145], v[10:17], v[190:197], v[142:145]
	v_mfma_f32_16x16x128_f8f6f4 v[138:141], v[2:9], v[190:197], v[138:141]
	v_mfma_f32_16x16x128_f8f6f4 v[126:129], v[10:17], v[198:205], v[126:129]
	v_mfma_f32_16x16x128_f8f6f4 v[122:125], v[2:9], v[198:205], v[122:125]
	v_mfma_f32_16x16x128_f8f6f4 v[106:109], v[10:17], v[206:213], v[106:109]
	v_mfma_f32_16x16x128_f8f6f4 v[102:105], v[2:9], v[206:213], v[102:105]
	s_barrier
	s_add_u32 s70, s30, 0xac000
	ds_read_b128 v[182:185], v237 offset:16384
	ds_read_b128 v[186:189], v237 offset:17408
	ds_read_b128 v[190:193], v237 offset:18432
	ds_read_b128 v[194:197], v237 offset:19456
	ds_read_b128 v[198:201], v237 offset:20480
	ds_read_b128 v[202:205], v237 offset:21504
	ds_read_b128 v[206:209], v237 offset:22528
	ds_read_b128 v[210:213], v237 offset:23552
	s_mov_b32 m0, s38
	s_nop 0
	global_load_lds_dwordx4 v169, s[30:31]
	s_addc_u32 s71, s31, 0
	s_mov_b32 m0, s39
	s_nop 0
	global_load_lds_dwordx4 v169, s[70:71]
	s_add_u32 s70, s30, 0x158000
	s_addc_u32 s71, s31, 0
	s_mov_b32 m0, s40
	s_nop 0
	global_load_lds_dwordx4 v169, s[70:71]
	s_add_u32 s70, s30, 0x204000
	s_addc_u32 s71, s31, 0
	s_mov_b32 m0, s41
	s_nop 0
	global_load_lds_dwordx4 v169, s[70:71]
	s_add_u32 s70, s4, 0xac000
	s_mov_b32 m0, s37
	s_nop 0
	global_load_lds_dwordx4 v1, s[4:5]
	s_addc_u32 s71, s5, 0
	s_mov_b32 m0, s42
	s_nop 0
	global_load_lds_dwordx4 v1, s[70:71]
	s_waitcnt vmcnt(8)
	s_waitcnt lgkmcnt(0)
	s_barrier
	s_waitcnt lgkmcnt(6)
	v_mfma_f32_16x16x128_f8f6f4 v[98:101], v[26:33], v[182:189], v[98:101]
	v_mfma_f32_16x16x128_f8f6f4 v[94:97], v[18:25], v[182:189], v[94:97]
	s_waitcnt lgkmcnt(4)
	v_mfma_f32_16x16x128_f8f6f4 v[70:73], v[26:33], v[190:197], v[70:73]
	v_mfma_f32_16x16x128_f8f6f4 v[66:69], v[18:25], v[190:197], v[66:69]
	s_waitcnt lgkmcnt(2)
	v_mfma_f32_16x16x128_f8f6f4 v[54:57], v[26:33], v[198:205], v[54:57]
	v_mfma_f32_16x16x128_f8f6f4 v[50:53], v[18:25], v[198:205], v[50:53]
	s_waitcnt lgkmcnt(0)
	v_mfma_f32_16x16x128_f8f6f4 v[38:41], v[26:33], v[206:213], v[38:41]
	v_mfma_f32_16x16x128_f8f6f4 v[34:37], v[18:25], v[206:213], v[34:37]
	v_mfma_f32_16x16x128_f8f6f4 v[150:153], v[10:17], v[182:189], v[150:153]
	v_mfma_f32_16x16x128_f8f6f4 v[146:149], v[2:9], v[182:189], v[146:149]
	v_mfma_f32_16x16x128_f8f6f4 v[134:137], v[10:17], v[190:197], v[134:137]
	v_mfma_f32_16x16x128_f8f6f4 v[130:133], v[2:9], v[190:197], v[130:133]
	v_mfma_f32_16x16x128_f8f6f4 v[118:121], v[10:17], v[198:205], v[118:121]
	v_mfma_f32_16x16x128_f8f6f4 v[114:117], v[2:9], v[198:205], v[114:117]
	v_mfma_f32_16x16x128_f8f6f4 v[90:93], v[10:17], v[206:213], v[90:93]
	v_mfma_f32_16x16x128_f8f6f4 v[86:89], v[2:9], v[206:213], v[86:89]
	s_barrier
	ds_read_b128 v[18:21], v238
	ds_read_b128 v[22:25], v238 offset:1024
	ds_read_b128 v[26:29], v238 offset:2048
	ds_read_b128 v[30:33], v238 offset:3072
	ds_read_b128 v[10:13], v239
	ds_read_b128 v[14:17], v239 offset:1024
	ds_read_b128 v[2:5], v239 offset:2048
	ds_read_b128 v[6:9], v239 offset:3072
	ds_read_b128 v[182:185], v237 offset:32768
	ds_read_b128 v[186:189], v237 offset:33792
	ds_read_b128 v[190:193], v237 offset:34816
	ds_read_b128 v[194:197], v237 offset:35840
	ds_read_b128 v[198:201], v237 offset:36864
	ds_read_b128 v[202:205], v237 offset:37888
	ds_read_b128 v[206:209], v237 offset:38912
	ds_read_b128 v[210:213], v237 offset:39936
	s_add_u32 s70, s4, 0x158000
	s_addc_u32 s71, s5, 0
	s_mov_b32 m0, s44
	s_nop 0
	global_load_lds_dwordx4 v1, s[70:71]
	s_add_u32 s70, s4, 0x204000
	s_addc_u32 s71, s5, 0
	s_mov_b32 m0, s45
	s_nop 0
	global_load_lds_dwordx4 v1, s[70:71]
	s_waitcnt vmcnt(8)
	s_waitcnt lgkmcnt(0)
	s_barrier
; #define PG8_STAGE(bufoff, gbase, X) do { _Pragma("unroll") for (int _i = 0; _i < 2; ++_i) { \
;         const char* gp_ = (const char*)(gbase) + (_i ? rs##X : (size_t)0); const unsigned la_ = (unsigned)(size_t)(lds + (bufoff) + ldsw + _i * 8192); \
;         asm volatile("s_mov_b32 m0, %2\n\ts_nop 0\n\tglobal_load_lds_dwordx4 %0, %1" :: "v"(voff##X), "s"(gp_), "s"(la_) : "memory", "m0"); } } while (0)
; #define PG8_LDA(dst, b, h) do { _Pragma("unroll") for (int m = 0; m < 4; ++m) _Pragma("unroll") for (int k = 0; k < 2; ++k) dst[m][k] = *(const LAS bf16x8*)(lds + PG8_SA(b, h) + aoff + m * 2048 + k * 1024); } while (0)
; #define PG8_WAIT_V(n) asm volatile("s_waitcnt vmcnt(" #n ")" ::: "memory")
; #define PG8_WAIT_L(n) asm volatile("s_waitcnt lgkmcnt(" #n ")" ::: "memory")
; #define PG8_BAR __builtin_amdgcn_s_barrier()
; #define PG8_SCHED __builtin_amdgcn_sched_barrier(0)
; template <class Epi>
; __device__ __forceinline__ void gemm_phase(LAS unsigned char* lds, const Gemm g_in, const StaticOrder& S, const Epi& E) {
;     ...
;             PG8_WAIT_V(8); PG8_WAIT_L(0); PG8_BAR; PG8_MMA(0, 0, At, B0); PG8_MMA(0, 1, At, B1); PG8_BAR; PG8_SCHED;
;             PG8_LDA(At, 1, 1); PG8_STAGE(PG8_SB(1, 0), b3, B); PG8_STAGE(PG8_SB(1, 1), b3 + hsB, B); PG8_STAGE(PG8_SA(1, 0), a3, A);
;             PG8_WAIT_V(8); PG8_WAIT_L(0); PG8_BAR; PG8_MMA(1, 0, At, B0); PG8_MMA(1, 1, At, B1); PG8_BAR; PG8_SCHED;
	s_waitcnt lgkmcnt(6)
	v_mfma_f32_16x16x128_f8f6f4 v[82:85], v[18:25], v[182:189], v[82:85]
	v_mfma_f32_16x16x128_f8f6f4 v[110:113], v[26:33], v[182:189], v[110:113]
	s_waitcnt lgkmcnt(4)
	v_mfma_f32_16x16x128_f8f6f4 v[78:81], v[18:25], v[190:197], v[78:81]
	v_mfma_f32_16x16x128_f8f6f4 v[74:77], v[26:33], v[190:197], v[74:77]
	s_waitcnt lgkmcnt(2)
	v_mfma_f32_16x16x128_f8f6f4 v[62:65], v[18:25], v[198:205], v[62:65]
	v_mfma_f32_16x16x128_f8f6f4 v[58:61], v[26:33], v[198:205], v[58:61]
	s_waitcnt lgkmcnt(0)
	v_mfma_f32_16x16x128_f8f6f4 v[46:49], v[18:25], v[206:213], v[46:49]
	v_mfma_f32_16x16x128_f8f6f4 v[42:45], v[26:33], v[206:213], v[42:45]
	v_mfma_f32_16x16x128_f8f6f4 v[158:161], v[10:17], v[182:189], v[158:161]
	v_mfma_f32_16x16x128_f8f6f4 v[154:157], v[2:9], v[182:189], v[154:157]
	v_mfma_f32_16x16x128_f8f6f4 v[142:145], v[10:17], v[190:197], v[142:145]
	v_mfma_f32_16x16x128_f8f6f4 v[138:141], v[2:9], v[190:197], v[138:141]
	v_mfma_f32_16x16x128_f8f6f4 v[126:129], v[10:17], v[198:205], v[126:129]
	v_mfma_f32_16x16x128_f8f6f4 v[122:125], v[2:9], v[198:205], v[122:125]
	v_mfma_f32_16x16x128_f8f6f4 v[106:109], v[10:17], v[206:213], v[106:109]
	v_mfma_f32_16x16x128_f8f6f4 v[102:105], v[2:9], v[206:213], v[102:105]
	s_barrier
	s_add_u32 s70, s30, 0x80
	s_addc_u32 s71, s31, 0
	ds_read_b128 v[182:185], v237 offset:49152
	ds_read_b128 v[186:189], v237 offset:50176
	ds_read_b128 v[190:193], v237 offset:51200
	ds_read_b128 v[194:197], v237 offset:52224
	ds_read_b128 v[198:201], v237 offset:53248
	ds_read_b128 v[202:205], v237 offset:54272
	ds_read_b128 v[206:209], v237 offset:55296
	ds_read_b128 v[210:213], v237 offset:56320
	s_mov_b32 m0, s46
	s_nop 0
	global_load_lds_dwordx4 v169, s[70:71]
	s_add_u32 s70, s30, 0xac080
	s_addc_u32 s71, s31, 0
	s_mov_b32 m0, s47
	s_nop 0
	global_load_lds_dwordx4 v169, s[70:71]
	s_add_u32 s70, s30, 0x158080
	s_addc_u32 s71, s31, 0
	s_mov_b32 m0, s52
	s_nop 0
	global_load_lds_dwordx4 v169, s[70:71]
	s_add_u32 s30, s30, 0x204080
	s_addc_u32 s31, s31, 0
	s_mov_b32 m0, s53
	s_nop 0
	global_load_lds_dwordx4 v169, s[30:31]
	s_add_u32 s4, s4, 0xac080
	s_mov_b32 m0, s50
	s_nop 0
	global_load_lds_dwordx4 v1, s[8:9]
	s_addc_u32 s5, s5, 0
	s_mov_b32 m0, s51
	s_nop 0
	global_load_lds_dwordx4 v1, s[4:5]
	s_waitcnt vmcnt(8)
	s_waitcnt lgkmcnt(0)
	s_barrier
	s_waitcnt lgkmcnt(6)
	v_mfma_f32_16x16x128_f8f6f4 v[98:101], v[18:25], v[182:189], v[98:101]
	v_mfma_f32_16x16x128_f8f6f4 v[94:97], v[26:33], v[182:189], v[94:97]
	s_waitcnt lgkmcnt(4)
	v_mfma_f32_16x16x128_f8f6f4 v[70:73], v[18:25], v[190:197], v[70:73]
	v_mfma_f32_16x16x128_f8f6f4 v[66:69], v[26:33], v[190:197], v[66:69]
	s_waitcnt lgkmcnt(2)
	v_mfma_f32_16x16x128_f8f6f4 v[54:57], v[18:25], v[198:205], v[54:57]
	v_mfma_f32_16x16x128_f8f6f4 v[50:53], v[26:33], v[198:205], v[50:53]
	s_waitcnt lgkmcnt(0)
	v_mfma_f32_16x16x128_f8f6f4 v[38:41], v[18:25], v[206:213], v[38:41]
	v_mfma_f32_16x16x128_f8f6f4 v[34:37], v[26:33], v[206:213], v[34:37]
	v_mfma_f32_16x16x128_f8f6f4 v[150:153], v[10:17], v[182:189], v[150:153]
	v_mfma_f32_16x16x128_f8f6f4 v[146:149], v[2:9], v[182:189], v[146:149]
	v_mfma_f32_16x16x128_f8f6f4 v[134:137], v[10:17], v[190:197], v[134:137]
	v_mfma_f32_16x16x128_f8f6f4 v[130:133], v[2:9], v[190:197], v[130:133]
	v_mfma_f32_16x16x128_f8f6f4 v[118:121], v[10:17], v[198:205], v[118:121]
	v_mfma_f32_16x16x128_f8f6f4 v[114:117], v[2:9], v[198:205], v[114:117]
	v_mfma_f32_16x16x128_f8f6f4 v[90:93], v[10:17], v[206:213], v[90:93]
	v_mfma_f32_16x16x128_f8f6f4 v[86:89], v[2:9], v[206:213], v[86:89]
	s_barrier
	s_add_u32 s66, s66, 0x100
	s_addc_u32 s67, s67, 0
	s_add_u32 s0, s0, 0x100
	s_addc_u32 s1, s1, 0
	s_cmp_ge_i32 s68, s35
	s_mov_b32 s4, s68
	s_cbranch_scc0 .LBB0_238
;     __device__ __forceinline__ void operator()(const f32x4 (&acc)[2][2][4][2], const Unit& u, int wr, int wc, int fr, int fq) const {
;     ...
;                     for (int bj = 0; bj < 2; ++bj) { f32x4 a0 = acc[ai][bj][m][0], a1 = acc[ai][bj][m][1];
;                         if (IN == 2) { a0 = __builtin_convertvector(__builtin_bit_cast(i32x4, a0), f32x4); a1 = __builtin_convertvector(__builtin_bit_cast(i32x4, a1), f32x4); }
;                         const f32x4 v0 = bv[m][bj][0] * ALPHA + a0 * scale, v1 = bv[m][bj][1] * ALPHA + a1 * scale;
	v_pk_mul_f32 v[232:233], v[84:85], s[24:25] op_sel_hi:[1,0]
	v_pk_mul_f32 v[230:231], v[82:83], s[24:25] op_sel_hi:[1,0]
	v_pk_mul_f32 v[228:229], v[112:113], s[24:25] op_sel_hi:[1,0]
	v_pk_mul_f32 v[226:227], v[110:111], s[24:25] op_sel_hi:[1,0]
	v_pk_mul_f32 v[220:221], v[160:161], s[24:25] op_sel_hi:[1,0]
	v_pk_mul_f32 v[218:219], v[158:159], s[24:25] op_sel_hi:[1,0]
	v_pk_mul_f32 v[214:215], v[156:157], s[24:25] op_sel_hi:[1,0]
	v_pk_mul_f32 v[210:211], v[154:155], s[24:25] op_sel_hi:[1,0]
	v_pk_mul_f32 v[224:225], v[80:81], s[24:25] op_sel_hi:[1,0]
	v_pk_mul_f32 v[222:223], v[78:79], s[24:25] op_sel_hi:[1,0]
	v_pk_mul_f32 v[216:217], v[76:77], s[24:25] op_sel_hi:[1,0]
	v_pk_mul_f32 v[212:213], v[74:75], s[24:25] op_sel_hi:[1,0]
	v_pk_mul_f32 v[204:205], v[144:145], s[24:25] op_sel_hi:[1,0]
	v_pk_mul_f32 v[202:203], v[142:143], s[24:25] op_sel_hi:[1,0]
	v_pk_mul_f32 v[198:199], v[140:141], s[24:25] op_sel_hi:[1,0]
	v_pk_mul_f32 v[194:195], v[138:139], s[24:25] op_sel_hi:[1,0]
	v_pk_mul_f32 v[208:209], v[64:65], s[24:25] op_sel_hi:[1,0]
	v_pk_mul_f32 v[206:207], v[62:63], s[24:25] op_sel_hi:[1,0]
	v_pk_mul_f32 v[200:201], v[60:61], s[24:25] op_sel_hi:[1,0]
	v_pk_mul_f32 v[196:197], v[58:59], s[24:25] op_sel_hi:[1,0]
	v_pk_mul_f32 v[192:193], v[128:129], s[24:25] op_sel_hi:[1,0]
	v_pk_mul_f32 v[190:191], v[126:127], s[24:25] op_sel_hi:[1,0]
	v_pk_mul_f32 v[188:189], v[124:125], s[24:25] op_sel_hi:[1,0]
	v_pk_mul_f32 v[186:187], v[122:123], s[24:25] op_sel_hi:[1,0]
	v_pk_mul_f32 v[184:185], v[48:49], s[24:25] op_sel_hi:[1,0]
	v_pk_mul_f32 v[182:183], v[46:47], s[24:25] op_sel_hi:[1,0]
	v_pk_mul_f32 v[160:161], v[44:45], s[24:25] op_sel_hi:[1,0]
	v_pk_mul_f32 v[158:159], v[42:43], s[24:25] op_sel_hi:[1,0]
	v_pk_mul_f32 v[156:157], v[108:109], s[24:25] op_sel_hi:[1,0]
	v_pk_mul_f32 v[154:155], v[106:107], s[24:25] op_sel_hi:[1,0]
	v_pk_mul_f32 v[144:145], v[104:105], s[24:25] op_sel_hi:[1,0]
	v_pk_mul_f32 v[142:143], v[102:103], s[24:25] op_sel_hi:[1,0]
	v_pk_mul_f32 v[140:141], v[100:101], s[24:25] op_sel_hi:[1,0]
	v_pk_mul_f32 v[138:139], v[98:99], s[24:25] op_sel_hi:[1,0]
	v_pk_mul_f32 v[128:129], v[96:97], s[24:25] op_sel_hi:[1,0]
	v_pk_mul_f32 v[126:127], v[94:95], s[24:25] op_sel_hi:[1,0]
	v_pk_mul_f32 v[112:113], v[152:153], s[24:25] op_sel_hi:[1,0]
	v_pk_mul_f32 v[110:111], v[150:151], s[24:25] op_sel_hi:[1,0]
	v_pk_mul_f32 v[106:107], v[148:149], s[24:25] op_sel_hi:[1,0]
	v_pk_mul_f32 v[102:103], v[146:147], s[24:25] op_sel_hi:[1,0]
	v_pk_mul_f32 v[124:125], v[72:73], s[24:25] op_sel_hi:[1,0]
	v_pk_mul_f32 v[122:123], v[70:71], s[24:25] op_sel_hi:[1,0]
	v_pk_mul_f32 v[108:109], v[68:69], s[24:25] op_sel_hi:[1,0]
	v_pk_mul_f32 v[104:105], v[66:67], s[24:25] op_sel_hi:[1,0]
	v_pk_mul_f32 v[96:97], v[136:137], s[24:25] op_sel_hi:[1,0]
	v_pk_mul_f32 v[94:95], v[134:135], s[24:25] op_sel_hi:[1,0]
	v_pk_mul_f32 v[82:83], v[132:133], s[24:25] op_sel_hi:[1,0]
	v_pk_mul_f32 v[78:79], v[130:131], s[24:25] op_sel_hi:[1,0]
	v_pk_mul_f32 v[100:101], v[56:57], s[24:25] op_sel_hi:[1,0]
	v_pk_mul_f32 v[98:99], v[54:55], s[24:25] op_sel_hi:[1,0]
	v_pk_mul_f32 v[84:85], v[52:53], s[24:25] op_sel_hi:[1,0]
	v_pk_mul_f32 v[80:81], v[50:51], s[24:25] op_sel_hi:[1,0]
	v_pk_mul_f32 v[76:77], v[120:121], s[24:25] op_sel_hi:[1,0]
	v_pk_mul_f32 v[74:75], v[118:119], s[24:25] op_sel_hi:[1,0]
	v_pk_mul_f32 v[72:73], v[116:117], s[24:25] op_sel_hi:[1,0]
	v_pk_mul_f32 v[70:71], v[114:115], s[24:25] op_sel_hi:[1,0]
	v_pk_mul_f32 v[68:69], v[40:41], s[24:25] op_sel_hi:[1,0]
	v_pk_mul_f32 v[66:67], v[38:39], s[24:25] op_sel_hi:[1,0]
	v_pk_mul_f32 v[64:65], v[36:37], s[24:25] op_sel_hi:[1,0]
	v_pk_mul_f32 v[62:63], v[34:35], s[24:25] op_sel_hi:[1,0]
	v_pk_mul_f32 v[60:61], v[92:93], s[24:25] op_sel_hi:[1,0]
	v_pk_mul_f32 v[58:59], v[90:91], s[24:25] op_sel_hi:[1,0]
	v_pk_mul_f32 v[56:57], v[88:89], s[24:25] op_sel_hi:[1,0]
	v_pk_mul_f32 v[54:55], v[86:87], s[24:25] op_sel_hi:[1,0]
	s_and_b64 vcc, exec, s[22:23]
	s_cbranch_vccz .LBB0_241

; #define PG8_STAGE(bufoff, gbase, X) do { _Pragma("unroll") for (int _i = 0; _i < 2; ++_i) { \
;         const char* gp_ = (const char*)(gbase) + (_i ? rs##X : (size_t)0); const unsigned la_ = (unsigned)(size_t)(lds + (bufoff) + ldsw + _i * 8192); \
;         asm volatile("s_mov_b32 m0, %2\n\ts_nop 0\n\tglobal_load_lds_dwordx4 %0, %1" :: "v"(voff##X), "s"(gp_), "s"(la_) : "memory", "m0"); } } while (0)
; #define PG8_LDA(dst, b, h) do { _Pragma("unroll") for (int m = 0; m < 4; ++m) _Pragma("unroll") for (int k = 0; k < 2; ++k) dst[m][k] = *(const LAS bf16x8*)(lds + PG8_SA(b, h) + aoff + m * 2048 + k * 1024); } while (0)
; #define PG8_LDB(dst, b, h) do { _Pragma("unroll") for (int n = 0; n < 2; ++n) _Pragma("unroll") for (int k = 0; k < 2; ++k) dst[n][k] = *(const LAS bf16x8*)(lds + PG8_SB(b, h) + boff + n * 2048 + k * 1024); } while (0)
; #define PG8_WAIT_V(n) asm volatile("s_waitcnt vmcnt(" #n ")" ::: "memory")
; #define PG8_WAIT_L(n) asm volatile("s_waitcnt lgkmcnt(" #n ")" ::: "memory")
; #define PG8_BAR __builtin_amdgcn_s_barrier()
; #define PG8_SCHED __builtin_amdgcn_sched_barrier(0)
; template <class Epi>
; __device__ __forceinline__ void gemm_phase(LAS unsigned char* lds, const Gemm g_in, const StaticOrder& S, const Epi& E) {
;     ...
;             PG8_LDB(B0, 0, 0); PG8_LDB(B1, 0, 1); PG8_SCHED; PG8_LDA(At, 0, 0); PG8_STAGE(PG8_SA(1, 1), a1 + hsA, A);
;             PG8_WAIT_V(8); PG8_WAIT_L(0); PG8_BAR; PG8_MMA(0, 0, At, B0); PG8_MMA(0, 1, At, B1); PG8_BAR; PG8_SCHED;
;             PG8_LDA(At, 0, 1); PG8_STAGE(PG8_SB(0, 0), b2, B); PG8_STAGE(PG8_SB(0, 1), b2 + hsB, B); PG8_STAGE(PG8_SA(0, 0), a2, A);
;             PG8_WAIT_V(8); PG8_WAIT_L(0); PG8_BAR; PG8_MMA(1, 0, At, B0); PG8_MMA(1, 1, At, B1); PG8_BAR; PG8_SCHED;
.LBB0_388:
	ds_read_b128 v[142:145], v137
	ds_read_b128 v[146:149], v137 offset:1024
	ds_read_b128 v[150:153], v137 offset:2048
	ds_read_b128 v[154:157], v137 offset:3072
	ds_read_b128 v[158:161], v138
	ds_read_b128 v[170:173], v138 offset:1024
	ds_read_b128 v[174:177], v138 offset:2048
	ds_read_b128 v[184:187], v138 offset:3072
	s_add_i32 s62, s22, 2
	s_add_u32 s24, s20, 0xffe80080
	s_addc_u32 s23, s21, -1
	s_cmp_eq_u32 s54, s22
	s_cselect_b32 s22, s15, s24
	s_cselect_b32 s23, s13, s23
	s_cselect_b32 s26, s59, s60
	s_cselect_b32 s27, s58, s61
	s_add_u32 s24, s22, 0x80
	s_addc_u32 s25, s23, 0
	ds_read_b128 v[188:191], v139
	ds_read_b128 v[192:195], v139 offset:1024
	ds_read_b128 v[196:199], v139 offset:2048
	ds_read_b128 v[204:207], v139 offset:3072
	ds_read_b128 v[208:211], v139 offset:4096
	ds_read_b128 v[212:215], v139 offset:5120
	ds_read_b128 v[216:219], v139 offset:6144
	ds_read_b128 v[220:223], v139 offset:7168
	s_add_u32 s64, s20, 0xfff80000
	s_addc_u32 s65, s21, -1
	s_mov_b32 m0, s55
	s_nop 0
	global_load_lds_dwordx4 v1, s[64:65]
	s_nop 0
	s_mov_b32 m0, s56
	s_nop 0
	global_load_lds_dwordx4 v1, s[20:21]
	s_waitcnt vmcnt(8)
	s_waitcnt lgkmcnt(0)
	s_barrier
	s_waitcnt lgkmcnt(7)
	v_mfma_f32_16x16x32_bf16 v[126:129], v[142:145], v[188:191], v[126:129]
	v_mfma_f32_16x16x32_bf16 v[122:125], v[150:153], v[188:191], v[122:125]
	s_waitcnt lgkmcnt(5)
	v_mfma_f32_16x16x32_bf16 v[110:113], v[142:145], v[196:199], v[110:113]
	v_mfma_f32_16x16x32_bf16 v[106:109], v[150:153], v[196:199], v[106:109]
	s_waitcnt lgkmcnt(3)
	v_mfma_f32_16x16x32_bf16 v[94:97], v[142:145], v[208:211], v[94:97]
	v_mfma_f32_16x16x32_bf16 v[90:93], v[150:153], v[208:211], v[90:93]
	s_waitcnt lgkmcnt(1)
	v_mfma_f32_16x16x32_bf16 v[78:81], v[142:145], v[216:219], v[78:81]
	v_mfma_f32_16x16x32_bf16 v[74:77], v[150:153], v[216:219], v[74:77]
	v_mfma_f32_16x16x32_bf16 v[126:129], v[146:149], v[192:195], v[126:129]
	v_mfma_f32_16x16x32_bf16 v[122:125], v[154:157], v[192:195], v[122:125]
	v_mfma_f32_16x16x32_bf16 v[110:113], v[146:149], v[204:207], v[110:113]
	v_mfma_f32_16x16x32_bf16 v[106:109], v[154:157], v[204:207], v[106:109]
	v_mfma_f32_16x16x32_bf16 v[94:97], v[146:149], v[212:215], v[94:97]
	v_mfma_f32_16x16x32_bf16 v[90:93], v[154:157], v[212:215], v[90:93]
	s_waitcnt lgkmcnt(0)
	v_mfma_f32_16x16x32_bf16 v[78:81], v[146:149], v[220:223], v[78:81]
	v_mfma_f32_16x16x32_bf16 v[74:77], v[154:157], v[220:223], v[74:77]
	v_mfma_f32_16x16x32_bf16 v[118:121], v[158:161], v[188:191], v[118:121]
	v_mfma_f32_16x16x32_bf16 v[114:117], v[174:177], v[188:191], v[114:117]
	v_mfma_f32_16x16x32_bf16 v[102:105], v[158:161], v[196:199], v[102:105]
	v_mfma_f32_16x16x32_bf16 v[98:101], v[174:177], v[196:199], v[98:101]
	v_mfma_f32_16x16x32_bf16 v[86:89], v[158:161], v[208:211], v[86:89]
	v_mfma_f32_16x16x32_bf16 v[82:85], v[174:177], v[208:211], v[82:85]
	v_mfma_f32_16x16x32_bf16 v[70:73], v[158:161], v[216:219], v[70:73]
	v_mfma_f32_16x16x32_bf16 v[66:69], v[174:177], v[216:219], v[66:69]
	v_mfma_f32_16x16x32_bf16 v[118:121], v[170:173], v[192:195], v[118:121]
	v_mfma_f32_16x16x32_bf16 v[114:117], v[184:187], v[192:195], v[114:117]
	v_mfma_f32_16x16x32_bf16 v[102:105], v[170:173], v[204:207], v[102:105]
	v_mfma_f32_16x16x32_bf16 v[98:101], v[184:187], v[204:207], v[98:101]
	v_mfma_f32_16x16x32_bf16 v[86:89], v[170:173], v[212:215], v[86:89]
	v_mfma_f32_16x16x32_bf16 v[82:85], v[184:187], v[212:215], v[82:85]
	v_mfma_f32_16x16x32_bf16 v[70:73], v[170:173], v[220:223], v[70:73]
	v_mfma_f32_16x16x32_bf16 v[66:69], v[184:187], v[220:223], v[66:69]
	s_barrier
	s_add_u32 s64, s26, 0x80000
	ds_read_b128 v[188:191], v139 offset:16384
	ds_read_b128 v[192:195], v139 offset:17408
	ds_read_b128 v[196:199], v139 offset:18432
	ds_read_b128 v[204:207], v139 offset:19456
	ds_read_b128 v[208:211], v139 offset:20480
	ds_read_b128 v[212:215], v139 offset:21504
	ds_read_b128 v[216:219], v139 offset:22528
	ds_read_b128 v[220:223], v139 offset:23552
	s_mov_b32 m0, s37
	s_nop 0
	global_load_lds_dwordx4 v134, s[26:27]
	s_addc_u32 s65, s27, 0
	s_mov_b32 m0, s38
	s_nop 0
	global_load_lds_dwordx4 v134, s[64:65]
	s_add_u32 s64, s26, 0x100000
	s_addc_u32 s65, s27, 0
	s_mov_b32 m0, s39
	s_nop 0
	global_load_lds_dwordx4 v134, s[64:65]
	s_add_u32 s64, s26, 0x180000
	s_addc_u32 s65, s27, 0
	s_mov_b32 m0, s40
	s_nop 0
	global_load_lds_dwordx4 v134, s[64:65]
	s_add_u32 s64, s22, 0x80000
	s_mov_b32 m0, s36
	s_nop 0
	global_load_lds_dwordx4 v1, s[22:23]
	s_addc_u32 s65, s23, 0
	s_mov_b32 m0, s41
	s_nop 0
	global_load_lds_dwordx4 v1, s[64:65]
	s_waitcnt vmcnt(8)
	s_waitcnt lgkmcnt(0)
	s_barrier
; #define PG8_STAGE(bufoff, gbase, X) do { _Pragma("unroll") for (int _i = 0; _i < 2; ++_i) { \
;         const char* gp_ = (const char*)(gbase) + (_i ? rs##X : (size_t)0); const unsigned la_ = (unsigned)(size_t)(lds + (bufoff) + ldsw + _i * 8192); \
;         asm volatile("s_mov_b32 m0, %2\n\ts_nop 0\n\tglobal_load_lds_dwordx4 %0, %1" :: "v"(voff##X), "s"(gp_), "s"(la_) : "memory", "m0"); } } while (0)
; #define PG8_LDA(dst, b, h) do { _Pragma("unroll") for (int m = 0; m < 4; ++m) _Pragma("unroll") for (int k = 0; k < 2; ++k) dst[m][k] = *(const LAS bf16x8*)(lds + PG8_SA(b, h) + aoff + m * 2048 + k * 1024); } while (0)
; #define PG8_LDB(dst, b, h) do { _Pragma("unroll") for (int n = 0; n < 2; ++n) _Pragma("unroll") for (int k = 0; k < 2; ++k) dst[n][k] = *(const LAS bf16x8*)(lds + PG8_SB(b, h) + boff + n * 2048 + k * 1024); } while (0)
; #define PG8_WAIT_V(n) asm volatile("s_waitcnt vmcnt(" #n ")" ::: "memory")
; #define PG8_WAIT_L(n) asm volatile("s_waitcnt lgkmcnt(" #n ")" ::: "memory")
; #define PG8_BAR __builtin_amdgcn_s_barrier()
; #define PG8_SCHED __builtin_amdgcn_sched_barrier(0)
; template <class Epi>
; __device__ __forceinline__ void gemm_phase(LAS unsigned char* lds, const Gemm g_in, const StaticOrder& S, const Epi& E) {
;     ...
;             PG8_WAIT_V(8); PG8_WAIT_L(0); PG8_BAR; PG8_MMA(0, 0, At, B0); PG8_MMA(0, 1, At, B1); PG8_BAR; PG8_SCHED;
;             PG8_LDA(At, 0, 1); PG8_STAGE(PG8_SB(0, 0), b2, B); PG8_STAGE(PG8_SB(0, 1), b2 + hsB, B); PG8_STAGE(PG8_SA(0, 0), a2, A);
;             PG8_WAIT_V(8); PG8_WAIT_L(0); PG8_BAR; PG8_MMA(1, 0, At, B0); PG8_MMA(1, 1, At, B1); PG8_BAR; PG8_SCHED;
;             PG8_LDB(B0, 1, 0); PG8_LDB(B1, 1, 1); PG8_SCHED; PG8_LDA(At, 1, 0); PG8_STAGE(PG8_SA(0, 1), a2 + hsA, A);
;             PG8_WAIT_V(8); PG8_WAIT_L(0); PG8_BAR; PG8_MMA(0, 0, At, B0); PG8_MMA(0, 1, At, B1); PG8_BAR; PG8_SCHED;
;             PG8_LDA(At, 1, 1); PG8_STAGE(PG8_SB(1, 0), b3, B); PG8_STAGE(PG8_SB(1, 1), b3 + hsB, B); PG8_STAGE(PG8_SA(1, 0), a3, A);
	s_waitcnt lgkmcnt(7)
	v_mfma_f32_16x16x32_bf16 v[62:65], v[142:145], v[188:191], v[62:65]
	v_mfma_f32_16x16x32_bf16 v[58:61], v[150:153], v[188:191], v[58:61]
	s_waitcnt lgkmcnt(5)
	v_mfma_f32_16x16x32_bf16 v[46:49], v[142:145], v[196:199], v[46:49]
	v_mfma_f32_16x16x32_bf16 v[42:45], v[150:153], v[196:199], v[42:45]
	s_waitcnt lgkmcnt(3)
	v_mfma_f32_16x16x32_bf16 v[30:33], v[142:145], v[208:211], v[30:33]
	v_mfma_f32_16x16x32_bf16 v[26:29], v[150:153], v[208:211], v[26:29]
	s_waitcnt lgkmcnt(1)
	v_mfma_f32_16x16x32_bf16 v[14:17], v[142:145], v[216:219], v[14:17]
	v_mfma_f32_16x16x32_bf16 v[10:13], v[150:153], v[216:219], v[10:13]
	v_mfma_f32_16x16x32_bf16 v[62:65], v[146:149], v[192:195], v[62:65]
	v_mfma_f32_16x16x32_bf16 v[58:61], v[154:157], v[192:195], v[58:61]
	v_mfma_f32_16x16x32_bf16 v[46:49], v[146:149], v[204:207], v[46:49]
	v_mfma_f32_16x16x32_bf16 v[42:45], v[154:157], v[204:207], v[42:45]
	v_mfma_f32_16x16x32_bf16 v[30:33], v[146:149], v[212:215], v[30:33]
	v_mfma_f32_16x16x32_bf16 v[26:29], v[154:157], v[212:215], v[26:29]
	s_waitcnt lgkmcnt(0)
	v_mfma_f32_16x16x32_bf16 v[14:17], v[146:149], v[220:223], v[14:17]
	v_mfma_f32_16x16x32_bf16 v[10:13], v[154:157], v[220:223], v[10:13]
	v_mfma_f32_16x16x32_bf16 v[54:57], v[158:161], v[188:191], v[54:57]
	v_mfma_f32_16x16x32_bf16 v[50:53], v[174:177], v[188:191], v[50:53]
	v_mfma_f32_16x16x32_bf16 v[38:41], v[158:161], v[196:199], v[38:41]
	v_mfma_f32_16x16x32_bf16 v[34:37], v[174:177], v[196:199], v[34:37]
	v_mfma_f32_16x16x32_bf16 v[22:25], v[158:161], v[208:211], v[22:25]
	v_mfma_f32_16x16x32_bf16 v[18:21], v[174:177], v[208:211], v[18:21]
	v_mfma_f32_16x16x32_bf16 v[6:9], v[158:161], v[216:219], v[6:9]
	v_mfma_f32_16x16x32_bf16 v[2:5], v[174:177], v[216:219], v[2:5]
	v_mfma_f32_16x16x32_bf16 v[54:57], v[170:173], v[192:195], v[54:57]
	v_mfma_f32_16x16x32_bf16 v[50:53], v[184:187], v[192:195], v[50:53]
	v_mfma_f32_16x16x32_bf16 v[38:41], v[170:173], v[204:207], v[38:41]
	v_mfma_f32_16x16x32_bf16 v[34:37], v[184:187], v[204:207], v[34:37]
	v_mfma_f32_16x16x32_bf16 v[22:25], v[170:173], v[212:215], v[22:25]
	v_mfma_f32_16x16x32_bf16 v[18:21], v[184:187], v[212:215], v[18:21]
	v_mfma_f32_16x16x32_bf16 v[6:9], v[170:173], v[220:223], v[6:9]
	v_mfma_f32_16x16x32_bf16 v[2:5], v[184:187], v[220:223], v[2:5]
	s_barrier
	ds_read_b128 v[142:145], v140
	ds_read_b128 v[146:149], v140 offset:1024
	ds_read_b128 v[150:153], v140 offset:2048
	ds_read_b128 v[154:157], v140 offset:3072
	ds_read_b128 v[158:161], v141
	ds_read_b128 v[170:173], v141 offset:1024
	ds_read_b128 v[174:177], v141 offset:2048
	ds_read_b128 v[184:187], v141 offset:3072
	ds_read_b128 v[188:191], v139 offset:32768
	ds_read_b128 v[192:195], v139 offset:33792
	ds_read_b128 v[196:199], v139 offset:34816
	ds_read_b128 v[204:207], v139 offset:35840
	ds_read_b128 v[208:211], v139 offset:36864
	ds_read_b128 v[212:215], v139 offset:37888
	ds_read_b128 v[216:219], v139 offset:38912
	ds_read_b128 v[220:223], v139 offset:39936
	s_add_u32 s64, s22, 0x100000
	s_addc_u32 s65, s23, 0
	s_mov_b32 m0, s42
	s_nop 0
	global_load_lds_dwordx4 v1, s[64:65]
	s_add_u32 s64, s22, 0x180000
	s_addc_u32 s65, s23, 0
	s_mov_b32 m0, s43
	s_nop 0
	global_load_lds_dwordx4 v1, s[64:65]
	s_waitcnt vmcnt(8)
	s_waitcnt lgkmcnt(0)
	s_barrier
	s_waitcnt lgkmcnt(7)
	v_mfma_f32_16x16x32_bf16 v[126:129], v[142:145], v[188:191], v[126:129]
	v_mfma_f32_16x16x32_bf16 v[122:125], v[150:153], v[188:191], v[122:125]
	s_waitcnt lgkmcnt(5)
	v_mfma_f32_16x16x32_bf16 v[110:113], v[142:145], v[196:199], v[110:113]
	v_mfma_f32_16x16x32_bf16 v[106:109], v[150:153], v[196:199], v[106:109]
	s_waitcnt lgkmcnt(3)
	v_mfma_f32_16x16x32_bf16 v[94:97], v[142:145], v[208:211], v[94:97]
	v_mfma_f32_16x16x32_bf16 v[90:93], v[150:153], v[208:211], v[90:93]
	s_waitcnt lgkmcnt(1)
	v_mfma_f32_16x16x32_bf16 v[78:81], v[142:145], v[216:219], v[78:81]
	v_mfma_f32_16x16x32_bf16 v[74:77], v[150:153], v[216:219], v[74:77]
	v_mfma_f32_16x16x32_bf16 v[126:129], v[146:149], v[192:195], v[126:129]
	v_mfma_f32_16x16x32_bf16 v[122:125], v[154:157], v[192:195], v[122:125]
	v_mfma_f32_16x16x32_bf16 v[110:113], v[146:149], v[204:207], v[110:113]
	v_mfma_f32_16x16x32_bf16 v[106:109], v[154:157], v[204:207], v[106:109]
	v_mfma_f32_16x16x32_bf16 v[94:97], v[146:149], v[212:215], v[94:97]
	v_mfma_f32_16x16x32_bf16 v[90:93], v[154:157], v[212:215], v[90:93]
	s_waitcnt lgkmcnt(0)
	v_mfma_f32_16x16x32_bf16 v[78:81], v[146:149], v[220:223], v[78:81]
	v_mfma_f32_16x16x32_bf16 v[74:77], v[154:157], v[220:223], v[74:77]
	v_mfma_f32_16x16x32_bf16 v[118:121], v[158:161], v[188:191], v[118:121]
	v_mfma_f32_16x16x32_bf16 v[114:117], v[174:177], v[188:191], v[114:117]
	v_mfma_f32_16x16x32_bf16 v[102:105], v[158:161], v[196:199], v[102:105]
	v_mfma_f32_16x16x32_bf16 v[98:101], v[174:177], v[196:199], v[98:101]
	v_mfma_f32_16x16x32_bf16 v[86:89], v[158:161], v[208:211], v[86:89]
	v_mfma_f32_16x16x32_bf16 v[82:85], v[174:177], v[208:211], v[82:85]
	v_mfma_f32_16x16x32_bf16 v[70:73], v[158:161], v[216:219], v[70:73]
	v_mfma_f32_16x16x32_bf16 v[66:69], v[174:177], v[216:219], v[66:69]
	v_mfma_f32_16x16x32_bf16 v[118:121], v[170:173], v[192:195], v[118:121]
	v_mfma_f32_16x16x32_bf16 v[114:117], v[184:187], v[192:195], v[114:117]
	v_mfma_f32_16x16x32_bf16 v[102:105], v[170:173], v[204:207], v[102:105]
	v_mfma_f32_16x16x32_bf16 v[98:101], v[184:187], v[204:207], v[98:101]
	v_mfma_f32_16x16x32_bf16 v[86:89], v[170:173], v[212:215], v[86:89]
	v_mfma_f32_16x16x32_bf16 v[82:85], v[184:187], v[212:215], v[82:85]
	v_mfma_f32_16x16x32_bf16 v[70:73], v[170:173], v[220:223], v[70:73]
	v_mfma_f32_16x16x32_bf16 v[66:69], v[184:187], v[220:223], v[66:69]
	s_barrier
; #define PG8_STAGE(bufoff, gbase, X) do { _Pragma("unroll") for (int _i = 0; _i < 2; ++_i) { \
;         const char* gp_ = (const char*)(gbase) + (_i ? rs##X : (size_t)0); const unsigned la_ = (unsigned)(size_t)(lds + (bufoff) + ldsw + _i * 8192); \
;         asm volatile("s_mov_b32 m0, %2\n\ts_nop 0\n\tglobal_load_lds_dwordx4 %0, %1" :: "v"(voff##X), "s"(gp_), "s"(la_) : "memory", "m0"); } } while (0)
; #define PG8_LDA(dst, b, h) do { _Pragma("unroll") for (int m = 0; m < 4; ++m) _Pragma("unroll") for (int k = 0; k < 2; ++k) dst[m][k] = *(const LAS bf16x8*)(lds + PG8_SA(b, h) + aoff + m * 2048 + k * 1024); } while (0)
; #define PG8_LDB(dst, b, h) do { _Pragma("unroll") for (int n = 0; n < 2; ++n) _Pragma("unroll") for (int k = 0; k < 2; ++k) dst[n][k] = *(const LAS bf16x8*)(lds + PG8_SB(b, h) + boff + n * 2048 + k * 1024); } while (0)
; #define PG8_WAIT_V(n) asm volatile("s_waitcnt vmcnt(" #n ")" ::: "memory")
; #define PG8_WAIT_L(n) asm volatile("s_waitcnt lgkmcnt(" #n ")" ::: "memory")
; #define PG8_BAR __builtin_amdgcn_s_barrier()
; #define PG8_SCHED __builtin_amdgcn_sched_barrier(0)
; template <class Epi>
; __device__ __forceinline__ void gemm_phase(LAS unsigned char* lds, const Gemm g_in, const StaticOrder& S, const Epi& E) {
;     ...
;             PG8_LDB(B0, 1, 0); PG8_LDB(B1, 1, 1); PG8_SCHED; PG8_LDA(At, 1, 0); PG8_STAGE(PG8_SA(0, 1), a2 + hsA, A);
;             PG8_WAIT_V(8); PG8_WAIT_L(0); PG8_BAR; PG8_MMA(0, 0, At, B0); PG8_MMA(0, 1, At, B1); PG8_BAR; PG8_SCHED;
;             PG8_LDA(At, 1, 1); PG8_STAGE(PG8_SB(1, 0), b3, B); PG8_STAGE(PG8_SB(1, 1), b3 + hsB, B); PG8_STAGE(PG8_SA(1, 0), a3, A);
;             PG8_WAIT_V(8); PG8_WAIT_L(0); PG8_BAR; PG8_MMA(1, 0, At, B0); PG8_MMA(1, 1, At, B1); PG8_BAR; PG8_SCHED;
;         }
	s_add_u32 s64, s26, 0x80
	s_addc_u32 s65, s27, 0
	ds_read_b128 v[188:191], v139 offset:49152
	ds_read_b128 v[192:195], v139 offset:50176
	ds_read_b128 v[196:199], v139 offset:51200
	ds_read_b128 v[204:207], v139 offset:52224
	ds_read_b128 v[208:211], v139 offset:53248
	ds_read_b128 v[212:215], v139 offset:54272
	ds_read_b128 v[216:219], v139 offset:55296
	ds_read_b128 v[220:223], v139 offset:56320
	s_mov_b32 m0, s46
	s_nop 0
	global_load_lds_dwordx4 v134, s[64:65]
	s_add_u32 s64, s26, 0x80080
	s_addc_u32 s65, s27, 0
	s_mov_b32 m0, s47
	s_nop 0
	global_load_lds_dwordx4 v134, s[64:65]
	s_add_u32 s64, s26, 0x100080
	s_addc_u32 s65, s27, 0
	s_mov_b32 m0, s52
	s_nop 0
	global_load_lds_dwordx4 v134, s[64:65]
	s_add_u32 s26, s26, 0x180080
	s_addc_u32 s27, s27, 0
	s_mov_b32 m0, s53
	s_nop 0
	global_load_lds_dwordx4 v134, s[26:27]
	s_add_u32 s22, s22, 0x80080
	s_mov_b32 m0, s50
	s_nop 0
	global_load_lds_dwordx4 v1, s[24:25]
	s_addc_u32 s23, s23, 0
	s_mov_b32 m0, s51
	s_nop 0
	global_load_lds_dwordx4 v1, s[22:23]
	s_waitcnt vmcnt(8)
	s_waitcnt lgkmcnt(0)
	s_barrier
	s_waitcnt lgkmcnt(7)
	v_mfma_f32_16x16x32_bf16 v[62:65], v[142:145], v[188:191], v[62:65]
	v_mfma_f32_16x16x32_bf16 v[58:61], v[150:153], v[188:191], v[58:61]
	s_waitcnt lgkmcnt(5)
	v_mfma_f32_16x16x32_bf16 v[46:49], v[142:145], v[196:199], v[46:49]
	v_mfma_f32_16x16x32_bf16 v[42:45], v[150:153], v[196:199], v[42:45]
	s_waitcnt lgkmcnt(3)
	v_mfma_f32_16x16x32_bf16 v[30:33], v[142:145], v[208:211], v[30:33]
	v_mfma_f32_16x16x32_bf16 v[26:29], v[150:153], v[208:211], v[26:29]
	s_waitcnt lgkmcnt(1)
	v_mfma_f32_16x16x32_bf16 v[14:17], v[142:145], v[216:219], v[14:17]
	v_mfma_f32_16x16x32_bf16 v[10:13], v[150:153], v[216:219], v[10:13]
	v_mfma_f32_16x16x32_bf16 v[62:65], v[146:149], v[192:195], v[62:65]
	v_mfma_f32_16x16x32_bf16 v[58:61], v[154:157], v[192:195], v[58:61]
	v_mfma_f32_16x16x32_bf16 v[46:49], v[146:149], v[204:207], v[46:49]
	v_mfma_f32_16x16x32_bf16 v[42:45], v[154:157], v[204:207], v[42:45]
	v_mfma_f32_16x16x32_bf16 v[30:33], v[146:149], v[212:215], v[30:33]
	v_mfma_f32_16x16x32_bf16 v[26:29], v[154:157], v[212:215], v[26:29]
	s_waitcnt lgkmcnt(0)
	v_mfma_f32_16x16x32_bf16 v[14:17], v[146:149], v[220:223], v[14:17]
	v_mfma_f32_16x16x32_bf16 v[10:13], v[154:157], v[220:223], v[10:13]
	v_mfma_f32_16x16x32_bf16 v[54:57], v[158:161], v[188:191], v[54:57]
	v_mfma_f32_16x16x32_bf16 v[50:53], v[174:177], v[188:191], v[50:53]
	v_mfma_f32_16x16x32_bf16 v[38:41], v[158:161], v[196:199], v[38:41]
	v_mfma_f32_16x16x32_bf16 v[34:37], v[174:177], v[196:199], v[34:37]
	v_mfma_f32_16x16x32_bf16 v[22:25], v[158:161], v[208:211], v[22:25]
	v_mfma_f32_16x16x32_bf16 v[18:21], v[174:177], v[208:211], v[18:21]
	v_mfma_f32_16x16x32_bf16 v[6:9], v[158:161], v[216:219], v[6:9]
	v_mfma_f32_16x16x32_bf16 v[2:5], v[174:177], v[216:219], v[2:5]
	v_mfma_f32_16x16x32_bf16 v[54:57], v[170:173], v[192:195], v[54:57]
	v_mfma_f32_16x16x32_bf16 v[50:53], v[184:187], v[192:195], v[50:53]
	v_mfma_f32_16x16x32_bf16 v[38:41], v[170:173], v[204:207], v[38:41]
	v_mfma_f32_16x16x32_bf16 v[34:37], v[184:187], v[204:207], v[34:37]
	v_mfma_f32_16x16x32_bf16 v[22:25], v[170:173], v[212:215], v[22:25]
	v_mfma_f32_16x16x32_bf16 v[18:21], v[184:187], v[212:215], v[18:21]
	v_mfma_f32_16x16x32_bf16 v[6:9], v[170:173], v[220:223], v[6:9]
	v_mfma_f32_16x16x32_bf16 v[2:5], v[184:187], v[220:223], v[2:5]
	s_barrier
	s_add_u32 s60, s60, 0x100
	s_addc_u32 s61, s61, 0
	s_add_u32 s20, s20, 0x100
	s_addc_u32 s21, s21, 0
	s_cmp_ge_i32 s62, s31
	s_mov_b32 s22, s62
	s_cbranch_scc0 .LBB0_388
	s_and_b64 vcc, exec, s[6:7]
	s_cbranch_vccz .LBB0_391

; #define PG8_STAGE(bufoff, gbase, X) do { _Pragma("unroll") for (int _i = 0; _i < 2; ++_i) { \
;         const char* gp_ = (const char*)(gbase) + (_i ? rs##X : (size_t)0); const unsigned la_ = (unsigned)(size_t)(lds + (bufoff) + ldsw + _i * 8192); \
;         asm volatile("s_mov_b32 m0, %2\n\ts_nop 0\n\tglobal_load_lds_dwordx4 %0, %1" :: "v"(voff##X), "s"(gp_), "s"(la_) : "memory", "m0"); } } while (0)
; #define PG8_LDA(dst, b, h) do { _Pragma("unroll") for (int m = 0; m < 4; ++m) _Pragma("unroll") for (int k = 0; k < 2; ++k) dst[m][k] = *(const LAS bf16x8*)(lds + PG8_SA(b, h) + aoff + m * 2048 + k * 1024); } while (0)
; #define PG8_LDB(dst, b, h) do { _Pragma("unroll") for (int n = 0; n < 2; ++n) _Pragma("unroll") for (int k = 0; k < 2; ++k) dst[n][k] = *(const LAS bf16x8*)(lds + PG8_SB(b, h) + boff + n * 2048 + k * 1024); } while (0)
; #define PG8_WAIT_V(n) asm volatile("s_waitcnt vmcnt(" #n ")" ::: "memory")
; #define PG8_WAIT_L(n) asm volatile("s_waitcnt lgkmcnt(" #n ")" ::: "memory")
; #define PG8_BAR __builtin_amdgcn_s_barrier()
; #define PG8_SCHED __builtin_amdgcn_sched_barrier(0)
; template <class Epi>
; __device__ __forceinline__ void gemm_phase(LAS unsigned char* lds, const Gemm g_in, const StaticOrder& S, const Epi& E) {
;     ...
;             PG8_LDB(B0, 0, 0); PG8_LDB(B1, 0, 1); PG8_SCHED; PG8_LDA(At, 0, 0); PG8_STAGE(PG8_SA(1, 1), a1 + hsA, A);
;             PG8_WAIT_V(8); PG8_WAIT_L(0); PG8_BAR; PG8_MMA(0, 0, At, B0); PG8_MMA(0, 1, At, B1); PG8_BAR; PG8_SCHED;
;             PG8_LDA(At, 0, 1); PG8_STAGE(PG8_SB(0, 0), b2, B); PG8_STAGE(PG8_SB(0, 1), b2 + hsB, B); PG8_STAGE(PG8_SA(0, 0), a2, A);
;             PG8_WAIT_V(8); PG8_WAIT_L(0); PG8_BAR; PG8_MMA(1, 0, At, B0); PG8_MMA(1, 1, At, B1); PG8_BAR; PG8_SCHED;
.LBB0_406:
	v_add_u32_e32 v143, 0x10000, v141
	ds_read_b128 v[134:137], v143
	ds_read_b128 v[144:147], v143 offset:1024
	ds_read_b128 v[148:151], v143 offset:2048
	ds_read_b128 v[152:155], v143 offset:3072
	v_add_u32_e32 v143, 0x14000, v141
	ds_read_b128 v[156:159], v143
	ds_read_b128 v[170:173], v143 offset:1024
	ds_read_b128 v[174:177], v143 offset:2048
	ds_read_b128 v[184:187], v143 offset:3072
	s_add_i32 s70, s30, 2
	s_add_u32 s34, s28, 0xfff40080
	s_addc_u32 s31, s29, -1
	s_cmp_eq_u32 s62, s30
	s_cselect_b32 s30, s21, s34
	s_cselect_b32 s31, s19, s31
	s_cselect_b32 s36, s67, s68
	s_cselect_b32 s37, s66, s69
	s_add_u32 s34, s30, 0x80
	s_addc_u32 s35, s31, 0
	ds_read_b128 v[188:191], v142
	ds_read_b128 v[192:195], v142 offset:1024
	ds_read_b128 v[196:199], v142 offset:2048
	ds_read_b128 v[204:207], v142 offset:3072
	ds_read_b128 v[208:211], v142 offset:4096
	ds_read_b128 v[212:215], v142 offset:5120
	ds_read_b128 v[216:219], v142 offset:6144
	ds_read_b128 v[220:223], v142 offset:7168
	s_add_u32 s72, s28, 0xfffc0000
	s_addc_u32 s73, s29, -1
	s_mov_b32 m0, s63
	s_nop 0
	global_load_lds_dwordx4 v1, s[72:73]
	s_nop 0
	s_mov_b32 m0, s64
	s_nop 0
	global_load_lds_dwordx4 v1, s[28:29]
	s_waitcnt vmcnt(8)
	s_waitcnt lgkmcnt(0)
	s_barrier
	s_waitcnt lgkmcnt(7)
	v_mfma_i32_16x16x64_i8 v[126:129], v[134:137], v[188:191], v[126:129]
	v_mfma_i32_16x16x64_i8 v[122:125], v[148:151], v[188:191], v[122:125]
	s_waitcnt lgkmcnt(5)
	v_mfma_i32_16x16x64_i8 v[118:121], v[134:137], v[196:199], v[118:121]
	v_mfma_i32_16x16x64_i8 v[110:113], v[148:151], v[196:199], v[110:113]
	s_waitcnt lgkmcnt(3)
	v_mfma_i32_16x16x64_i8 v[102:105], v[134:137], v[208:211], v[102:105]
	v_mfma_i32_16x16x64_i8 v[94:97], v[148:151], v[208:211], v[94:97]
	s_waitcnt lgkmcnt(1)
	v_mfma_i32_16x16x64_i8 v[86:89], v[134:137], v[216:219], v[86:89]
	v_mfma_i32_16x16x64_i8 v[78:81], v[148:151], v[216:219], v[78:81]
	v_mfma_i32_16x16x64_i8 v[126:129], v[144:147], v[192:195], v[126:129]
	v_mfma_i32_16x16x64_i8 v[122:125], v[152:155], v[192:195], v[122:125]
	v_mfma_i32_16x16x64_i8 v[118:121], v[144:147], v[204:207], v[118:121]
	v_mfma_i32_16x16x64_i8 v[110:113], v[152:155], v[204:207], v[110:113]
	v_mfma_i32_16x16x64_i8 v[102:105], v[144:147], v[212:215], v[102:105]
	v_mfma_i32_16x16x64_i8 v[94:97], v[152:155], v[212:215], v[94:97]
	s_waitcnt lgkmcnt(0)
	v_mfma_i32_16x16x64_i8 v[86:89], v[144:147], v[220:223], v[86:89]
	v_mfma_i32_16x16x64_i8 v[78:81], v[152:155], v[220:223], v[78:81]
	v_mfma_i32_16x16x64_i8 v[114:117], v[156:159], v[188:191], v[114:117]
	v_mfma_i32_16x16x64_i8 v[106:109], v[174:177], v[188:191], v[106:109]
	v_mfma_i32_16x16x64_i8 v[98:101], v[156:159], v[196:199], v[98:101]
	v_mfma_i32_16x16x64_i8 v[90:93], v[174:177], v[196:199], v[90:93]
	v_mfma_i32_16x16x64_i8 v[82:85], v[156:159], v[208:211], v[82:85]
	v_mfma_i32_16x16x64_i8 v[74:77], v[174:177], v[208:211], v[74:77]
	v_mfma_i32_16x16x64_i8 v[70:73], v[156:159], v[216:219], v[70:73]
	v_mfma_i32_16x16x64_i8 v[66:69], v[174:177], v[216:219], v[66:69]
	v_mfma_i32_16x16x64_i8 v[114:117], v[170:173], v[192:195], v[114:117]
	v_mfma_i32_16x16x64_i8 v[106:109], v[184:187], v[192:195], v[106:109]
	v_mfma_i32_16x16x64_i8 v[98:101], v[170:173], v[204:207], v[98:101]
	v_mfma_i32_16x16x64_i8 v[90:93], v[184:187], v[204:207], v[90:93]
	v_mfma_i32_16x16x64_i8 v[82:85], v[170:173], v[212:215], v[82:85]
	v_mfma_i32_16x16x64_i8 v[74:77], v[184:187], v[212:215], v[74:77]
	v_mfma_i32_16x16x64_i8 v[70:73], v[170:173], v[220:223], v[70:73]
	v_mfma_i32_16x16x64_i8 v[66:69], v[184:187], v[220:223], v[66:69]
	s_barrier
	s_add_u32 s72, s36, 0x40000
	ds_read_b128 v[188:191], v142 offset:16384
	ds_read_b128 v[192:195], v142 offset:17408
	ds_read_b128 v[196:199], v142 offset:18432
	ds_read_b128 v[204:207], v142 offset:19456
	ds_read_b128 v[208:211], v142 offset:20480
	ds_read_b128 v[212:215], v142 offset:21504
	ds_read_b128 v[216:219], v142 offset:22528
	ds_read_b128 v[220:223], v142 offset:23552
	s_mov_b32 m0, s44
	s_nop 0
	global_load_lds_dwordx4 v138, s[36:37]
	s_addc_u32 s73, s37, 0
	s_mov_b32 m0, s45
	s_nop 0
	global_load_lds_dwordx4 v138, s[72:73]
	s_add_u32 s72, s36, 0x80000
	s_addc_u32 s73, s37, 0
	s_mov_b32 m0, s46
	s_nop 0
	global_load_lds_dwordx4 v138, s[72:73]
	s_add_u32 s72, s36, 0xc0000
	s_addc_u32 s73, s37, 0
	s_mov_b32 m0, s47
	s_nop 0
	global_load_lds_dwordx4 v138, s[72:73]
	s_add_u32 s72, s30, 0x40000
	s_mov_b32 m0, s23
	s_nop 0
	global_load_lds_dwordx4 v1, s[30:31]
	s_addc_u32 s73, s31, 0
	s_mov_b32 m0, s50
	s_nop 0
	global_load_lds_dwordx4 v1, s[72:73]
	s_waitcnt vmcnt(8)
	s_waitcnt lgkmcnt(0)
	s_barrier
; #define PG8_STAGE(bufoff, gbase, X) do { _Pragma("unroll") for (int _i = 0; _i < 2; ++_i) { \
;         const char* gp_ = (const char*)(gbase) + (_i ? rs##X : (size_t)0); const unsigned la_ = (unsigned)(size_t)(lds + (bufoff) + ldsw + _i * 8192); \
;         asm volatile("s_mov_b32 m0, %2\n\ts_nop 0\n\tglobal_load_lds_dwordx4 %0, %1" :: "v"(voff##X), "s"(gp_), "s"(la_) : "memory", "m0"); } } while (0)
; #define PG8_LDA(dst, b, h) do { _Pragma("unroll") for (int m = 0; m < 4; ++m) _Pragma("unroll") for (int k = 0; k < 2; ++k) dst[m][k] = *(const LAS bf16x8*)(lds + PG8_SA(b, h) + aoff + m * 2048 + k * 1024); } while (0)
; #define PG8_LDB(dst, b, h) do { _Pragma("unroll") for (int n = 0; n < 2; ++n) _Pragma("unroll") for (int k = 0; k < 2; ++k) dst[n][k] = *(const LAS bf16x8*)(lds + PG8_SB(b, h) + boff + n * 2048 + k * 1024); } while (0)
; #define PG8_WAIT_V(n) asm volatile("s_waitcnt vmcnt(" #n ")" ::: "memory")
; #define PG8_WAIT_L(n) asm volatile("s_waitcnt lgkmcnt(" #n ")" ::: "memory")
; #define PG8_BAR __builtin_amdgcn_s_barrier()
; #define PG8_SCHED __builtin_amdgcn_sched_barrier(0)
; template <class Epi>
; __device__ __forceinline__ void gemm_phase(LAS unsigned char* lds, const Gemm g_in, const StaticOrder& S, const Epi& E) {
;     ...
;             PG8_WAIT_V(8); PG8_WAIT_L(0); PG8_BAR; PG8_MMA(0, 0, At, B0); PG8_MMA(0, 1, At, B1); PG8_BAR; PG8_SCHED;
;             PG8_LDA(At, 0, 1); PG8_STAGE(PG8_SB(0, 0), b2, B); PG8_STAGE(PG8_SB(0, 1), b2 + hsB, B); PG8_STAGE(PG8_SA(0, 0), a2, A);
;             PG8_WAIT_V(8); PG8_WAIT_L(0); PG8_BAR; PG8_MMA(1, 0, At, B0); PG8_MMA(1, 1, At, B1); PG8_BAR; PG8_SCHED;
;             PG8_LDB(B0, 1, 0); PG8_LDB(B1, 1, 1); PG8_SCHED; PG8_LDA(At, 1, 0); PG8_STAGE(PG8_SA(0, 1), a2 + hsA, A);
;             PG8_WAIT_V(8); PG8_WAIT_L(0); PG8_BAR; PG8_MMA(0, 0, At, B0); PG8_MMA(0, 1, At, B1); PG8_BAR; PG8_SCHED;
;             PG8_LDA(At, 1, 1); PG8_STAGE(PG8_SB(1, 0), b3, B); PG8_STAGE(PG8_SB(1, 1), b3 + hsB, B); PG8_STAGE(PG8_SA(1, 0), a3, A);
	s_waitcnt lgkmcnt(7)
	v_mfma_i32_16x16x64_i8 v[62:65], v[134:137], v[188:191], v[62:65]
	v_mfma_i32_16x16x64_i8 v[58:61], v[148:151], v[188:191], v[58:61]
	s_waitcnt lgkmcnt(5)
	v_mfma_i32_16x16x64_i8 v[54:57], v[134:137], v[196:199], v[54:57]
	v_mfma_i32_16x16x64_i8 v[46:49], v[148:151], v[196:199], v[46:49]
	s_waitcnt lgkmcnt(3)
	v_mfma_i32_16x16x64_i8 v[38:41], v[134:137], v[208:211], v[38:41]
	v_mfma_i32_16x16x64_i8 v[30:33], v[148:151], v[208:211], v[30:33]
	s_waitcnt lgkmcnt(1)
	v_mfma_i32_16x16x64_i8 v[22:25], v[134:137], v[216:219], v[22:25]
	v_mfma_i32_16x16x64_i8 v[14:17], v[148:151], v[216:219], v[14:17]
	v_mfma_i32_16x16x64_i8 v[62:65], v[144:147], v[192:195], v[62:65]
	v_mfma_i32_16x16x64_i8 v[58:61], v[152:155], v[192:195], v[58:61]
	v_mfma_i32_16x16x64_i8 v[54:57], v[144:147], v[204:207], v[54:57]
	v_mfma_i32_16x16x64_i8 v[46:49], v[152:155], v[204:207], v[46:49]
	v_mfma_i32_16x16x64_i8 v[38:41], v[144:147], v[212:215], v[38:41]
	v_mfma_i32_16x16x64_i8 v[30:33], v[152:155], v[212:215], v[30:33]
	s_waitcnt lgkmcnt(0)
	v_mfma_i32_16x16x64_i8 v[22:25], v[144:147], v[220:223], v[22:25]
	v_mfma_i32_16x16x64_i8 v[14:17], v[152:155], v[220:223], v[14:17]
	v_mfma_i32_16x16x64_i8 v[50:53], v[156:159], v[188:191], v[50:53]
	v_mfma_i32_16x16x64_i8 v[42:45], v[174:177], v[188:191], v[42:45]
	v_mfma_i32_16x16x64_i8 v[34:37], v[156:159], v[196:199], v[34:37]
	v_mfma_i32_16x16x64_i8 v[26:29], v[174:177], v[196:199], v[26:29]
	v_mfma_i32_16x16x64_i8 v[18:21], v[156:159], v[208:211], v[18:21]
	v_mfma_i32_16x16x64_i8 v[10:13], v[174:177], v[208:211], v[10:13]
	v_mfma_i32_16x16x64_i8 v[6:9], v[156:159], v[216:219], v[6:9]
	v_mfma_i32_16x16x64_i8 v[2:5], v[174:177], v[216:219], v[2:5]
	v_mfma_i32_16x16x64_i8 v[50:53], v[170:173], v[192:195], v[50:53]
	v_mfma_i32_16x16x64_i8 v[42:45], v[184:187], v[192:195], v[42:45]
	v_mfma_i32_16x16x64_i8 v[34:37], v[170:173], v[204:207], v[34:37]
	v_mfma_i32_16x16x64_i8 v[26:29], v[184:187], v[204:207], v[26:29]
	v_mfma_i32_16x16x64_i8 v[18:21], v[170:173], v[212:215], v[18:21]
	v_mfma_i32_16x16x64_i8 v[10:13], v[184:187], v[212:215], v[10:13]
	v_mfma_i32_16x16x64_i8 v[6:9], v[170:173], v[220:223], v[6:9]
	v_mfma_i32_16x16x64_i8 v[2:5], v[184:187], v[220:223], v[2:5]
	s_barrier
	v_add_u32_e32 v143, 0x18000, v141
	ds_read_b128 v[134:137], v143
	ds_read_b128 v[144:147], v143 offset:1024
	ds_read_b128 v[148:151], v143 offset:2048
	ds_read_b128 v[152:155], v143 offset:3072
	v_add_u32_e32 v143, 0x1c000, v141
	ds_read_b128 v[156:159], v143
	ds_read_b128 v[170:173], v143 offset:1024
	ds_read_b128 v[174:177], v143 offset:2048
	ds_read_b128 v[184:187], v143 offset:3072
	ds_read_b128 v[188:191], v142 offset:32768
	ds_read_b128 v[192:195], v142 offset:33792
	ds_read_b128 v[196:199], v142 offset:34816
	ds_read_b128 v[204:207], v142 offset:35840
	ds_read_b128 v[208:211], v142 offset:36864
	ds_read_b128 v[212:215], v142 offset:37888
	ds_read_b128 v[216:219], v142 offset:38912
	ds_read_b128 v[220:223], v142 offset:39936
	s_add_u32 s72, s30, 0x80000
	s_addc_u32 s73, s31, 0
	s_mov_b32 m0, s51
	s_nop 0
	global_load_lds_dwordx4 v1, s[72:73]
	s_add_u32 s72, s30, 0xc0000
	s_addc_u32 s73, s31, 0
	s_mov_b32 m0, s52
	s_nop 0
	global_load_lds_dwordx4 v1, s[72:73]
	s_waitcnt vmcnt(8)
	s_waitcnt lgkmcnt(0)
	s_barrier
	s_waitcnt lgkmcnt(7)
	v_mfma_i32_16x16x64_i8 v[126:129], v[134:137], v[188:191], v[126:129]
	v_mfma_i32_16x16x64_i8 v[122:125], v[148:151], v[188:191], v[122:125]
	s_waitcnt lgkmcnt(5)
	v_mfma_i32_16x16x64_i8 v[118:121], v[134:137], v[196:199], v[118:121]
	v_mfma_i32_16x16x64_i8 v[110:113], v[148:151], v[196:199], v[110:113]
	s_waitcnt lgkmcnt(3)
	v_mfma_i32_16x16x64_i8 v[102:105], v[134:137], v[208:211], v[102:105]
	v_mfma_i32_16x16x64_i8 v[94:97], v[148:151], v[208:211], v[94:97]
	s_waitcnt lgkmcnt(1)
	v_mfma_i32_16x16x64_i8 v[86:89], v[134:137], v[216:219], v[86:89]
	v_mfma_i32_16x16x64_i8 v[78:81], v[148:151], v[216:219], v[78:81]
	v_mfma_i32_16x16x64_i8 v[126:129], v[144:147], v[192:195], v[126:129]
	v_mfma_i32_16x16x64_i8 v[122:125], v[152:155], v[192:195], v[122:125]
	v_mfma_i32_16x16x64_i8 v[118:121], v[144:147], v[204:207], v[118:121]
	v_mfma_i32_16x16x64_i8 v[110:113], v[152:155], v[204:207], v[110:113]
	v_mfma_i32_16x16x64_i8 v[102:105], v[144:147], v[212:215], v[102:105]
	v_mfma_i32_16x16x64_i8 v[94:97], v[152:155], v[212:215], v[94:97]
	s_waitcnt lgkmcnt(0)
	v_mfma_i32_16x16x64_i8 v[86:89], v[144:147], v[220:223], v[86:89]
	v_mfma_i32_16x16x64_i8 v[78:81], v[152:155], v[220:223], v[78:81]
	v_mfma_i32_16x16x64_i8 v[114:117], v[156:159], v[188:191], v[114:117]
	v_mfma_i32_16x16x64_i8 v[106:109], v[174:177], v[188:191], v[106:109]
	v_mfma_i32_16x16x64_i8 v[98:101], v[156:159], v[196:199], v[98:101]
	v_mfma_i32_16x16x64_i8 v[90:93], v[174:177], v[196:199], v[90:93]
	v_mfma_i32_16x16x64_i8 v[82:85], v[156:159], v[208:211], v[82:85]
	v_mfma_i32_16x16x64_i8 v[74:77], v[174:177], v[208:211], v[74:77]
	v_mfma_i32_16x16x64_i8 v[70:73], v[156:159], v[216:219], v[70:73]
	v_mfma_i32_16x16x64_i8 v[66:69], v[174:177], v[216:219], v[66:69]
	v_mfma_i32_16x16x64_i8 v[114:117], v[170:173], v[192:195], v[114:117]
	v_mfma_i32_16x16x64_i8 v[106:109], v[184:187], v[192:195], v[106:109]
	v_mfma_i32_16x16x64_i8 v[98:101], v[170:173], v[204:207], v[98:101]
	v_mfma_i32_16x16x64_i8 v[90:93], v[184:187], v[204:207], v[90:93]
	v_mfma_i32_16x16x64_i8 v[82:85], v[170:173], v[212:215], v[82:85]
	v_mfma_i32_16x16x64_i8 v[74:77], v[184:187], v[212:215], v[74:77]
	v_mfma_i32_16x16x64_i8 v[70:73], v[170:173], v[220:223], v[70:73]
	v_mfma_i32_16x16x64_i8 v[66:69], v[184:187], v[220:223], v[66:69]
	s_barrier
; #define PG8_STAGE(bufoff, gbase, X) do { _Pragma("unroll") for (int _i = 0; _i < 2; ++_i) { \
;         const char* gp_ = (const char*)(gbase) + (_i ? rs##X : (size_t)0); const unsigned la_ = (unsigned)(size_t)(lds + (bufoff) + ldsw + _i * 8192); \
;         asm volatile("s_mov_b32 m0, %2\n\ts_nop 0\n\tglobal_load_lds_dwordx4 %0, %1" :: "v"(voff##X), "s"(gp_), "s"(la_) : "memory", "m0"); } } while (0)
; #define PG8_LDA(dst, b, h) do { _Pragma("unroll") for (int m = 0; m < 4; ++m) _Pragma("unroll") for (int k = 0; k < 2; ++k) dst[m][k] = *(const LAS bf16x8*)(lds + PG8_SA(b, h) + aoff + m * 2048 + k * 1024); } while (0)
; #define PG8_WAIT_V(n) asm volatile("s_waitcnt vmcnt(" #n ")" ::: "memory")
; #define PG8_WAIT_L(n) asm volatile("s_waitcnt lgkmcnt(" #n ")" ::: "memory")
; #define PG8_BAR __builtin_amdgcn_s_barrier()
; #define PG8_SCHED __builtin_amdgcn_sched_barrier(0)
; template <class Epi>
; __device__ __forceinline__ void gemm_phase(LAS unsigned char* lds, const Gemm g_in, const StaticOrder& S, const Epi& E) {
;     ...
;             PG8_WAIT_V(8); PG8_WAIT_L(0); PG8_BAR; PG8_MMA(0, 0, At, B0); PG8_MMA(0, 1, At, B1); PG8_BAR; PG8_SCHED;
;             PG8_LDA(At, 1, 1); PG8_STAGE(PG8_SB(1, 0), b3, B); PG8_STAGE(PG8_SB(1, 1), b3 + hsB, B); PG8_STAGE(PG8_SA(1, 0), a3, A);
;             PG8_WAIT_V(8); PG8_WAIT_L(0); PG8_BAR; PG8_MMA(1, 0, At, B0); PG8_MMA(1, 1, At, B1); PG8_BAR; PG8_SCHED;
;         }
;     __device__ __forceinline__ void operator()(const f32x4 (&acc)[2][2][4][2], const Unit& u, int wr, int wc, int fr, int fq) const {
;     ...
;                 for (int bj = 0; bj < 2; ++bj) { f32x4 v0 = acc[ai][bj][m][0], v1 = acc[ai][bj][m][1];
;                     if (I8_) { v0 = __builtin_convertvector(__builtin_bit_cast(i32x4, v0), f32x4) * I8_DEQ; v1 = __builtin_convertvector(__builtin_bit_cast(i32x4, v1), f32x4) * I8_DEQ; }
	s_add_u32 s72, s36, 0x80
	s_addc_u32 s73, s37, 0
	ds_read_b128 v[188:191], v142 offset:49152
	ds_read_b128 v[192:195], v142 offset:50176
	ds_read_b128 v[196:199], v142 offset:51200
	ds_read_b128 v[204:207], v142 offset:52224
	ds_read_b128 v[208:211], v142 offset:53248
	ds_read_b128 v[212:215], v142 offset:54272
	ds_read_b128 v[216:219], v142 offset:55296
	ds_read_b128 v[220:223], v142 offset:56320
	s_mov_b32 m0, s56
	s_nop 0
	global_load_lds_dwordx4 v138, s[72:73]
	s_add_u32 s72, s36, 0x40080
	s_addc_u32 s73, s37, 0
	s_mov_b32 m0, s57
	s_nop 0
	global_load_lds_dwordx4 v138, s[72:73]
	s_add_u32 s72, s36, 0x80080
	s_addc_u32 s73, s37, 0
	s_mov_b32 m0, s60
	s_nop 0
	global_load_lds_dwordx4 v138, s[72:73]
	s_add_u32 s36, s36, 0xc0080
	s_addc_u32 s37, s37, 0
	s_mov_b32 m0, s61
	s_nop 0
	global_load_lds_dwordx4 v138, s[36:37]
	s_add_u32 s30, s30, 0x40080
	s_mov_b32 m0, s58
	s_nop 0
	global_load_lds_dwordx4 v1, s[34:35]
	s_addc_u32 s31, s31, 0
	s_mov_b32 m0, s59
	s_nop 0
	global_load_lds_dwordx4 v1, s[30:31]
	s_waitcnt vmcnt(8)
	s_waitcnt lgkmcnt(0)
	s_barrier
	s_waitcnt lgkmcnt(7)
	v_mfma_i32_16x16x64_i8 v[62:65], v[134:137], v[188:191], v[62:65]
	v_mfma_i32_16x16x64_i8 v[58:61], v[148:151], v[188:191], v[58:61]
	s_waitcnt lgkmcnt(5)
	v_mfma_i32_16x16x64_i8 v[54:57], v[134:137], v[196:199], v[54:57]
	v_mfma_i32_16x16x64_i8 v[46:49], v[148:151], v[196:199], v[46:49]
	s_waitcnt lgkmcnt(3)
	v_mfma_i32_16x16x64_i8 v[38:41], v[134:137], v[208:211], v[38:41]
	v_mfma_i32_16x16x64_i8 v[30:33], v[148:151], v[208:211], v[30:33]
	s_waitcnt lgkmcnt(1)
	v_mfma_i32_16x16x64_i8 v[22:25], v[134:137], v[216:219], v[22:25]
	v_mfma_i32_16x16x64_i8 v[14:17], v[148:151], v[216:219], v[14:17]
	v_mfma_i32_16x16x64_i8 v[62:65], v[144:147], v[192:195], v[62:65]
	v_mfma_i32_16x16x64_i8 v[58:61], v[152:155], v[192:195], v[58:61]
	v_mfma_i32_16x16x64_i8 v[54:57], v[144:147], v[204:207], v[54:57]
	v_mfma_i32_16x16x64_i8 v[46:49], v[152:155], v[204:207], v[46:49]
	v_mfma_i32_16x16x64_i8 v[38:41], v[144:147], v[212:215], v[38:41]
	v_mfma_i32_16x16x64_i8 v[30:33], v[152:155], v[212:215], v[30:33]
	s_waitcnt lgkmcnt(0)
	v_mfma_i32_16x16x64_i8 v[22:25], v[144:147], v[220:223], v[22:25]
	v_mfma_i32_16x16x64_i8 v[14:17], v[152:155], v[220:223], v[14:17]
	v_mfma_i32_16x16x64_i8 v[50:53], v[156:159], v[188:191], v[50:53]
	v_mfma_i32_16x16x64_i8 v[42:45], v[174:177], v[188:191], v[42:45]
	v_mfma_i32_16x16x64_i8 v[34:37], v[156:159], v[196:199], v[34:37]
	v_mfma_i32_16x16x64_i8 v[26:29], v[174:177], v[196:199], v[26:29]
	v_mfma_i32_16x16x64_i8 v[18:21], v[156:159], v[208:211], v[18:21]
	v_mfma_i32_16x16x64_i8 v[10:13], v[174:177], v[208:211], v[10:13]
	v_mfma_i32_16x16x64_i8 v[6:9], v[156:159], v[216:219], v[6:9]
	v_mfma_i32_16x16x64_i8 v[2:5], v[174:177], v[216:219], v[2:5]
	v_mfma_i32_16x16x64_i8 v[50:53], v[170:173], v[192:195], v[50:53]
	v_mfma_i32_16x16x64_i8 v[42:45], v[184:187], v[192:195], v[42:45]
	v_mfma_i32_16x16x64_i8 v[34:37], v[170:173], v[204:207], v[34:37]
	v_mfma_i32_16x16x64_i8 v[26:29], v[184:187], v[204:207], v[26:29]
	v_mfma_i32_16x16x64_i8 v[18:21], v[170:173], v[212:215], v[18:21]
	v_mfma_i32_16x16x64_i8 v[10:13], v[184:187], v[212:215], v[10:13]
	v_mfma_i32_16x16x64_i8 v[6:9], v[170:173], v[220:223], v[6:9]
	v_mfma_i32_16x16x64_i8 v[2:5], v[184:187], v[220:223], v[2:5]
	s_barrier
	s_add_u32 s68, s68, 0x100
	s_addc_u32 s69, s69, 0
	s_add_u32 s28, s28, 0x100
	s_addc_u32 s29, s29, 0
	s_cmp_ge_i32 s70, s41
	s_mov_b32 s30, s70
	s_cbranch_scc0 .LBB0_406
	v_cvt_f32_i32_e32 v129, v129
	v_cvt_f32_i32_e32 v128, v128
	v_cvt_f32_i32_e32 v135, v123
	v_cvt_f32_i32_e32 v134, v122
	v_cvt_f32_i32_e32 v109, v109
	v_pk_mul_f32 v[122:123], v[128:129], s[8:9] op_sel_hi:[1,0]
	v_cvt_f32_i32_e32 v108, v108
	v_pk_mul_f32 v[128:129], v[134:135], s[8:9] op_sel_hi:[1,0]
	v_cvt_f32_i32_e32 v135, v115
	v_cvt_f32_i32_e32 v134, v114
	v_cvt_f32_i32_e32 v115, v117
	v_cvt_f32_i32_e32 v114, v116
	v_cvt_f32_i32_e32 v113, v113
	v_pk_mul_f32 v[116:117], v[134:135], s[8:9] op_sel_hi:[1,0]
	v_pk_mul_f32 v[134:135], v[108:109], s[8:9] op_sel_hi:[1,0]
	v_cvt_f32_i32_e32 v109, v119
	v_cvt_f32_i32_e32 v108, v118
	v_cvt_f32_i32_e32 v119, v111
	v_cvt_f32_i32_e32 v112, v112
	v_cvt_f32_i32_e32 v118, v110
	v_cvt_f32_i32_e32 v93, v93
	v_cvt_f32_i32_e32 v92, v92
	v_pk_mul_f32 v[110:111], v[112:113], s[8:9] op_sel_hi:[1,0]
	v_pk_mul_f32 v[112:113], v[118:119], s[8:9] op_sel_hi:[1,0]
	v_cvt_f32_i32_e32 v119, v99
	v_cvt_f32_i32_e32 v118, v98
	v_cvt_f32_i32_e32 v99, v101
	v_cvt_f32_i32_e32 v98, v100
	v_cvt_f32_i32_e32 v97, v97
	v_pk_mul_f32 v[100:101], v[118:119], s[8:9] op_sel_hi:[1,0]
	v_pk_mul_f32 v[118:119], v[92:93], s[8:9] op_sel_hi:[1,0]
	v_cvt_f32_i32_e32 v93, v103
	v_cvt_f32_i32_e32 v92, v102
	v_cvt_f32_i32_e32 v103, v95
	v_cvt_f32_i32_e32 v96, v96
	v_cvt_f32_i32_e32 v102, v94
	v_cvt_f32_i32_e32 v77, v77
	v_cvt_f32_i32_e32 v76, v76
	v_pk_mul_f32 v[94:95], v[96:97], s[8:9] op_sel_hi:[1,0]
	v_pk_mul_f32 v[96:97], v[102:103], s[8:9] op_sel_hi:[1,0]
	v_cvt_f32_i32_e32 v103, v83
	v_cvt_f32_i32_e32 v102, v82
	v_cvt_f32_i32_e32 v83, v85
	v_cvt_f32_i32_e32 v82, v84
	v_cvt_f32_i32_e32 v81, v81
	v_pk_mul_f32 v[84:85], v[102:103], s[8:9] op_sel_hi:[1,0]
	v_pk_mul_f32 v[102:103], v[76:77], s[8:9] op_sel_hi:[1,0]
	v_cvt_f32_i32_e32 v77, v87
	v_cvt_f32_i32_e32 v76, v86
	v_cvt_f32_i32_e32 v87, v79
	v_cvt_f32_i32_e32 v80, v80
	v_cvt_f32_i32_e32 v86, v78
	v_cvt_f32_i32_e32 v73, v73
	v_cvt_f32_i32_e32 v72, v72
;     __device__ __forceinline__ void operator()(const f32x4 (&acc)[2][2][4][2], const Unit& u, int wr, int wc, int fr, int fq) const {
;     ...
;                 for (int bj = 0; bj < 2; ++bj) { f32x4 v0 = acc[ai][bj][m][0], v1 = acc[ai][bj][m][1];
;                     if (I8_) { v0 = __builtin_convertvector(__builtin_bit_cast(i32x4, v0), f32x4) * I8_DEQ; v1 = __builtin_convertvector(__builtin_bit_cast(i32x4, v1), f32x4) * I8_DEQ; }
	v_pk_mul_f32 v[78:79], v[80:81], s[8:9] op_sel_hi:[1,0]
	v_pk_mul_f32 v[80:81], v[86:87], s[8:9] op_sel_hi:[1,0]
	v_cvt_f32_i32_e32 v87, v67
	v_cvt_f32_i32_e32 v86, v66
	v_pk_mul_f32 v[66:67], v[72:73], s[8:9] op_sel_hi:[1,0]
	v_cvt_f32_i32_e32 v65, v65
	v_cvt_f32_i32_e32 v64, v64
	v_pk_mul_f32 v[72:73], v[86:87], s[8:9] op_sel_hi:[1,0]
	v_cvt_f32_i32_e32 v87, v59
	v_cvt_f32_i32_e32 v86, v58
	v_pk_mul_f32 v[58:59], v[64:65], s[8:9] op_sel_hi:[1,0]
	v_cvt_f32_i32_e32 v45, v45
	v_cvt_f32_i32_e32 v44, v44
	v_pk_mul_f32 v[64:65], v[86:87], s[8:9] op_sel_hi:[1,0]
	v_cvt_f32_i32_e32 v87, v51
	v_cvt_f32_i32_e32 v86, v50
	v_cvt_f32_i32_e32 v51, v53
	v_cvt_f32_i32_e32 v50, v52
	v_cvt_f32_i32_e32 v49, v49
	v_pk_mul_f32 v[52:53], v[86:87], s[8:9] op_sel_hi:[1,0]
	v_pk_mul_f32 v[86:87], v[44:45], s[8:9] op_sel_hi:[1,0]
	v_cvt_f32_i32_e32 v45, v55
	v_cvt_f32_i32_e32 v44, v54
	v_cvt_f32_i32_e32 v55, v47
	v_cvt_f32_i32_e32 v48, v48
	v_cvt_f32_i32_e32 v54, v46
	v_cvt_f32_i32_e32 v29, v29
	v_cvt_f32_i32_e32 v28, v28
	v_pk_mul_f32 v[46:47], v[48:49], s[8:9] op_sel_hi:[1,0]
	v_pk_mul_f32 v[48:49], v[54:55], s[8:9] op_sel_hi:[1,0]
	v_cvt_f32_i32_e32 v55, v35
	v_cvt_f32_i32_e32 v54, v34
	v_cvt_f32_i32_e32 v127, v127
	v_cvt_f32_i32_e32 v126, v126
	v_cvt_f32_i32_e32 v137, v125
	v_cvt_f32_i32_e32 v136, v124
	v_cvt_f32_i32_e32 v107, v107
	v_cvt_f32_i32_e32 v106, v106
	v_cvt_f32_i32_e32 v91, v91
	v_cvt_f32_i32_e32 v90, v90
	v_cvt_f32_i32_e32 v75, v75
	v_cvt_f32_i32_e32 v74, v74
	v_cvt_f32_i32_e32 v35, v37
	v_cvt_f32_i32_e32 v34, v36
	v_pk_mul_f32 v[36:37], v[54:55], s[8:9] op_sel_hi:[1,0]
	v_pk_mul_f32 v[54:55], v[28:29], s[8:9] op_sel_hi:[1,0]
	v_cvt_f32_i32_e32 v29, v39
	v_cvt_f32_i32_e32 v28, v38
	v_cvt_f32_i32_e32 v39, v31
	v_cvt_f32_i32_e32 v33, v33
	v_cvt_f32_i32_e32 v32, v32
	v_cvt_f32_i32_e32 v38, v30
	v_pk_mul_f32 v[124:125], v[126:127], s[8:9] op_sel_hi:[1,0]
	v_pk_mul_f32 v[126:127], v[136:137], s[8:9] op_sel_hi:[1,0]
	v_pk_mul_f32 v[136:137], v[106:107], s[8:9] op_sel_hi:[1,0]
	v_cvt_f32_i32_e32 v107, v121
	v_cvt_f32_i32_e32 v106, v120
	v_pk_mul_f32 v[120:121], v[90:91], s[8:9] op_sel_hi:[1,0]
	v_cvt_f32_i32_e32 v91, v105
	v_cvt_f32_i32_e32 v90, v104
	v_pk_mul_f32 v[104:105], v[74:75], s[8:9] op_sel_hi:[1,0]
	v_cvt_f32_i32_e32 v75, v89
	v_cvt_f32_i32_e32 v74, v88
	v_cvt_f32_i32_e32 v71, v71
	v_cvt_f32_i32_e32 v70, v70
	v_cvt_f32_i32_e32 v89, v69
	v_cvt_f32_i32_e32 v88, v68
	v_pk_mul_f32 v[30:31], v[32:33], s[8:9] op_sel_hi:[1,0]
	v_pk_mul_f32 v[32:33], v[38:39], s[8:9] op_sel_hi:[1,0]
	v_cvt_f32_i32_e32 v39, v19
	v_cvt_f32_i32_e32 v38, v18
	v_cvt_f32_i32_e32 v13, v13
	v_cvt_f32_i32_e32 v12, v12
	v_pk_mul_f32 v[68:69], v[70:71], s[8:9] op_sel_hi:[1,0]
	v_pk_mul_f32 v[70:71], v[88:89], s[8:9] op_sel_hi:[1,0]
	v_cvt_f32_i32_e32 v63, v63
	v_cvt_f32_i32_e32 v62, v62
	v_cvt_f32_i32_e32 v89, v61
	v_cvt_f32_i32_e32 v88, v60
	v_cvt_f32_i32_e32 v43, v43
	v_cvt_f32_i32_e32 v42, v42
	v_cvt_f32_i32_e32 v27, v27
	v_cvt_f32_i32_e32 v26, v26
	v_cvt_f32_i32_e32 v19, v21
	v_cvt_f32_i32_e32 v18, v20
	v_cvt_f32_i32_e32 v11, v11
	v_cvt_f32_i32_e32 v10, v10
	v_pk_mul_f32 v[20:21], v[38:39], s[8:9] op_sel_hi:[1,0]
	v_pk_mul_f32 v[38:39], v[12:13], s[8:9] op_sel_hi:[1,0]
	v_cvt_f32_i32_e32 v13, v23
	v_cvt_f32_i32_e32 v12, v22
	v_cvt_f32_i32_e32 v23, v15
	v_cvt_f32_i32_e32 v17, v17
	v_cvt_f32_i32_e32 v16, v16
	v_cvt_f32_i32_e32 v22, v14
	v_pk_mul_f32 v[60:61], v[62:63], s[8:9] op_sel_hi:[1,0]
	v_pk_mul_f32 v[62:63], v[88:89], s[8:9] op_sel_hi:[1,0]
	v_pk_mul_f32 v[88:89], v[42:43], s[8:9] op_sel_hi:[1,0]
	v_cvt_f32_i32_e32 v43, v57
	v_cvt_f32_i32_e32 v42, v56
	v_pk_mul_f32 v[56:57], v[26:27], s[8:9] op_sel_hi:[1,0]
	v_cvt_f32_i32_e32 v27, v41
	v_cvt_f32_i32_e32 v26, v40
	v_pk_mul_f32 v[40:41], v[10:11], s[8:9] op_sel_hi:[1,0]
	v_cvt_f32_i32_e32 v11, v25
	v_cvt_f32_i32_e32 v10, v24
	v_pk_mul_f32 v[14:15], v[16:17], s[8:9] op_sel_hi:[1,0]
	v_pk_mul_f32 v[16:17], v[22:23], s[8:9] op_sel_hi:[1,0]
	v_cvt_f32_i32_e32 v7, v7
	v_cvt_f32_i32_e32 v6, v6
	v_cvt_f32_i32_e32 v9, v9
	v_cvt_f32_i32_e32 v8, v8
	v_cvt_f32_i32_e32 v23, v3
	v_cvt_f32_i32_e32 v25, v5
	v_cvt_f32_i32_e32 v24, v4
	v_cvt_f32_i32_e32 v22, v2
	v_pk_mul_f32 v[114:115], v[114:115], s[8:9] op_sel_hi:[1,0]
	v_pk_mul_f32 v[106:107], v[106:107], s[8:9] op_sel_hi:[1,0]
	v_pk_mul_f32 v[108:109], v[108:109], s[8:9] op_sel_hi:[1,0]
	v_pk_mul_f32 v[98:99], v[98:99], s[8:9] op_sel_hi:[1,0]
	v_pk_mul_f32 v[90:91], v[90:91], s[8:9] op_sel_hi:[1,0]
	v_pk_mul_f32 v[92:93], v[92:93], s[8:9] op_sel_hi:[1,0]
	v_pk_mul_f32 v[82:83], v[82:83], s[8:9] op_sel_hi:[1,0]
	v_pk_mul_f32 v[74:75], v[74:75], s[8:9] op_sel_hi:[1,0]
	v_pk_mul_f32 v[76:77], v[76:77], s[8:9] op_sel_hi:[1,0]
	v_pk_mul_f32 v[50:51], v[50:51], s[8:9] op_sel_hi:[1,0]
	v_pk_mul_f32 v[42:43], v[42:43], s[8:9] op_sel_hi:[1,0]
	v_pk_mul_f32 v[44:45], v[44:45], s[8:9] op_sel_hi:[1,0]
	v_pk_mul_f32 v[34:35], v[34:35], s[8:9] op_sel_hi:[1,0]
	v_pk_mul_f32 v[26:27], v[26:27], s[8:9] op_sel_hi:[1,0]
	v_pk_mul_f32 v[28:29], v[28:29], s[8:9] op_sel_hi:[1,0]
	v_pk_mul_f32 v[18:19], v[18:19], s[8:9] op_sel_hi:[1,0]
	v_pk_mul_f32 v[10:11], v[10:11], s[8:9] op_sel_hi:[1,0]
	v_pk_mul_f32 v[12:13], v[12:13], s[8:9] op_sel_hi:[1,0]
	v_pk_mul_f32 v[2:3], v[8:9], s[8:9] op_sel_hi:[1,0]
	v_pk_mul_f32 v[4:5], v[6:7], s[8:9] op_sel_hi:[1,0]
	v_pk_mul_f32 v[6:7], v[24:25], s[8:9] op_sel_hi:[1,0]
	v_pk_mul_f32 v[8:9], v[22:23], s[8:9] op_sel_hi:[1,0]
	s_and_b64 vcc, exec, s[4:5]
	s_cbranch_vccz .LBB0_409

; #define PG8_STAGE(bufoff, gbase, X) do { _Pragma("unroll") for (int _i = 0; _i < 2; ++_i) { \
;         const char* gp_ = (const char*)(gbase) + (_i ? rs##X : (size_t)0); const unsigned la_ = (unsigned)(size_t)(lds + (bufoff) + ldsw + _i * 8192); \
;         asm volatile("s_mov_b32 m0, %2\n\ts_nop 0\n\tglobal_load_lds_dwordx4 %0, %1" :: "v"(voff##X), "s"(gp_), "s"(la_) : "memory", "m0"); } } while (0)
; #define PG8_LDA(dst, b, h) do { _Pragma("unroll") for (int m = 0; m < 4; ++m) _Pragma("unroll") for (int k = 0; k < 2; ++k) dst[m][k] = *(const LAS bf16x8*)(lds + PG8_SA(b, h) + aoff + m * 2048 + k * 1024); } while (0)
; #define PG8_LDB(dst, b, h) do { _Pragma("unroll") for (int n = 0; n < 2; ++n) _Pragma("unroll") for (int k = 0; k < 2; ++k) dst[n][k] = *(const LAS bf16x8*)(lds + PG8_SB(b, h) + boff + n * 2048 + k * 1024); } while (0)
; #define PG8_WAIT_V(n) asm volatile("s_waitcnt vmcnt(" #n ")" ::: "memory")
; #define PG8_WAIT_L(n) asm volatile("s_waitcnt lgkmcnt(" #n ")" ::: "memory")
; #define PG8_BAR __builtin_amdgcn_s_barrier()
; #define PG8_SCHED __builtin_amdgcn_sched_barrier(0)
; template <class Epi>
; __device__ __forceinline__ void gemm_phase(LAS unsigned char* lds, const Gemm g_in, const StaticOrder& S, const Epi& E) {
;     ...
;             PG8_LDB(B0, 0, 0); PG8_LDB(B1, 0, 1); PG8_SCHED; PG8_LDA(At, 0, 0); PG8_STAGE(PG8_SA(1, 1), a1 + hsA, A);
;             PG8_WAIT_V(8); PG8_WAIT_L(0); PG8_BAR; PG8_MMA(0, 0, At, B0); PG8_MMA(0, 1, At, B1); PG8_BAR; PG8_SCHED;
;             PG8_LDA(At, 0, 1); PG8_STAGE(PG8_SB(0, 0), b2, B); PG8_STAGE(PG8_SB(0, 1), b2 + hsB, B); PG8_STAGE(PG8_SA(0, 0), a2, A);
;             PG8_WAIT_V(8); PG8_WAIT_L(0); PG8_BAR; PG8_MMA(1, 0, At, B0); PG8_MMA(1, 1, At, B1); PG8_BAR; PG8_SCHED;
.LBB0_751:
	ds_read_b128 v[130:133], v157
	ds_read_b128 v[134:137], v157 offset:1024
	ds_read_b128 v[142:145], v157 offset:2048
	ds_read_b128 v[146:149], v157 offset:3072
	ds_read_b128 v[168:171], v158
	ds_read_b128 v[172:175], v158 offset:1024
	ds_read_b128 v[184:187], v158 offset:2048
	ds_read_b128 v[188:191], v158 offset:3072
	s_add_i32 s62, s24, 2
	s_add_u32 s26, s22, 0xfffa0080
	s_addc_u32 s25, s23, -1
	s_cmp_eq_u32 s55, s24
	s_cselect_b32 s24, s11, s26
	s_cselect_b32 s25, s1, s25
	s_cselect_b32 s28, s59, s60
	s_cselect_b32 s29, s58, s61
	s_add_u32 s26, s24, 0x80
	s_addc_u32 s27, s25, 0
	ds_read_b128 v[192:195], v159
	ds_read_b128 v[196:199], v159 offset:1024
	ds_read_b128 v[204:207], v159 offset:2048
	ds_read_b128 v[208:211], v159 offset:3072
	ds_read_b128 v[212:215], v159 offset:4096
	ds_read_b128 v[216:219], v159 offset:5120
	ds_read_b128 v[220:223], v159 offset:6144
	ds_read_b128 v[224:227], v159 offset:7168
	s_add_u32 s64, s22, 0xfffe0000
	s_addc_u32 s65, s23, -1
	s_mov_b32 m0, s56
	s_nop 0
	global_load_lds_dwordx4 v1, s[64:65]
	s_nop 0
	s_mov_b32 m0, s57
	s_nop 0
	global_load_lds_dwordx4 v1, s[22:23]
	s_waitcnt vmcnt(8)
	s_waitcnt lgkmcnt(0)
	s_barrier
	s_waitcnt lgkmcnt(7)
	v_mfma_f32_16x16x32_bf16 v[126:129], v[130:133], v[192:195], v[126:129]
	v_mfma_f32_16x16x32_bf16 v[122:125], v[142:145], v[192:195], v[122:125]
	s_waitcnt lgkmcnt(5)
	v_mfma_f32_16x16x32_bf16 v[118:121], v[130:133], v[204:207], v[118:121]
	v_mfma_f32_16x16x32_bf16 v[114:117], v[142:145], v[204:207], v[114:117]
	s_waitcnt lgkmcnt(3)
	v_mfma_f32_16x16x32_bf16 v[110:113], v[130:133], v[212:215], v[110:113]
	v_mfma_f32_16x16x32_bf16 v[106:109], v[142:145], v[212:215], v[106:109]
	s_waitcnt lgkmcnt(1)
	v_mfma_f32_16x16x32_bf16 v[102:105], v[130:133], v[220:223], v[102:105]
	v_mfma_f32_16x16x32_bf16 v[94:97], v[142:145], v[220:223], v[94:97]
	v_mfma_f32_16x16x32_bf16 v[126:129], v[134:137], v[196:199], v[126:129]
	v_mfma_f32_16x16x32_bf16 v[122:125], v[146:149], v[196:199], v[122:125]
	v_mfma_f32_16x16x32_bf16 v[118:121], v[134:137], v[208:211], v[118:121]
	v_mfma_f32_16x16x32_bf16 v[114:117], v[146:149], v[208:211], v[114:117]
	v_mfma_f32_16x16x32_bf16 v[110:113], v[134:137], v[216:219], v[110:113]
	v_mfma_f32_16x16x32_bf16 v[106:109], v[146:149], v[216:219], v[106:109]
	s_waitcnt lgkmcnt(0)
	v_mfma_f32_16x16x32_bf16 v[102:105], v[134:137], v[224:227], v[102:105]
	v_mfma_f32_16x16x32_bf16 v[94:97], v[146:149], v[224:227], v[94:97]
	v_mfma_f32_16x16x32_bf16 v[62:65], v[168:171], v[192:195], v[62:65]
	v_mfma_f32_16x16x32_bf16 v[58:61], v[184:187], v[192:195], v[58:61]
	v_mfma_f32_16x16x32_bf16 v[54:57], v[168:171], v[204:207], v[54:57]
	v_mfma_f32_16x16x32_bf16 v[50:53], v[184:187], v[204:207], v[50:53]
	v_mfma_f32_16x16x32_bf16 v[46:49], v[168:171], v[212:215], v[46:49]
	v_mfma_f32_16x16x32_bf16 v[42:45], v[184:187], v[212:215], v[42:45]
	v_mfma_f32_16x16x32_bf16 v[38:41], v[168:171], v[220:223], v[38:41]
	v_mfma_f32_16x16x32_bf16 v[34:37], v[184:187], v[220:223], v[34:37]
	v_mfma_f32_16x16x32_bf16 v[62:65], v[172:175], v[196:199], v[62:65]
	v_mfma_f32_16x16x32_bf16 v[58:61], v[188:191], v[196:199], v[58:61]
	v_mfma_f32_16x16x32_bf16 v[54:57], v[172:175], v[208:211], v[54:57]
	v_mfma_f32_16x16x32_bf16 v[50:53], v[188:191], v[208:211], v[50:53]
	v_mfma_f32_16x16x32_bf16 v[46:49], v[172:175], v[216:219], v[46:49]
	v_mfma_f32_16x16x32_bf16 v[42:45], v[188:191], v[216:219], v[42:45]
	v_mfma_f32_16x16x32_bf16 v[38:41], v[172:175], v[224:227], v[38:41]
	v_mfma_f32_16x16x32_bf16 v[34:37], v[188:191], v[224:227], v[34:37]
	s_barrier
	s_add_u32 s64, s28, 0x8000
	ds_read_b128 v[192:195], v159 offset:16384
	ds_read_b128 v[196:199], v159 offset:17408
	ds_read_b128 v[204:207], v159 offset:18432
	ds_read_b128 v[208:211], v159 offset:19456
	ds_read_b128 v[212:215], v159 offset:20480
	ds_read_b128 v[216:219], v159 offset:21504
	ds_read_b128 v[220:223], v159 offset:22528
	ds_read_b128 v[224:227], v159 offset:23552
	s_mov_b32 m0, s42
	s_nop 0
	global_load_lds_dwordx4 v154, s[28:29]
	s_addc_u32 s65, s29, 0
	s_mov_b32 m0, s43
	s_nop 0
	global_load_lds_dwordx4 v154, s[64:65]
	s_add_u32 s64, s28, 0x10000
	s_addc_u32 s65, s29, 0
	s_mov_b32 m0, s44
	s_nop 0
	global_load_lds_dwordx4 v154, s[64:65]
	s_add_u32 s64, s28, 0x18000
	s_addc_u32 s65, s29, 0
	s_mov_b32 m0, s45
	s_nop 0
	global_load_lds_dwordx4 v154, s[64:65]
	s_add_u32 s64, s24, 0x20000
	s_mov_b32 m0, s41
	s_nop 0
	global_load_lds_dwordx4 v1, s[24:25]
	s_addc_u32 s65, s25, 0
	s_mov_b32 m0, s46
	s_nop 0
	global_load_lds_dwordx4 v1, s[64:65]
	s_waitcnt vmcnt(8)
	s_waitcnt lgkmcnt(0)
	s_barrier
; #define PG8_STAGE(bufoff, gbase, X) do { _Pragma("unroll") for (int _i = 0; _i < 2; ++_i) { \
;         const char* gp_ = (const char*)(gbase) + (_i ? rs##X : (size_t)0); const unsigned la_ = (unsigned)(size_t)(lds + (bufoff) + ldsw + _i * 8192); \
;         asm volatile("s_mov_b32 m0, %2\n\ts_nop 0\n\tglobal_load_lds_dwordx4 %0, %1" :: "v"(voff##X), "s"(gp_), "s"(la_) : "memory", "m0"); } } while (0)
; #define PG8_LDA(dst, b, h) do { _Pragma("unroll") for (int m = 0; m < 4; ++m) _Pragma("unroll") for (int k = 0; k < 2; ++k) dst[m][k] = *(const LAS bf16x8*)(lds + PG8_SA(b, h) + aoff + m * 2048 + k * 1024); } while (0)
; #define PG8_LDB(dst, b, h) do { _Pragma("unroll") for (int n = 0; n < 2; ++n) _Pragma("unroll") for (int k = 0; k < 2; ++k) dst[n][k] = *(const LAS bf16x8*)(lds + PG8_SB(b, h) + boff + n * 2048 + k * 1024); } while (0)
; #define PG8_WAIT_V(n) asm volatile("s_waitcnt vmcnt(" #n ")" ::: "memory")
; #define PG8_WAIT_L(n) asm volatile("s_waitcnt lgkmcnt(" #n ")" ::: "memory")
; #define PG8_BAR __builtin_amdgcn_s_barrier()
; #define PG8_SCHED __builtin_amdgcn_sched_barrier(0)
; template <class Epi>
; __device__ __forceinline__ void gemm_phase(LAS unsigned char* lds, const Gemm g_in, const StaticOrder& S, const Epi& E) {
;     ...
;             PG8_WAIT_V(8); PG8_WAIT_L(0); PG8_BAR; PG8_MMA(0, 0, At, B0); PG8_MMA(0, 1, At, B1); PG8_BAR; PG8_SCHED;
;             PG8_LDA(At, 0, 1); PG8_STAGE(PG8_SB(0, 0), b2, B); PG8_STAGE(PG8_SB(0, 1), b2 + hsB, B); PG8_STAGE(PG8_SA(0, 0), a2, A);
;             PG8_WAIT_V(8); PG8_WAIT_L(0); PG8_BAR; PG8_MMA(1, 0, At, B0); PG8_MMA(1, 1, At, B1); PG8_BAR; PG8_SCHED;
;             PG8_LDB(B0, 1, 0); PG8_LDB(B1, 1, 1); PG8_SCHED; PG8_LDA(At, 1, 0); PG8_STAGE(PG8_SA(0, 1), a2 + hsA, A);
;             PG8_WAIT_V(8); PG8_WAIT_L(0); PG8_BAR; PG8_MMA(0, 0, At, B0); PG8_MMA(0, 1, At, B1); PG8_BAR; PG8_SCHED;
;             PG8_LDA(At, 1, 1); PG8_STAGE(PG8_SB(1, 0), b3, B); PG8_STAGE(PG8_SB(1, 1), b3 + hsB, B); PG8_STAGE(PG8_SA(1, 0), a3, A);
	s_waitcnt lgkmcnt(7)
	v_mfma_f32_16x16x32_bf16 v[98:101], v[130:133], v[192:195], v[98:101]
	v_mfma_f32_16x16x32_bf16 v[90:93], v[142:145], v[192:195], v[90:93]
	s_waitcnt lgkmcnt(5)
	v_mfma_f32_16x16x32_bf16 v[86:89], v[130:133], v[204:207], v[86:89]
	v_mfma_f32_16x16x32_bf16 v[82:85], v[142:145], v[204:207], v[82:85]
	s_waitcnt lgkmcnt(3)
	v_mfma_f32_16x16x32_bf16 v[78:81], v[130:133], v[212:215], v[78:81]
	v_mfma_f32_16x16x32_bf16 v[74:77], v[142:145], v[212:215], v[74:77]
	s_waitcnt lgkmcnt(1)
	v_mfma_f32_16x16x32_bf16 v[70:73], v[130:133], v[220:223], v[70:73]
	v_mfma_f32_16x16x32_bf16 v[66:69], v[142:145], v[220:223], v[66:69]
	v_mfma_f32_16x16x32_bf16 v[98:101], v[134:137], v[196:199], v[98:101]
	v_mfma_f32_16x16x32_bf16 v[90:93], v[146:149], v[196:199], v[90:93]
	v_mfma_f32_16x16x32_bf16 v[86:89], v[134:137], v[208:211], v[86:89]
	v_mfma_f32_16x16x32_bf16 v[82:85], v[146:149], v[208:211], v[82:85]
	v_mfma_f32_16x16x32_bf16 v[78:81], v[134:137], v[216:219], v[78:81]
	v_mfma_f32_16x16x32_bf16 v[74:77], v[146:149], v[216:219], v[74:77]
	s_waitcnt lgkmcnt(0)
	v_mfma_f32_16x16x32_bf16 v[70:73], v[134:137], v[224:227], v[70:73]
	v_mfma_f32_16x16x32_bf16 v[66:69], v[146:149], v[224:227], v[66:69]
	v_mfma_f32_16x16x32_bf16 v[30:33], v[168:171], v[192:195], v[30:33]
	v_mfma_f32_16x16x32_bf16 v[26:29], v[184:187], v[192:195], v[26:29]
	v_mfma_f32_16x16x32_bf16 v[22:25], v[168:171], v[204:207], v[22:25]
	v_mfma_f32_16x16x32_bf16 v[18:21], v[184:187], v[204:207], v[18:21]
	v_mfma_f32_16x16x32_bf16 v[14:17], v[168:171], v[212:215], v[14:17]
	v_mfma_f32_16x16x32_bf16 v[10:13], v[184:187], v[212:215], v[10:13]
	v_mfma_f32_16x16x32_bf16 v[6:9], v[168:171], v[220:223], v[6:9]
	v_mfma_f32_16x16x32_bf16 v[2:5], v[184:187], v[220:223], v[2:5]
	v_mfma_f32_16x16x32_bf16 v[30:33], v[172:175], v[196:199], v[30:33]
	v_mfma_f32_16x16x32_bf16 v[26:29], v[188:191], v[196:199], v[26:29]
	v_mfma_f32_16x16x32_bf16 v[22:25], v[172:175], v[208:211], v[22:25]
	v_mfma_f32_16x16x32_bf16 v[18:21], v[188:191], v[208:211], v[18:21]
	v_mfma_f32_16x16x32_bf16 v[14:17], v[172:175], v[216:219], v[14:17]
	v_mfma_f32_16x16x32_bf16 v[10:13], v[188:191], v[216:219], v[10:13]
	v_mfma_f32_16x16x32_bf16 v[6:9], v[172:175], v[224:227], v[6:9]
	v_mfma_f32_16x16x32_bf16 v[2:5], v[188:191], v[224:227], v[2:5]
	s_barrier
	ds_read_b128 v[130:133], v160
	ds_read_b128 v[134:137], v160 offset:1024
	ds_read_b128 v[142:145], v160 offset:2048
	ds_read_b128 v[146:149], v160 offset:3072
	ds_read_b128 v[168:171], v161
	ds_read_b128 v[172:175], v161 offset:1024
	ds_read_b128 v[184:187], v161 offset:2048
	ds_read_b128 v[188:191], v161 offset:3072
	ds_read_b128 v[192:195], v159 offset:32768
	ds_read_b128 v[196:199], v159 offset:33792
	ds_read_b128 v[204:207], v159 offset:34816
	ds_read_b128 v[208:211], v159 offset:35840
	ds_read_b128 v[212:215], v159 offset:36864
	ds_read_b128 v[216:219], v159 offset:37888
	ds_read_b128 v[220:223], v159 offset:38912
	ds_read_b128 v[224:227], v159 offset:39936
	s_add_u32 s64, s24, 0x40000
	s_addc_u32 s65, s25, 0
	s_mov_b32 m0, s47
	s_nop 0
	global_load_lds_dwordx4 v1, s[64:65]
	s_add_u32 s64, s24, 0x60000
	s_addc_u32 s65, s25, 0
	s_mov_b32 m0, s48
	s_nop 0
	global_load_lds_dwordx4 v1, s[64:65]
	s_waitcnt vmcnt(8)
	s_waitcnt lgkmcnt(0)
	s_barrier
	s_waitcnt lgkmcnt(7)
	v_mfma_f32_16x16x32_bf16 v[126:129], v[130:133], v[192:195], v[126:129]
	v_mfma_f32_16x16x32_bf16 v[122:125], v[142:145], v[192:195], v[122:125]
	s_waitcnt lgkmcnt(5)
	v_mfma_f32_16x16x32_bf16 v[118:121], v[130:133], v[204:207], v[118:121]
	v_mfma_f32_16x16x32_bf16 v[114:117], v[142:145], v[204:207], v[114:117]
	s_waitcnt lgkmcnt(3)
	v_mfma_f32_16x16x32_bf16 v[110:113], v[130:133], v[212:215], v[110:113]
	v_mfma_f32_16x16x32_bf16 v[106:109], v[142:145], v[212:215], v[106:109]
	s_waitcnt lgkmcnt(1)
	v_mfma_f32_16x16x32_bf16 v[102:105], v[130:133], v[220:223], v[102:105]
	v_mfma_f32_16x16x32_bf16 v[94:97], v[142:145], v[220:223], v[94:97]
	v_mfma_f32_16x16x32_bf16 v[126:129], v[134:137], v[196:199], v[126:129]
	v_mfma_f32_16x16x32_bf16 v[122:125], v[146:149], v[196:199], v[122:125]
	v_mfma_f32_16x16x32_bf16 v[118:121], v[134:137], v[208:211], v[118:121]
	v_mfma_f32_16x16x32_bf16 v[114:117], v[146:149], v[208:211], v[114:117]
	v_mfma_f32_16x16x32_bf16 v[110:113], v[134:137], v[216:219], v[110:113]
	v_mfma_f32_16x16x32_bf16 v[106:109], v[146:149], v[216:219], v[106:109]
	s_waitcnt lgkmcnt(0)
	v_mfma_f32_16x16x32_bf16 v[102:105], v[134:137], v[224:227], v[102:105]
	v_mfma_f32_16x16x32_bf16 v[94:97], v[146:149], v[224:227], v[94:97]
	v_mfma_f32_16x16x32_bf16 v[62:65], v[168:171], v[192:195], v[62:65]
	v_mfma_f32_16x16x32_bf16 v[58:61], v[184:187], v[192:195], v[58:61]
	v_mfma_f32_16x16x32_bf16 v[54:57], v[168:171], v[204:207], v[54:57]
	v_mfma_f32_16x16x32_bf16 v[50:53], v[184:187], v[204:207], v[50:53]
	v_mfma_f32_16x16x32_bf16 v[46:49], v[168:171], v[212:215], v[46:49]
	v_mfma_f32_16x16x32_bf16 v[42:45], v[184:187], v[212:215], v[42:45]
	v_mfma_f32_16x16x32_bf16 v[38:41], v[168:171], v[220:223], v[38:41]
	v_mfma_f32_16x16x32_bf16 v[34:37], v[184:187], v[220:223], v[34:37]
	v_mfma_f32_16x16x32_bf16 v[62:65], v[172:175], v[196:199], v[62:65]
	v_mfma_f32_16x16x32_bf16 v[58:61], v[188:191], v[196:199], v[58:61]
	v_mfma_f32_16x16x32_bf16 v[54:57], v[172:175], v[208:211], v[54:57]
	v_mfma_f32_16x16x32_bf16 v[50:53], v[188:191], v[208:211], v[50:53]
	v_mfma_f32_16x16x32_bf16 v[46:49], v[172:175], v[216:219], v[46:49]
	v_mfma_f32_16x16x32_bf16 v[42:45], v[188:191], v[216:219], v[42:45]
	v_mfma_f32_16x16x32_bf16 v[38:41], v[172:175], v[224:227], v[38:41]
	v_mfma_f32_16x16x32_bf16 v[34:37], v[188:191], v[224:227], v[34:37]
	s_barrier
; #define PG8_STAGE(bufoff, gbase, X) do { _Pragma("unroll") for (int _i = 0; _i < 2; ++_i) { \
;         const char* gp_ = (const char*)(gbase) + (_i ? rs##X : (size_t)0); const unsigned la_ = (unsigned)(size_t)(lds + (bufoff) + ldsw + _i * 8192); \
;         asm volatile("s_mov_b32 m0, %2\n\ts_nop 0\n\tglobal_load_lds_dwordx4 %0, %1" :: "v"(voff##X), "s"(gp_), "s"(la_) : "memory", "m0"); } } while (0)
; #define PG8_LDA(dst, b, h) do { _Pragma("unroll") for (int m = 0; m < 4; ++m) _Pragma("unroll") for (int k = 0; k < 2; ++k) dst[m][k] = *(const LAS bf16x8*)(lds + PG8_SA(b, h) + aoff + m * 2048 + k * 1024); } while (0)
; #define PG8_LDB(dst, b, h) do { _Pragma("unroll") for (int n = 0; n < 2; ++n) _Pragma("unroll") for (int k = 0; k < 2; ++k) dst[n][k] = *(const LAS bf16x8*)(lds + PG8_SB(b, h) + boff + n * 2048 + k * 1024); } while (0)
; #define PG8_WAIT_V(n) asm volatile("s_waitcnt vmcnt(" #n ")" ::: "memory")
; #define PG8_WAIT_L(n) asm volatile("s_waitcnt lgkmcnt(" #n ")" ::: "memory")
; #define PG8_BAR __builtin_amdgcn_s_barrier()
; #define PG8_SCHED __builtin_amdgcn_sched_barrier(0)
; template <class Epi>
; __device__ __forceinline__ void gemm_phase(LAS unsigned char* lds, const Gemm g_in, const StaticOrder& S, const Epi& E) {
;     ...
;             PG8_LDB(B0, 1, 0); PG8_LDB(B1, 1, 1); PG8_SCHED; PG8_LDA(At, 1, 0); PG8_STAGE(PG8_SA(0, 1), a2 + hsA, A);
;             PG8_WAIT_V(8); PG8_WAIT_L(0); PG8_BAR; PG8_MMA(0, 0, At, B0); PG8_MMA(0, 1, At, B1); PG8_BAR; PG8_SCHED;
;             PG8_LDA(At, 1, 1); PG8_STAGE(PG8_SB(1, 0), b3, B); PG8_STAGE(PG8_SB(1, 1), b3 + hsB, B); PG8_STAGE(PG8_SA(1, 0), a3, A);
;             PG8_WAIT_V(8); PG8_WAIT_L(0); PG8_BAR; PG8_MMA(1, 0, At, B0); PG8_MMA(1, 1, At, B1); PG8_BAR; PG8_SCHED;
;         }
	s_add_u32 s64, s28, 0x80
	s_addc_u32 s65, s29, 0
	ds_read_b128 v[192:195], v159 offset:49152
	ds_read_b128 v[196:199], v159 offset:50176
	ds_read_b128 v[204:207], v159 offset:51200
	ds_read_b128 v[208:211], v159 offset:52224
	ds_read_b128 v[212:215], v159 offset:53248
	ds_read_b128 v[216:219], v159 offset:54272
	ds_read_b128 v[220:223], v159 offset:55296
	ds_read_b128 v[224:227], v159 offset:56320
	s_mov_b32 m0, s49
	s_nop 0
	global_load_lds_dwordx4 v154, s[64:65]
	s_add_u32 s64, s28, 0x8080
	s_addc_u32 s65, s29, 0
	s_mov_b32 m0, s50
	s_nop 0
	global_load_lds_dwordx4 v154, s[64:65]
	s_add_u32 s64, s28, 0x10080
	s_addc_u32 s65, s29, 0
	s_mov_b32 m0, s53
	s_nop 0
	global_load_lds_dwordx4 v154, s[64:65]
	s_add_u32 s28, s28, 0x18080
	s_addc_u32 s29, s29, 0
	s_mov_b32 m0, s54
	s_nop 0
	global_load_lds_dwordx4 v154, s[28:29]
	s_add_u32 s24, s24, 0x20080
	s_mov_b32 m0, s51
	s_nop 0
	global_load_lds_dwordx4 v1, s[26:27]
	s_addc_u32 s25, s25, 0
	s_mov_b32 m0, s52
	s_nop 0
	global_load_lds_dwordx4 v1, s[24:25]
	s_waitcnt vmcnt(8)
	s_waitcnt lgkmcnt(0)
	s_barrier
	s_waitcnt lgkmcnt(7)
	v_mfma_f32_16x16x32_bf16 v[98:101], v[130:133], v[192:195], v[98:101]
	v_mfma_f32_16x16x32_bf16 v[90:93], v[142:145], v[192:195], v[90:93]
	s_waitcnt lgkmcnt(5)
	v_mfma_f32_16x16x32_bf16 v[86:89], v[130:133], v[204:207], v[86:89]
	v_mfma_f32_16x16x32_bf16 v[82:85], v[142:145], v[204:207], v[82:85]
	s_waitcnt lgkmcnt(3)
	v_mfma_f32_16x16x32_bf16 v[78:81], v[130:133], v[212:215], v[78:81]
	v_mfma_f32_16x16x32_bf16 v[74:77], v[142:145], v[212:215], v[74:77]
	s_waitcnt lgkmcnt(1)
	v_mfma_f32_16x16x32_bf16 v[70:73], v[130:133], v[220:223], v[70:73]
	v_mfma_f32_16x16x32_bf16 v[66:69], v[142:145], v[220:223], v[66:69]
	v_mfma_f32_16x16x32_bf16 v[98:101], v[134:137], v[196:199], v[98:101]
	v_mfma_f32_16x16x32_bf16 v[90:93], v[146:149], v[196:199], v[90:93]
	v_mfma_f32_16x16x32_bf16 v[86:89], v[134:137], v[208:211], v[86:89]
	v_mfma_f32_16x16x32_bf16 v[82:85], v[146:149], v[208:211], v[82:85]
	v_mfma_f32_16x16x32_bf16 v[78:81], v[134:137], v[216:219], v[78:81]
	v_mfma_f32_16x16x32_bf16 v[74:77], v[146:149], v[216:219], v[74:77]
	s_waitcnt lgkmcnt(0)
	v_mfma_f32_16x16x32_bf16 v[70:73], v[134:137], v[224:227], v[70:73]
	v_mfma_f32_16x16x32_bf16 v[66:69], v[146:149], v[224:227], v[66:69]
	v_mfma_f32_16x16x32_bf16 v[30:33], v[168:171], v[192:195], v[30:33]
	v_mfma_f32_16x16x32_bf16 v[26:29], v[184:187], v[192:195], v[26:29]
	v_mfma_f32_16x16x32_bf16 v[22:25], v[168:171], v[204:207], v[22:25]
	v_mfma_f32_16x16x32_bf16 v[18:21], v[184:187], v[204:207], v[18:21]
	v_mfma_f32_16x16x32_bf16 v[14:17], v[168:171], v[212:215], v[14:17]
	v_mfma_f32_16x16x32_bf16 v[10:13], v[184:187], v[212:215], v[10:13]
	v_mfma_f32_16x16x32_bf16 v[6:9], v[168:171], v[220:223], v[6:9]
	v_mfma_f32_16x16x32_bf16 v[2:5], v[184:187], v[220:223], v[2:5]
	v_mfma_f32_16x16x32_bf16 v[30:33], v[172:175], v[196:199], v[30:33]
	v_mfma_f32_16x16x32_bf16 v[26:29], v[188:191], v[196:199], v[26:29]
	v_mfma_f32_16x16x32_bf16 v[22:25], v[172:175], v[208:211], v[22:25]
	v_mfma_f32_16x16x32_bf16 v[18:21], v[188:191], v[208:211], v[18:21]
	v_mfma_f32_16x16x32_bf16 v[14:17], v[172:175], v[216:219], v[14:17]
	v_mfma_f32_16x16x32_bf16 v[10:13], v[188:191], v[216:219], v[10:13]
	v_mfma_f32_16x16x32_bf16 v[6:9], v[172:175], v[224:227], v[6:9]
	v_mfma_f32_16x16x32_bf16 v[2:5], v[188:191], v[224:227], v[2:5]
	s_barrier
	s_add_u32 s60, s60, 0x100
	s_addc_u32 s61, s61, 0
	s_add_u32 s22, s22, 0x100
	s_addc_u32 s23, s23, 0
	s_cmp_ge_i32 s62, s37
	s_mov_b32 s24, s62
	s_cbranch_scc0 .LBB0_751
	s_and_b64 vcc, exec, s[14:15]
	s_cbranch_vccz .LBB0_754

; #define PG8_STAGE(bufoff, gbase, X) do { _Pragma("unroll") for (int _i = 0; _i < 2; ++_i) { \
;         const char* gp_ = (const char*)(gbase) + (_i ? rs##X : (size_t)0); const unsigned la_ = (unsigned)(size_t)(lds + (bufoff) + ldsw + _i * 8192); \
;         asm volatile("s_mov_b32 m0, %2\n\ts_nop 0\n\tglobal_load_lds_dwordx4 %0, %1" :: "v"(voff##X), "s"(gp_), "s"(la_) : "memory", "m0"); } } while (0)
; #define PG8_LDA(dst, b, h) do { _Pragma("unroll") for (int m = 0; m < 4; ++m) _Pragma("unroll") for (int k = 0; k < 2; ++k) dst[m][k] = *(const LAS bf16x8*)(lds + PG8_SA(b, h) + aoff + m * 2048 + k * 1024); } while (0)
; #define PG8_LDB(dst, b, h) do { _Pragma("unroll") for (int n = 0; n < 2; ++n) _Pragma("unroll") for (int k = 0; k < 2; ++k) dst[n][k] = *(const LAS bf16x8*)(lds + PG8_SB(b, h) + boff + n * 2048 + k * 1024); } while (0)
; #define PG8_WAIT_V(n) asm volatile("s_waitcnt vmcnt(" #n ")" ::: "memory")
; #define PG8_WAIT_L(n) asm volatile("s_waitcnt lgkmcnt(" #n ")" ::: "memory")
; #define PG8_BAR __builtin_amdgcn_s_barrier()
; #define PG8_SCHED __builtin_amdgcn_sched_barrier(0)
; template <class Epi>
; __device__ __forceinline__ void gemm_phase(LAS unsigned char* lds, const Gemm g_in, const StaticOrder& S, const Epi& E) {
;     ...
;             PG8_LDB(B0, 0, 0); PG8_LDB(B1, 0, 1); PG8_SCHED; PG8_LDA(At, 0, 0); PG8_STAGE(PG8_SA(1, 1), a1 + hsA, A);
;             PG8_WAIT_V(8); PG8_WAIT_L(0); PG8_BAR; PG8_MMA(0, 0, At, B0); PG8_MMA(0, 1, At, B1); PG8_BAR; PG8_SCHED;
;             PG8_LDA(At, 0, 1); PG8_STAGE(PG8_SB(0, 0), b2, B); PG8_STAGE(PG8_SB(0, 1), b2 + hsB, B); PG8_STAGE(PG8_SA(0, 0), a2, A);
;             PG8_WAIT_V(8); PG8_WAIT_L(0); PG8_BAR; PG8_MMA(1, 0, At, B0); PG8_MMA(1, 1, At, B1); PG8_BAR; PG8_SCHED;
.LBB0_769:
	ds_read_b128 v[130:133], v147
	ds_read_b128 v[134:137], v147 offset:1024
	ds_read_b128 v[154:157], v147 offset:2048
	ds_read_b128 v[158:161], v147 offset:3072
	ds_read_b128 v[168:171], v148
	ds_read_b128 v[172:175], v148 offset:1024
	ds_read_b128 v[184:187], v148 offset:2048
	ds_read_b128 v[188:191], v148 offset:3072
	s_add_i32 s64, s10, 2
	s_add_u32 s28, s6, 0xfffa0080
	s_addc_u32 s11, s7, -1
	s_cmp_eq_u32 s57, s10
	s_cselect_b32 s10, s23, s28
	s_cselect_b32 s11, s21, s11
	s_cselect_b32 s30, s61, s62
	s_cselect_b32 s31, s60, s63
	s_add_u32 s28, s10, 0x80
	s_addc_u32 s29, s11, 0
	ds_read_b128 v[192:195], v149
	ds_read_b128 v[196:199], v149 offset:1024
	ds_read_b128 v[204:207], v149 offset:2048
	ds_read_b128 v[208:211], v149 offset:3072
	ds_read_b128 v[212:215], v149 offset:4096
	ds_read_b128 v[216:219], v149 offset:5120
	ds_read_b128 v[220:223], v149 offset:6144
	ds_read_b128 v[224:227], v149 offset:7168
	s_add_u32 s66, s6, 0xfffe0000
	s_addc_u32 s67, s7, -1
	s_mov_b32 m0, s58
	s_nop 0
	global_load_lds_dwordx4 v1, s[66:67]
	s_nop 0
	s_mov_b32 m0, s59
	s_nop 0
	global_load_lds_dwordx4 v1, s[6:7]
	s_waitcnt vmcnt(8)
	s_waitcnt lgkmcnt(0)
	s_barrier
	s_waitcnt lgkmcnt(7)
	v_mfma_f32_16x16x32_bf16 v[126:129], v[130:133], v[192:195], v[126:129]
	v_mfma_f32_16x16x32_bf16 v[122:125], v[154:157], v[192:195], v[122:125]
	s_waitcnt lgkmcnt(5)
	v_mfma_f32_16x16x32_bf16 v[118:121], v[130:133], v[204:207], v[118:121]
	v_mfma_f32_16x16x32_bf16 v[114:117], v[154:157], v[204:207], v[114:117]
	s_waitcnt lgkmcnt(3)
	v_mfma_f32_16x16x32_bf16 v[110:113], v[130:133], v[212:215], v[110:113]
	v_mfma_f32_16x16x32_bf16 v[106:109], v[154:157], v[212:215], v[106:109]
	s_waitcnt lgkmcnt(1)
	v_mfma_f32_16x16x32_bf16 v[102:105], v[130:133], v[220:223], v[102:105]
	v_mfma_f32_16x16x32_bf16 v[98:101], v[154:157], v[220:223], v[98:101]
	v_mfma_f32_16x16x32_bf16 v[126:129], v[134:137], v[196:199], v[126:129]
	v_mfma_f32_16x16x32_bf16 v[122:125], v[158:161], v[196:199], v[122:125]
	v_mfma_f32_16x16x32_bf16 v[118:121], v[134:137], v[208:211], v[118:121]
	v_mfma_f32_16x16x32_bf16 v[114:117], v[158:161], v[208:211], v[114:117]
	v_mfma_f32_16x16x32_bf16 v[110:113], v[134:137], v[216:219], v[110:113]
	v_mfma_f32_16x16x32_bf16 v[106:109], v[158:161], v[216:219], v[106:109]
	s_waitcnt lgkmcnt(0)
	v_mfma_f32_16x16x32_bf16 v[102:105], v[134:137], v[224:227], v[102:105]
	v_mfma_f32_16x16x32_bf16 v[98:101], v[158:161], v[224:227], v[98:101]
	v_mfma_f32_16x16x32_bf16 v[62:65], v[168:171], v[192:195], v[62:65]
	v_mfma_f32_16x16x32_bf16 v[58:61], v[184:187], v[192:195], v[58:61]
	v_mfma_f32_16x16x32_bf16 v[54:57], v[168:171], v[204:207], v[54:57]
	v_mfma_f32_16x16x32_bf16 v[50:53], v[184:187], v[204:207], v[50:53]
	v_mfma_f32_16x16x32_bf16 v[46:49], v[168:171], v[212:215], v[46:49]
	v_mfma_f32_16x16x32_bf16 v[42:45], v[184:187], v[212:215], v[42:45]
	v_mfma_f32_16x16x32_bf16 v[38:41], v[168:171], v[220:223], v[38:41]
	v_mfma_f32_16x16x32_bf16 v[34:37], v[184:187], v[220:223], v[34:37]
	v_mfma_f32_16x16x32_bf16 v[62:65], v[172:175], v[196:199], v[62:65]
	v_mfma_f32_16x16x32_bf16 v[58:61], v[188:191], v[196:199], v[58:61]
	v_mfma_f32_16x16x32_bf16 v[54:57], v[172:175], v[208:211], v[54:57]
	v_mfma_f32_16x16x32_bf16 v[50:53], v[188:191], v[208:211], v[50:53]
	v_mfma_f32_16x16x32_bf16 v[46:49], v[172:175], v[216:219], v[46:49]
	v_mfma_f32_16x16x32_bf16 v[42:45], v[188:191], v[216:219], v[42:45]
	v_mfma_f32_16x16x32_bf16 v[38:41], v[172:175], v[224:227], v[38:41]
	v_mfma_f32_16x16x32_bf16 v[34:37], v[188:191], v[224:227], v[34:37]
	s_barrier
	s_add_u32 s66, s30, 0x8000
	ds_read_b128 v[192:195], v149 offset:16384
	ds_read_b128 v[196:199], v149 offset:17408
	ds_read_b128 v[204:207], v149 offset:18432
	ds_read_b128 v[208:211], v149 offset:19456
	ds_read_b128 v[212:215], v149 offset:20480
	ds_read_b128 v[216:219], v149 offset:21504
	ds_read_b128 v[220:223], v149 offset:22528
	ds_read_b128 v[224:227], v149 offset:23552
	s_mov_b32 m0, s44
	s_nop 0
	global_load_lds_dwordx4 v144, s[30:31]
	s_addc_u32 s67, s31, 0
	s_mov_b32 m0, s45
	s_nop 0
	global_load_lds_dwordx4 v144, s[66:67]
	s_add_u32 s66, s30, 0x10000
	s_addc_u32 s67, s31, 0
	s_mov_b32 m0, s46
	s_nop 0
	global_load_lds_dwordx4 v144, s[66:67]
	s_add_u32 s66, s30, 0x18000
	s_addc_u32 s67, s31, 0
	s_mov_b32 m0, s47
	s_nop 0
	global_load_lds_dwordx4 v144, s[66:67]
	s_add_u32 s66, s10, 0x20000
	s_mov_b32 m0, s43
	s_nop 0
	global_load_lds_dwordx4 v1, s[10:11]
	s_addc_u32 s67, s11, 0
	s_mov_b32 m0, s48
	s_nop 0
	global_load_lds_dwordx4 v1, s[66:67]
	s_waitcnt vmcnt(8)
	s_waitcnt lgkmcnt(0)
	s_barrier
; #define PG8_STAGE(bufoff, gbase, X) do { _Pragma("unroll") for (int _i = 0; _i < 2; ++_i) { \
;         const char* gp_ = (const char*)(gbase) + (_i ? rs##X : (size_t)0); const unsigned la_ = (unsigned)(size_t)(lds + (bufoff) + ldsw + _i * 8192); \
;         asm volatile("s_mov_b32 m0, %2\n\ts_nop 0\n\tglobal_load_lds_dwordx4 %0, %1" :: "v"(voff##X), "s"(gp_), "s"(la_) : "memory", "m0"); } } while (0)
; #define PG8_LDA(dst, b, h) do { _Pragma("unroll") for (int m = 0; m < 4; ++m) _Pragma("unroll") for (int k = 0; k < 2; ++k) dst[m][k] = *(const LAS bf16x8*)(lds + PG8_SA(b, h) + aoff + m * 2048 + k * 1024); } while (0)
; #define PG8_LDB(dst, b, h) do { _Pragma("unroll") for (int n = 0; n < 2; ++n) _Pragma("unroll") for (int k = 0; k < 2; ++k) dst[n][k] = *(const LAS bf16x8*)(lds + PG8_SB(b, h) + boff + n * 2048 + k * 1024); } while (0)
; #define PG8_WAIT_V(n) asm volatile("s_waitcnt vmcnt(" #n ")" ::: "memory")
; #define PG8_WAIT_L(n) asm volatile("s_waitcnt lgkmcnt(" #n ")" ::: "memory")
; #define PG8_BAR __builtin_amdgcn_s_barrier()
; #define PG8_SCHED __builtin_amdgcn_sched_barrier(0)
; template <class Epi>
; __device__ __forceinline__ void gemm_phase(LAS unsigned char* lds, const Gemm g_in, const StaticOrder& S, const Epi& E) {
;     ...
;             PG8_WAIT_V(8); PG8_WAIT_L(0); PG8_BAR; PG8_MMA(0, 0, At, B0); PG8_MMA(0, 1, At, B1); PG8_BAR; PG8_SCHED;
;             PG8_LDA(At, 0, 1); PG8_STAGE(PG8_SB(0, 0), b2, B); PG8_STAGE(PG8_SB(0, 1), b2 + hsB, B); PG8_STAGE(PG8_SA(0, 0), a2, A);
;             PG8_WAIT_V(8); PG8_WAIT_L(0); PG8_BAR; PG8_MMA(1, 0, At, B0); PG8_MMA(1, 1, At, B1); PG8_BAR; PG8_SCHED;
;             PG8_LDB(B0, 1, 0); PG8_LDB(B1, 1, 1); PG8_SCHED; PG8_LDA(At, 1, 0); PG8_STAGE(PG8_SA(0, 1), a2 + hsA, A);
;             PG8_WAIT_V(8); PG8_WAIT_L(0); PG8_BAR; PG8_MMA(0, 0, At, B0); PG8_MMA(0, 1, At, B1); PG8_BAR; PG8_SCHED;
;             PG8_LDA(At, 1, 1); PG8_STAGE(PG8_SB(1, 0), b3, B); PG8_STAGE(PG8_SB(1, 1), b3 + hsB, B); PG8_STAGE(PG8_SA(1, 0), a3, A);
	s_waitcnt lgkmcnt(7)
	v_mfma_f32_16x16x32_bf16 v[94:97], v[130:133], v[192:195], v[94:97]
	v_mfma_f32_16x16x32_bf16 v[90:93], v[154:157], v[192:195], v[90:93]
	s_waitcnt lgkmcnt(5)
	v_mfma_f32_16x16x32_bf16 v[86:89], v[130:133], v[204:207], v[86:89]
	v_mfma_f32_16x16x32_bf16 v[82:85], v[154:157], v[204:207], v[82:85]
	s_waitcnt lgkmcnt(3)
	v_mfma_f32_16x16x32_bf16 v[78:81], v[130:133], v[212:215], v[78:81]
	v_mfma_f32_16x16x32_bf16 v[74:77], v[154:157], v[212:215], v[74:77]
	s_waitcnt lgkmcnt(1)
	v_mfma_f32_16x16x32_bf16 v[70:73], v[130:133], v[220:223], v[70:73]
	v_mfma_f32_16x16x32_bf16 v[66:69], v[154:157], v[220:223], v[66:69]
	v_mfma_f32_16x16x32_bf16 v[94:97], v[134:137], v[196:199], v[94:97]
	v_mfma_f32_16x16x32_bf16 v[90:93], v[158:161], v[196:199], v[90:93]
	v_mfma_f32_16x16x32_bf16 v[86:89], v[134:137], v[208:211], v[86:89]
	v_mfma_f32_16x16x32_bf16 v[82:85], v[158:161], v[208:211], v[82:85]
	v_mfma_f32_16x16x32_bf16 v[78:81], v[134:137], v[216:219], v[78:81]
	v_mfma_f32_16x16x32_bf16 v[74:77], v[158:161], v[216:219], v[74:77]
	s_waitcnt lgkmcnt(0)
	v_mfma_f32_16x16x32_bf16 v[70:73], v[134:137], v[224:227], v[70:73]
	v_mfma_f32_16x16x32_bf16 v[66:69], v[158:161], v[224:227], v[66:69]
	v_mfma_f32_16x16x32_bf16 v[30:33], v[168:171], v[192:195], v[30:33]
	v_mfma_f32_16x16x32_bf16 v[26:29], v[184:187], v[192:195], v[26:29]
	v_mfma_f32_16x16x32_bf16 v[22:25], v[168:171], v[204:207], v[22:25]
	v_mfma_f32_16x16x32_bf16 v[18:21], v[184:187], v[204:207], v[18:21]
	v_mfma_f32_16x16x32_bf16 v[14:17], v[168:171], v[212:215], v[14:17]
	v_mfma_f32_16x16x32_bf16 v[10:13], v[184:187], v[212:215], v[10:13]
	v_mfma_f32_16x16x32_bf16 v[6:9], v[168:171], v[220:223], v[6:9]
	v_mfma_f32_16x16x32_bf16 v[2:5], v[184:187], v[220:223], v[2:5]
	v_mfma_f32_16x16x32_bf16 v[30:33], v[172:175], v[196:199], v[30:33]
	v_mfma_f32_16x16x32_bf16 v[26:29], v[188:191], v[196:199], v[26:29]
	v_mfma_f32_16x16x32_bf16 v[22:25], v[172:175], v[208:211], v[22:25]
	v_mfma_f32_16x16x32_bf16 v[18:21], v[188:191], v[208:211], v[18:21]
	v_mfma_f32_16x16x32_bf16 v[14:17], v[172:175], v[216:219], v[14:17]
	v_mfma_f32_16x16x32_bf16 v[10:13], v[188:191], v[216:219], v[10:13]
	v_mfma_f32_16x16x32_bf16 v[6:9], v[172:175], v[224:227], v[6:9]
	v_mfma_f32_16x16x32_bf16 v[2:5], v[188:191], v[224:227], v[2:5]
	s_barrier
	ds_read_b128 v[130:133], v150
	ds_read_b128 v[134:137], v150 offset:1024
	ds_read_b128 v[154:157], v150 offset:2048
	ds_read_b128 v[158:161], v150 offset:3072
	ds_read_b128 v[168:171], v151
	ds_read_b128 v[172:175], v151 offset:1024
	ds_read_b128 v[184:187], v151 offset:2048
	ds_read_b128 v[188:191], v151 offset:3072
	ds_read_b128 v[192:195], v149 offset:32768
	ds_read_b128 v[196:199], v149 offset:33792
	ds_read_b128 v[204:207], v149 offset:34816
	ds_read_b128 v[208:211], v149 offset:35840
	ds_read_b128 v[212:215], v149 offset:36864
	ds_read_b128 v[216:219], v149 offset:37888
	ds_read_b128 v[220:223], v149 offset:38912
	ds_read_b128 v[224:227], v149 offset:39936
	s_add_u32 s66, s10, 0x40000
	s_addc_u32 s67, s11, 0
	s_mov_b32 m0, s49
	s_nop 0
	global_load_lds_dwordx4 v1, s[66:67]
	s_add_u32 s66, s10, 0x60000
	s_addc_u32 s67, s11, 0
	s_mov_b32 m0, s50
	s_nop 0
	global_load_lds_dwordx4 v1, s[66:67]
	s_waitcnt vmcnt(8)
	s_waitcnt lgkmcnt(0)
	s_barrier
	s_waitcnt lgkmcnt(7)
	v_mfma_f32_16x16x32_bf16 v[126:129], v[130:133], v[192:195], v[126:129]
	v_mfma_f32_16x16x32_bf16 v[122:125], v[154:157], v[192:195], v[122:125]
	s_waitcnt lgkmcnt(5)
	v_mfma_f32_16x16x32_bf16 v[118:121], v[130:133], v[204:207], v[118:121]
	v_mfma_f32_16x16x32_bf16 v[114:117], v[154:157], v[204:207], v[114:117]
	s_waitcnt lgkmcnt(3)
	v_mfma_f32_16x16x32_bf16 v[110:113], v[130:133], v[212:215], v[110:113]
	v_mfma_f32_16x16x32_bf16 v[106:109], v[154:157], v[212:215], v[106:109]
	s_waitcnt lgkmcnt(1)
	v_mfma_f32_16x16x32_bf16 v[102:105], v[130:133], v[220:223], v[102:105]
	v_mfma_f32_16x16x32_bf16 v[98:101], v[154:157], v[220:223], v[98:101]
	v_mfma_f32_16x16x32_bf16 v[126:129], v[134:137], v[196:199], v[126:129]
	v_mfma_f32_16x16x32_bf16 v[122:125], v[158:161], v[196:199], v[122:125]
	v_mfma_f32_16x16x32_bf16 v[118:121], v[134:137], v[208:211], v[118:121]
	v_mfma_f32_16x16x32_bf16 v[114:117], v[158:161], v[208:211], v[114:117]
	v_mfma_f32_16x16x32_bf16 v[110:113], v[134:137], v[216:219], v[110:113]
	v_mfma_f32_16x16x32_bf16 v[106:109], v[158:161], v[216:219], v[106:109]
	s_waitcnt lgkmcnt(0)
	v_mfma_f32_16x16x32_bf16 v[102:105], v[134:137], v[224:227], v[102:105]
	v_mfma_f32_16x16x32_bf16 v[98:101], v[158:161], v[224:227], v[98:101]
	v_mfma_f32_16x16x32_bf16 v[62:65], v[168:171], v[192:195], v[62:65]
	v_mfma_f32_16x16x32_bf16 v[58:61], v[184:187], v[192:195], v[58:61]
	v_mfma_f32_16x16x32_bf16 v[54:57], v[168:171], v[204:207], v[54:57]
	v_mfma_f32_16x16x32_bf16 v[50:53], v[184:187], v[204:207], v[50:53]
	v_mfma_f32_16x16x32_bf16 v[46:49], v[168:171], v[212:215], v[46:49]
	v_mfma_f32_16x16x32_bf16 v[42:45], v[184:187], v[212:215], v[42:45]
	v_mfma_f32_16x16x32_bf16 v[38:41], v[168:171], v[220:223], v[38:41]
	v_mfma_f32_16x16x32_bf16 v[34:37], v[184:187], v[220:223], v[34:37]
	v_mfma_f32_16x16x32_bf16 v[62:65], v[172:175], v[196:199], v[62:65]
	v_mfma_f32_16x16x32_bf16 v[58:61], v[188:191], v[196:199], v[58:61]
	v_mfma_f32_16x16x32_bf16 v[54:57], v[172:175], v[208:211], v[54:57]
	v_mfma_f32_16x16x32_bf16 v[50:53], v[188:191], v[208:211], v[50:53]
	v_mfma_f32_16x16x32_bf16 v[46:49], v[172:175], v[216:219], v[46:49]
	v_mfma_f32_16x16x32_bf16 v[42:45], v[188:191], v[216:219], v[42:45]
	v_mfma_f32_16x16x32_bf16 v[38:41], v[172:175], v[224:227], v[38:41]
	v_mfma_f32_16x16x32_bf16 v[34:37], v[188:191], v[224:227], v[34:37]
	s_barrier
; #define PG8_STAGE(bufoff, gbase, X) do { _Pragma("unroll") for (int _i = 0; _i < 2; ++_i) { \
;         const char* gp_ = (const char*)(gbase) + (_i ? rs##X : (size_t)0); const unsigned la_ = (unsigned)(size_t)(lds + (bufoff) + ldsw + _i * 8192); \
;         asm volatile("s_mov_b32 m0, %2\n\ts_nop 0\n\tglobal_load_lds_dwordx4 %0, %1" :: "v"(voff##X), "s"(gp_), "s"(la_) : "memory", "m0"); } } while (0)
; #define PG8_LDA(dst, b, h) do { _Pragma("unroll") for (int m = 0; m < 4; ++m) _Pragma("unroll") for (int k = 0; k < 2; ++k) dst[m][k] = *(const LAS bf16x8*)(lds + PG8_SA(b, h) + aoff + m * 2048 + k * 1024); } while (0)
; #define PG8_WAIT_V(n) asm volatile("s_waitcnt vmcnt(" #n ")" ::: "memory")
; #define PG8_WAIT_L(n) asm volatile("s_waitcnt lgkmcnt(" #n ")" ::: "memory")
; #define PG8_BAR __builtin_amdgcn_s_barrier()
; #define PG8_SCHED __builtin_amdgcn_sched_barrier(0)
; template <class Epi>
; __device__ __forceinline__ void gemm_phase(LAS unsigned char* lds, const Gemm g_in, const StaticOrder& S, const Epi& E) {
;     ...
;             PG8_LDA(At, 1, 1); PG8_STAGE(PG8_SB(1, 0), b3, B); PG8_STAGE(PG8_SB(1, 1), b3 + hsB, B); PG8_STAGE(PG8_SA(1, 0), a3, A);
;             PG8_WAIT_V(8); PG8_WAIT_L(0); PG8_BAR; PG8_MMA(1, 0, At, B0); PG8_MMA(1, 1, At, B1); PG8_BAR; PG8_SCHED;
;         }
	s_add_u32 s66, s30, 0x80
	s_addc_u32 s67, s31, 0
	ds_read_b128 v[192:195], v149 offset:49152
	ds_read_b128 v[196:199], v149 offset:50176
	ds_read_b128 v[204:207], v149 offset:51200
	ds_read_b128 v[208:211], v149 offset:52224
	ds_read_b128 v[212:215], v149 offset:53248
	ds_read_b128 v[216:219], v149 offset:54272
	ds_read_b128 v[220:223], v149 offset:55296
	ds_read_b128 v[224:227], v149 offset:56320
	s_mov_b32 m0, s51
	s_nop 0
	global_load_lds_dwordx4 v144, s[66:67]
	s_add_u32 s66, s30, 0x8080
	s_addc_u32 s67, s31, 0
	s_mov_b32 m0, s52
	s_nop 0
	global_load_lds_dwordx4 v144, s[66:67]
	s_add_u32 s66, s30, 0x10080
	s_addc_u32 s67, s31, 0
	s_mov_b32 m0, s55
	s_nop 0
	global_load_lds_dwordx4 v144, s[66:67]
	s_add_u32 s30, s30, 0x18080
	s_addc_u32 s31, s31, 0
	s_mov_b32 m0, s56
	s_nop 0
	global_load_lds_dwordx4 v144, s[30:31]
	s_add_u32 s10, s10, 0x20080
	s_mov_b32 m0, s53
	s_nop 0
	global_load_lds_dwordx4 v1, s[28:29]
	s_addc_u32 s11, s11, 0
	s_mov_b32 m0, s54
	s_nop 0
	global_load_lds_dwordx4 v1, s[10:11]
	s_waitcnt vmcnt(8)
	s_waitcnt lgkmcnt(0)
	s_barrier
	s_waitcnt lgkmcnt(7)
	v_mfma_f32_16x16x32_bf16 v[94:97], v[130:133], v[192:195], v[94:97]
	v_mfma_f32_16x16x32_bf16 v[90:93], v[154:157], v[192:195], v[90:93]
	s_waitcnt lgkmcnt(5)
	v_mfma_f32_16x16x32_bf16 v[86:89], v[130:133], v[204:207], v[86:89]
	v_mfma_f32_16x16x32_bf16 v[82:85], v[154:157], v[204:207], v[82:85]
	s_waitcnt lgkmcnt(3)
	v_mfma_f32_16x16x32_bf16 v[78:81], v[130:133], v[212:215], v[78:81]
	v_mfma_f32_16x16x32_bf16 v[74:77], v[154:157], v[212:215], v[74:77]
	s_waitcnt lgkmcnt(1)
	v_mfma_f32_16x16x32_bf16 v[70:73], v[130:133], v[220:223], v[70:73]
	v_mfma_f32_16x16x32_bf16 v[66:69], v[154:157], v[220:223], v[66:69]
	v_mfma_f32_16x16x32_bf16 v[94:97], v[134:137], v[196:199], v[94:97]
	v_mfma_f32_16x16x32_bf16 v[90:93], v[158:161], v[196:199], v[90:93]
	v_mfma_f32_16x16x32_bf16 v[86:89], v[134:137], v[208:211], v[86:89]
	v_mfma_f32_16x16x32_bf16 v[82:85], v[158:161], v[208:211], v[82:85]
	v_mfma_f32_16x16x32_bf16 v[78:81], v[134:137], v[216:219], v[78:81]
	v_mfma_f32_16x16x32_bf16 v[74:77], v[158:161], v[216:219], v[74:77]
	s_waitcnt lgkmcnt(0)
	v_mfma_f32_16x16x32_bf16 v[70:73], v[134:137], v[224:227], v[70:73]
	v_mfma_f32_16x16x32_bf16 v[66:69], v[158:161], v[224:227], v[66:69]
	v_mfma_f32_16x16x32_bf16 v[30:33], v[168:171], v[192:195], v[30:33]
	v_mfma_f32_16x16x32_bf16 v[26:29], v[184:187], v[192:195], v[26:29]
	v_mfma_f32_16x16x32_bf16 v[22:25], v[168:171], v[204:207], v[22:25]
	v_mfma_f32_16x16x32_bf16 v[18:21], v[184:187], v[204:207], v[18:21]
	v_mfma_f32_16x16x32_bf16 v[14:17], v[168:171], v[212:215], v[14:17]
	v_mfma_f32_16x16x32_bf16 v[10:13], v[184:187], v[212:215], v[10:13]
	v_mfma_f32_16x16x32_bf16 v[6:9], v[168:171], v[220:223], v[6:9]
	v_mfma_f32_16x16x32_bf16 v[2:5], v[184:187], v[220:223], v[2:5]
	v_mfma_f32_16x16x32_bf16 v[30:33], v[172:175], v[196:199], v[30:33]
	v_mfma_f32_16x16x32_bf16 v[26:29], v[188:191], v[196:199], v[26:29]
	v_mfma_f32_16x16x32_bf16 v[22:25], v[172:175], v[208:211], v[22:25]
	v_mfma_f32_16x16x32_bf16 v[18:21], v[188:191], v[208:211], v[18:21]
	v_mfma_f32_16x16x32_bf16 v[14:17], v[172:175], v[216:219], v[14:17]
	v_mfma_f32_16x16x32_bf16 v[10:13], v[188:191], v[216:219], v[10:13]
	v_mfma_f32_16x16x32_bf16 v[6:9], v[172:175], v[224:227], v[6:9]
	v_mfma_f32_16x16x32_bf16 v[2:5], v[188:191], v[224:227], v[2:5]
	s_barrier
	s_add_u32 s62, s62, 0x100
	s_addc_u32 s63, s63, 0
	s_add_u32 s6, s6, 0x100
	s_addc_u32 s7, s7, 0
	s_cmp_ge_i32 s64, s39
	s_mov_b32 s10, s64
	s_cbranch_scc0 .LBB0_769
	s_and_b64 vcc, exec, s[16:17]
	s_cbranch_vccz .LBB0_772

; #define PG8_STAGE(bufoff, gbase, X) do { _Pragma("unroll") for (int _i = 0; _i < 2; ++_i) { \
;         const char* gp_ = (const char*)(gbase) + (_i ? rs##X : (size_t)0); const unsigned la_ = (unsigned)(size_t)(lds + (bufoff) + ldsw + _i * 8192); \
;         asm volatile("s_mov_b32 m0, %2\n\ts_nop 0\n\tglobal_load_lds_dwordx4 %0, %1" :: "v"(voff##X), "s"(gp_), "s"(la_) : "memory", "m0"); } } while (0)
; #define PG8_LDA(dst, b, h) do { _Pragma("unroll") for (int m = 0; m < 4; ++m) _Pragma("unroll") for (int k = 0; k < 2; ++k) dst[m][k] = *(const LAS bf16x8*)(lds + PG8_SA(b, h) + aoff + m * 2048 + k * 1024); } while (0)
; #define PG8_LDB(dst, b, h) do { _Pragma("unroll") for (int n = 0; n < 2; ++n) _Pragma("unroll") for (int k = 0; k < 2; ++k) dst[n][k] = *(const LAS bf16x8*)(lds + PG8_SB(b, h) + boff + n * 2048 + k * 1024); } while (0)
; #define PG8_WAIT_V(n) asm volatile("s_waitcnt vmcnt(" #n ")" ::: "memory")
; #define PG8_WAIT_L(n) asm volatile("s_waitcnt lgkmcnt(" #n ")" ::: "memory")
; #define PG8_BAR __builtin_amdgcn_s_barrier()
; #define PG8_SCHED __builtin_amdgcn_sched_barrier(0)
; template <class Epi>
; __device__ __forceinline__ void gemm_phase(LAS unsigned char* lds, const Gemm g_in, const StaticOrder& S, const Epi& E) {
;     ...
;         const bool has_next = S.next(ui + 1, nxt);
;         const char* nA = has_next ? (const char*)g.A + (size_t)nxt.pm * tsA : cA; const char* nB = has_next ? (const char*)g.Bt + (size_t)nxt.pn * tsB : cB;
;         for (int t = 0; t < nt; t += 2) {
;             const bool last = (t == nt - 2);
;             const char* a1 = cA + (size_t)(t + 1) * kstep;
;             const char* a2 = last ? nA : cA + (size_t)(t + 2) * kstep; const char* b2 = last ? nB : cB + (size_t)(t + 2) * kstep;
;             const char* a3 = a2 + kstep; const char* b3 = b2 + kstep;
;             PG8_LDB(B0, 0, 0); PG8_LDB(B1, 0, 1); PG8_SCHED; PG8_LDA(At, 0, 0); PG8_STAGE(PG8_SA(1, 1), a1 + hsA, A);
;             PG8_WAIT_V(8); PG8_WAIT_L(0); PG8_BAR; PG8_MMA(0, 0, At, B0); PG8_MMA(0, 1, At, B1); PG8_BAR; PG8_SCHED;
;             PG8_LDA(At, 0, 1); PG8_STAGE(PG8_SB(0, 0), b2, B); PG8_STAGE(PG8_SB(0, 1), b2 + hsB, B); PG8_STAGE(PG8_SA(0, 0), a2, A);
;             PG8_WAIT_V(8); PG8_WAIT_L(0); PG8_BAR; PG8_MMA(1, 0, At, B0); PG8_MMA(1, 1, At, B1); PG8_BAR; PG8_SCHED;
.LBB0_787:
	ds_read_b128 v[142:145], v137
	ds_read_b128 v[146:149], v137 offset:1024
	ds_read_b128 v[154:157], v137 offset:2048
	ds_read_b128 v[158:161], v137 offset:3072
	ds_read_b128 v[168:171], v138
	ds_read_b128 v[172:175], v138 offset:1024
	ds_read_b128 v[184:187], v138 offset:2048
	ds_read_b128 v[188:191], v138 offset:3072
	s_add_i32 s63, s26, 2
	s_add_u32 s28, s24, 0xfffa0080
	s_addc_u32 s27, s25, -1
	s_cmp_eq_u32 s55, s26
	s_cselect_b32 s26, s17, s28
	s_cselect_b32 s27, s15, s27
	s_cselect_b32 s30, s60, s61
	s_cselect_b32 s31, s59, s62
	s_add_u32 s28, s26, 0x80
	s_addc_u32 s29, s27, 0
	ds_read_b128 v[192:195], v139
	ds_read_b128 v[196:199], v139 offset:1024
	ds_read_b128 v[204:207], v139 offset:2048
	ds_read_b128 v[208:211], v139 offset:3072
	ds_read_b128 v[212:215], v139 offset:4096
	ds_read_b128 v[216:219], v139 offset:5120
	ds_read_b128 v[220:223], v139 offset:6144
	ds_read_b128 v[224:227], v139 offset:7168
	s_add_u32 s64, s24, 0xfffe0000
	s_addc_u32 s65, s25, -1
	s_mov_b32 m0, s56
	s_nop 0
	global_load_lds_dwordx4 v1, s[64:65]
	s_nop 0
	s_mov_b32 m0, s57
	s_nop 0
	global_load_lds_dwordx4 v1, s[24:25]
	s_waitcnt vmcnt(8)
	s_waitcnt lgkmcnt(0)
	s_barrier
	s_waitcnt lgkmcnt(7)
	v_mfma_f32_16x16x32_bf16 v[126:129], v[142:145], v[192:195], v[126:129]
	v_mfma_f32_16x16x32_bf16 v[122:125], v[154:157], v[192:195], v[122:125]
	s_waitcnt lgkmcnt(5)
	v_mfma_f32_16x16x32_bf16 v[110:113], v[142:145], v[204:207], v[110:113]
	v_mfma_f32_16x16x32_bf16 v[106:109], v[154:157], v[204:207], v[106:109]
	s_waitcnt lgkmcnt(3)
	v_mfma_f32_16x16x32_bf16 v[94:97], v[142:145], v[212:215], v[94:97]
	v_mfma_f32_16x16x32_bf16 v[90:93], v[154:157], v[212:215], v[90:93]
	s_waitcnt lgkmcnt(1)
	v_mfma_f32_16x16x32_bf16 v[78:81], v[142:145], v[220:223], v[78:81]
	v_mfma_f32_16x16x32_bf16 v[74:77], v[154:157], v[220:223], v[74:77]
	v_mfma_f32_16x16x32_bf16 v[126:129], v[146:149], v[196:199], v[126:129]
	v_mfma_f32_16x16x32_bf16 v[122:125], v[158:161], v[196:199], v[122:125]
	v_mfma_f32_16x16x32_bf16 v[110:113], v[146:149], v[208:211], v[110:113]
	v_mfma_f32_16x16x32_bf16 v[106:109], v[158:161], v[208:211], v[106:109]
	v_mfma_f32_16x16x32_bf16 v[94:97], v[146:149], v[216:219], v[94:97]
	v_mfma_f32_16x16x32_bf16 v[90:93], v[158:161], v[216:219], v[90:93]
	s_waitcnt lgkmcnt(0)
	v_mfma_f32_16x16x32_bf16 v[78:81], v[146:149], v[224:227], v[78:81]
	v_mfma_f32_16x16x32_bf16 v[74:77], v[158:161], v[224:227], v[74:77]
	v_mfma_f32_16x16x32_bf16 v[118:121], v[168:171], v[192:195], v[118:121]
	v_mfma_f32_16x16x32_bf16 v[114:117], v[184:187], v[192:195], v[114:117]
	v_mfma_f32_16x16x32_bf16 v[102:105], v[168:171], v[204:207], v[102:105]
	v_mfma_f32_16x16x32_bf16 v[98:101], v[184:187], v[204:207], v[98:101]
	v_mfma_f32_16x16x32_bf16 v[86:89], v[168:171], v[212:215], v[86:89]
	v_mfma_f32_16x16x32_bf16 v[82:85], v[184:187], v[212:215], v[82:85]
	v_mfma_f32_16x16x32_bf16 v[70:73], v[168:171], v[220:223], v[70:73]
	v_mfma_f32_16x16x32_bf16 v[66:69], v[184:187], v[220:223], v[66:69]
	v_mfma_f32_16x16x32_bf16 v[118:121], v[172:175], v[196:199], v[118:121]
	v_mfma_f32_16x16x32_bf16 v[114:117], v[188:191], v[196:199], v[114:117]
	v_mfma_f32_16x16x32_bf16 v[102:105], v[172:175], v[208:211], v[102:105]
	v_mfma_f32_16x16x32_bf16 v[98:101], v[188:191], v[208:211], v[98:101]
	v_mfma_f32_16x16x32_bf16 v[86:89], v[172:175], v[216:219], v[86:89]
	v_mfma_f32_16x16x32_bf16 v[82:85], v[188:191], v[216:219], v[82:85]
	v_mfma_f32_16x16x32_bf16 v[70:73], v[172:175], v[224:227], v[70:73]
	v_mfma_f32_16x16x32_bf16 v[66:69], v[188:191], v[224:227], v[66:69]
	s_barrier
	s_add_u32 s64, s30, 0x10000
	ds_read_b128 v[192:195], v139 offset:16384
	ds_read_b128 v[196:199], v139 offset:17408
	ds_read_b128 v[204:207], v139 offset:18432
	ds_read_b128 v[208:211], v139 offset:19456
	ds_read_b128 v[212:215], v139 offset:20480
	ds_read_b128 v[216:219], v139 offset:21504
	ds_read_b128 v[220:223], v139 offset:22528
	ds_read_b128 v[224:227], v139 offset:23552
	s_mov_b32 m0, s42
	s_nop 0
	global_load_lds_dwordx4 v134, s[30:31]
	s_addc_u32 s65, s31, 0
	s_mov_b32 m0, s43
	s_nop 0
	global_load_lds_dwordx4 v134, s[64:65]
	s_add_u32 s64, s30, 0x20000
	s_addc_u32 s65, s31, 0
	s_mov_b32 m0, s44
	s_nop 0
	global_load_lds_dwordx4 v134, s[64:65]
	s_add_u32 s64, s30, 0x30000
	s_addc_u32 s65, s31, 0
	s_mov_b32 m0, s45
	s_nop 0
	global_load_lds_dwordx4 v134, s[64:65]
	s_add_u32 s64, s26, 0x20000
	s_mov_b32 m0, s13
	s_nop 0
	global_load_lds_dwordx4 v1, s[26:27]
	s_addc_u32 s65, s27, 0
	s_mov_b32 m0, s46
	s_nop 0
	global_load_lds_dwordx4 v1, s[64:65]
	s_waitcnt vmcnt(8)
	s_waitcnt lgkmcnt(0)
	s_barrier
; #define PG8_STAGE(bufoff, gbase, X) do { _Pragma("unroll") for (int _i = 0; _i < 2; ++_i) { \
;         const char* gp_ = (const char*)(gbase) + (_i ? rs##X : (size_t)0); const unsigned la_ = (unsigned)(size_t)(lds + (bufoff) + ldsw + _i * 8192); \
;         asm volatile("s_mov_b32 m0, %2\n\ts_nop 0\n\tglobal_load_lds_dwordx4 %0, %1" :: "v"(voff##X), "s"(gp_), "s"(la_) : "memory", "m0"); } } while (0)
; #define PG8_LDA(dst, b, h) do { _Pragma("unroll") for (int m = 0; m < 4; ++m) _Pragma("unroll") for (int k = 0; k < 2; ++k) dst[m][k] = *(const LAS bf16x8*)(lds + PG8_SA(b, h) + aoff + m * 2048 + k * 1024); } while (0)
; #define PG8_LDB(dst, b, h) do { _Pragma("unroll") for (int n = 0; n < 2; ++n) _Pragma("unroll") for (int k = 0; k < 2; ++k) dst[n][k] = *(const LAS bf16x8*)(lds + PG8_SB(b, h) + boff + n * 2048 + k * 1024); } while (0)
; #define PG8_WAIT_V(n) asm volatile("s_waitcnt vmcnt(" #n ")" ::: "memory")
; #define PG8_WAIT_L(n) asm volatile("s_waitcnt lgkmcnt(" #n ")" ::: "memory")
; #define PG8_BAR __builtin_amdgcn_s_barrier()
; #define PG8_SCHED __builtin_amdgcn_sched_barrier(0)
; template <class Epi>
; __device__ __forceinline__ void gemm_phase(LAS unsigned char* lds, const Gemm g_in, const StaticOrder& S, const Epi& E) {
;     ...
;             PG8_WAIT_V(8); PG8_WAIT_L(0); PG8_BAR; PG8_MMA(1, 0, At, B0); PG8_MMA(1, 1, At, B1); PG8_BAR; PG8_SCHED;
;             PG8_LDB(B0, 1, 0); PG8_LDB(B1, 1, 1); PG8_SCHED; PG8_LDA(At, 1, 0); PG8_STAGE(PG8_SA(0, 1), a2 + hsA, A);
;             PG8_WAIT_V(8); PG8_WAIT_L(0); PG8_BAR; PG8_MMA(0, 0, At, B0); PG8_MMA(0, 1, At, B1); PG8_BAR; PG8_SCHED;
	s_waitcnt lgkmcnt(7)
	v_mfma_f32_16x16x32_bf16 v[62:65], v[142:145], v[192:195], v[62:65]
	v_mfma_f32_16x16x32_bf16 v[58:61], v[154:157], v[192:195], v[58:61]
	s_waitcnt lgkmcnt(5)
	v_mfma_f32_16x16x32_bf16 v[46:49], v[142:145], v[204:207], v[46:49]
	v_mfma_f32_16x16x32_bf16 v[42:45], v[154:157], v[204:207], v[42:45]
	s_waitcnt lgkmcnt(3)
	v_mfma_f32_16x16x32_bf16 v[30:33], v[142:145], v[212:215], v[30:33]
	v_mfma_f32_16x16x32_bf16 v[26:29], v[154:157], v[212:215], v[26:29]
	s_waitcnt lgkmcnt(1)
	v_mfma_f32_16x16x32_bf16 v[14:17], v[142:145], v[220:223], v[14:17]
	v_mfma_f32_16x16x32_bf16 v[10:13], v[154:157], v[220:223], v[10:13]
	v_mfma_f32_16x16x32_bf16 v[62:65], v[146:149], v[196:199], v[62:65]
	v_mfma_f32_16x16x32_bf16 v[58:61], v[158:161], v[196:199], v[58:61]
	v_mfma_f32_16x16x32_bf16 v[46:49], v[146:149], v[208:211], v[46:49]
	v_mfma_f32_16x16x32_bf16 v[42:45], v[158:161], v[208:211], v[42:45]
	v_mfma_f32_16x16x32_bf16 v[30:33], v[146:149], v[216:219], v[30:33]
	v_mfma_f32_16x16x32_bf16 v[26:29], v[158:161], v[216:219], v[26:29]
	s_waitcnt lgkmcnt(0)
	v_mfma_f32_16x16x32_bf16 v[14:17], v[146:149], v[224:227], v[14:17]
	v_mfma_f32_16x16x32_bf16 v[10:13], v[158:161], v[224:227], v[10:13]
	v_mfma_f32_16x16x32_bf16 v[54:57], v[168:171], v[192:195], v[54:57]
	v_mfma_f32_16x16x32_bf16 v[50:53], v[184:187], v[192:195], v[50:53]
	v_mfma_f32_16x16x32_bf16 v[38:41], v[168:171], v[204:207], v[38:41]
	v_mfma_f32_16x16x32_bf16 v[34:37], v[184:187], v[204:207], v[34:37]
	v_mfma_f32_16x16x32_bf16 v[22:25], v[168:171], v[212:215], v[22:25]
	v_mfma_f32_16x16x32_bf16 v[18:21], v[184:187], v[212:215], v[18:21]
	v_mfma_f32_16x16x32_bf16 v[6:9], v[168:171], v[220:223], v[6:9]
	v_mfma_f32_16x16x32_bf16 v[2:5], v[184:187], v[220:223], v[2:5]
	v_mfma_f32_16x16x32_bf16 v[54:57], v[172:175], v[196:199], v[54:57]
	v_mfma_f32_16x16x32_bf16 v[50:53], v[188:191], v[196:199], v[50:53]
	v_mfma_f32_16x16x32_bf16 v[38:41], v[172:175], v[208:211], v[38:41]
	v_mfma_f32_16x16x32_bf16 v[34:37], v[188:191], v[208:211], v[34:37]
	v_mfma_f32_16x16x32_bf16 v[22:25], v[172:175], v[216:219], v[22:25]
	v_mfma_f32_16x16x32_bf16 v[18:21], v[188:191], v[216:219], v[18:21]
	v_mfma_f32_16x16x32_bf16 v[6:9], v[172:175], v[224:227], v[6:9]
	v_mfma_f32_16x16x32_bf16 v[2:5], v[188:191], v[224:227], v[2:5]
	s_barrier
	ds_read_b128 v[142:145], v140
	ds_read_b128 v[146:149], v140 offset:1024
	ds_read_b128 v[154:157], v140 offset:2048
	ds_read_b128 v[158:161], v140 offset:3072
	ds_read_b128 v[168:171], v141
	ds_read_b128 v[172:175], v141 offset:1024
	ds_read_b128 v[184:187], v141 offset:2048
	ds_read_b128 v[188:191], v141 offset:3072
	ds_read_b128 v[192:195], v139 offset:32768
	ds_read_b128 v[196:199], v139 offset:33792
	ds_read_b128 v[204:207], v139 offset:34816
	ds_read_b128 v[208:211], v139 offset:35840
	ds_read_b128 v[212:215], v139 offset:36864
	ds_read_b128 v[216:219], v139 offset:37888
	ds_read_b128 v[220:223], v139 offset:38912
	ds_read_b128 v[224:227], v139 offset:39936
	s_add_u32 s64, s26, 0x40000
	s_addc_u32 s65, s27, 0
	s_mov_b32 m0, s47
	s_nop 0
	global_load_lds_dwordx4 v1, s[64:65]
	s_add_u32 s64, s26, 0x60000
	s_addc_u32 s65, s27, 0
	s_mov_b32 m0, s48
	s_nop 0
	global_load_lds_dwordx4 v1, s[64:65]
	s_waitcnt vmcnt(8)
	s_waitcnt lgkmcnt(0)
	s_barrier
	s_waitcnt lgkmcnt(7)
	v_mfma_f32_16x16x32_bf16 v[126:129], v[142:145], v[192:195], v[126:129]
	v_mfma_f32_16x16x32_bf16 v[122:125], v[154:157], v[192:195], v[122:125]
	s_waitcnt lgkmcnt(5)
	v_mfma_f32_16x16x32_bf16 v[110:113], v[142:145], v[204:207], v[110:113]
	v_mfma_f32_16x16x32_bf16 v[106:109], v[154:157], v[204:207], v[106:109]
	s_waitcnt lgkmcnt(3)
	v_mfma_f32_16x16x32_bf16 v[94:97], v[142:145], v[212:215], v[94:97]
	v_mfma_f32_16x16x32_bf16 v[90:93], v[154:157], v[212:215], v[90:93]
	s_waitcnt lgkmcnt(1)
	v_mfma_f32_16x16x32_bf16 v[78:81], v[142:145], v[220:223], v[78:81]
	v_mfma_f32_16x16x32_bf16 v[74:77], v[154:157], v[220:223], v[74:77]
	v_mfma_f32_16x16x32_bf16 v[126:129], v[146:149], v[196:199], v[126:129]
	v_mfma_f32_16x16x32_bf16 v[122:125], v[158:161], v[196:199], v[122:125]
	v_mfma_f32_16x16x32_bf16 v[110:113], v[146:149], v[208:211], v[110:113]
	v_mfma_f32_16x16x32_bf16 v[106:109], v[158:161], v[208:211], v[106:109]
	v_mfma_f32_16x16x32_bf16 v[94:97], v[146:149], v[216:219], v[94:97]
	v_mfma_f32_16x16x32_bf16 v[90:93], v[158:161], v[216:219], v[90:93]
	s_waitcnt lgkmcnt(0)
	v_mfma_f32_16x16x32_bf16 v[78:81], v[146:149], v[224:227], v[78:81]
	v_mfma_f32_16x16x32_bf16 v[74:77], v[158:161], v[224:227], v[74:77]
	v_mfma_f32_16x16x32_bf16 v[118:121], v[168:171], v[192:195], v[118:121]
	v_mfma_f32_16x16x32_bf16 v[114:117], v[184:187], v[192:195], v[114:117]
	v_mfma_f32_16x16x32_bf16 v[102:105], v[168:171], v[204:207], v[102:105]
	v_mfma_f32_16x16x32_bf16 v[98:101], v[184:187], v[204:207], v[98:101]
	v_mfma_f32_16x16x32_bf16 v[86:89], v[168:171], v[212:215], v[86:89]
	v_mfma_f32_16x16x32_bf16 v[82:85], v[184:187], v[212:215], v[82:85]
	v_mfma_f32_16x16x32_bf16 v[70:73], v[168:171], v[220:223], v[70:73]
	v_mfma_f32_16x16x32_bf16 v[66:69], v[184:187], v[220:223], v[66:69]
	v_mfma_f32_16x16x32_bf16 v[118:121], v[172:175], v[196:199], v[118:121]
	v_mfma_f32_16x16x32_bf16 v[114:117], v[188:191], v[196:199], v[114:117]
	v_mfma_f32_16x16x32_bf16 v[102:105], v[172:175], v[208:211], v[102:105]
	v_mfma_f32_16x16x32_bf16 v[98:101], v[188:191], v[208:211], v[98:101]
	v_mfma_f32_16x16x32_bf16 v[86:89], v[172:175], v[216:219], v[86:89]
	v_mfma_f32_16x16x32_bf16 v[82:85], v[188:191], v[216:219], v[82:85]
	v_mfma_f32_16x16x32_bf16 v[70:73], v[172:175], v[224:227], v[70:73]
	v_mfma_f32_16x16x32_bf16 v[66:69], v[188:191], v[224:227], v[66:69]
	s_barrier
; #define PG8_STAGE(bufoff, gbase, X) do { _Pragma("unroll") for (int _i = 0; _i < 2; ++_i) { \
;         const char* gp_ = (const char*)(gbase) + (_i ? rs##X : (size_t)0); const unsigned la_ = (unsigned)(size_t)(lds + (bufoff) + ldsw + _i * 8192); \
;         asm volatile("s_mov_b32 m0, %2\n\ts_nop 0\n\tglobal_load_lds_dwordx4 %0, %1" :: "v"(voff##X), "s"(gp_), "s"(la_) : "memory", "m0"); } } while (0)
; #define PG8_LDA(dst, b, h) do { _Pragma("unroll") for (int m = 0; m < 4; ++m) _Pragma("unroll") for (int k = 0; k < 2; ++k) dst[m][k] = *(const LAS bf16x8*)(lds + PG8_SA(b, h) + aoff + m * 2048 + k * 1024); } while (0)
; #define PG8_WAIT_V(n) asm volatile("s_waitcnt vmcnt(" #n ")" ::: "memory")
; #define PG8_WAIT_L(n) asm volatile("s_waitcnt lgkmcnt(" #n ")" ::: "memory")
; #define PG8_BAR __builtin_amdgcn_s_barrier()
; #define PG8_SCHED __builtin_amdgcn_sched_barrier(0)
; template <class Epi>
; __device__ __forceinline__ void gemm_phase(LAS unsigned char* lds, const Gemm g_in, const StaticOrder& S, const Epi& E) {
;     ...
;             PG8_LDA(At, 1, 1); PG8_STAGE(PG8_SB(1, 0), b3, B); PG8_STAGE(PG8_SB(1, 1), b3 + hsB, B); PG8_STAGE(PG8_SA(1, 0), a3, A);
;             PG8_WAIT_V(8); PG8_WAIT_L(0); PG8_BAR; PG8_MMA(1, 0, At, B0); PG8_MMA(1, 1, At, B1); PG8_BAR; PG8_SCHED;
;         }
	s_add_u32 s64, s30, 0x80
	s_addc_u32 s65, s31, 0
	ds_read_b128 v[192:195], v139 offset:49152
	ds_read_b128 v[196:199], v139 offset:50176
	ds_read_b128 v[204:207], v139 offset:51200
	ds_read_b128 v[208:211], v139 offset:52224
	ds_read_b128 v[212:215], v139 offset:53248
	ds_read_b128 v[216:219], v139 offset:54272
	ds_read_b128 v[220:223], v139 offset:55296
	ds_read_b128 v[224:227], v139 offset:56320
	s_mov_b32 m0, s49
	s_nop 0
	global_load_lds_dwordx4 v134, s[64:65]
	s_add_u32 s64, s30, 0x10080
	s_addc_u32 s65, s31, 0
	s_mov_b32 m0, s50
	s_nop 0
	global_load_lds_dwordx4 v134, s[64:65]
	s_add_u32 s64, s30, 0x20080
	s_addc_u32 s65, s31, 0
	s_mov_b32 m0, s53
	s_nop 0
	global_load_lds_dwordx4 v134, s[64:65]
	s_add_u32 s30, s30, 0x30080
	s_addc_u32 s31, s31, 0
	s_mov_b32 m0, s54
	s_nop 0
	global_load_lds_dwordx4 v134, s[30:31]
	s_add_u32 s26, s26, 0x20080
	s_mov_b32 m0, s51
	s_nop 0
	global_load_lds_dwordx4 v1, s[28:29]
	s_addc_u32 s27, s27, 0
	s_mov_b32 m0, s52
	s_nop 0
	global_load_lds_dwordx4 v1, s[26:27]
	s_waitcnt vmcnt(8)
	s_waitcnt lgkmcnt(0)
	s_barrier
	s_waitcnt lgkmcnt(7)
	v_mfma_f32_16x16x32_bf16 v[62:65], v[142:145], v[192:195], v[62:65]
	v_mfma_f32_16x16x32_bf16 v[58:61], v[154:157], v[192:195], v[58:61]
	s_waitcnt lgkmcnt(5)
	v_mfma_f32_16x16x32_bf16 v[46:49], v[142:145], v[204:207], v[46:49]
	v_mfma_f32_16x16x32_bf16 v[42:45], v[154:157], v[204:207], v[42:45]
	s_waitcnt lgkmcnt(3)
	v_mfma_f32_16x16x32_bf16 v[30:33], v[142:145], v[212:215], v[30:33]
	v_mfma_f32_16x16x32_bf16 v[26:29], v[154:157], v[212:215], v[26:29]
	s_waitcnt lgkmcnt(1)
	v_mfma_f32_16x16x32_bf16 v[14:17], v[142:145], v[220:223], v[14:17]
	v_mfma_f32_16x16x32_bf16 v[10:13], v[154:157], v[220:223], v[10:13]
	v_mfma_f32_16x16x32_bf16 v[62:65], v[146:149], v[196:199], v[62:65]
	v_mfma_f32_16x16x32_bf16 v[58:61], v[158:161], v[196:199], v[58:61]
	v_mfma_f32_16x16x32_bf16 v[46:49], v[146:149], v[208:211], v[46:49]
	v_mfma_f32_16x16x32_bf16 v[42:45], v[158:161], v[208:211], v[42:45]
	v_mfma_f32_16x16x32_bf16 v[30:33], v[146:149], v[216:219], v[30:33]
	v_mfma_f32_16x16x32_bf16 v[26:29], v[158:161], v[216:219], v[26:29]
	s_waitcnt lgkmcnt(0)
	v_mfma_f32_16x16x32_bf16 v[14:17], v[146:149], v[224:227], v[14:17]
	v_mfma_f32_16x16x32_bf16 v[10:13], v[158:161], v[224:227], v[10:13]
	v_mfma_f32_16x16x32_bf16 v[54:57], v[168:171], v[192:195], v[54:57]
	v_mfma_f32_16x16x32_bf16 v[50:53], v[184:187], v[192:195], v[50:53]
	v_mfma_f32_16x16x32_bf16 v[38:41], v[168:171], v[204:207], v[38:41]
	v_mfma_f32_16x16x32_bf16 v[34:37], v[184:187], v[204:207], v[34:37]
	v_mfma_f32_16x16x32_bf16 v[22:25], v[168:171], v[212:215], v[22:25]
	v_mfma_f32_16x16x32_bf16 v[18:21], v[184:187], v[212:215], v[18:21]
	v_mfma_f32_16x16x32_bf16 v[6:9], v[168:171], v[220:223], v[6:9]
	v_mfma_f32_16x16x32_bf16 v[2:5], v[184:187], v[220:223], v[2:5]
	v_mfma_f32_16x16x32_bf16 v[54:57], v[172:175], v[196:199], v[54:57]
	v_mfma_f32_16x16x32_bf16 v[50:53], v[188:191], v[196:199], v[50:53]
	v_mfma_f32_16x16x32_bf16 v[38:41], v[172:175], v[208:211], v[38:41]
	v_mfma_f32_16x16x32_bf16 v[34:37], v[188:191], v[208:211], v[34:37]
	v_mfma_f32_16x16x32_bf16 v[22:25], v[172:175], v[216:219], v[22:25]
	v_mfma_f32_16x16x32_bf16 v[18:21], v[188:191], v[216:219], v[18:21]
	v_mfma_f32_16x16x32_bf16 v[6:9], v[172:175], v[224:227], v[6:9]
	v_mfma_f32_16x16x32_bf16 v[2:5], v[188:191], v[224:227], v[2:5]
	s_barrier
	s_add_u32 s61, s61, 0x100
	s_addc_u32 s62, s62, 0
	s_add_u32 s24, s24, 0x100
	s_addc_u32 s25, s25, 0
	s_cmp_ge_i32 s63, s38
	s_mov_b32 s26, s63
	s_cbranch_scc0 .LBB0_787
	s_and_b64 vcc, exec, s[10:11]
	s_cbranch_vccz .LBB0_790

; #define PG8_STAGE(bufoff, gbase, X) do { _Pragma("unroll") for (int _i = 0; _i < 2; ++_i) { \
;         const char* gp_ = (const char*)(gbase) + (_i ? rs##X : (size_t)0); const unsigned la_ = (unsigned)(size_t)(lds + (bufoff) + ldsw + _i * 8192); \
;         asm volatile("s_mov_b32 m0, %2\n\ts_nop 0\n\tglobal_load_lds_dwordx4 %0, %1" :: "v"(voff##X), "s"(gp_), "s"(la_) : "memory", "m0"); } } while (0)
; #define PG8_LDA(dst, b, h) do { _Pragma("unroll") for (int m = 0; m < 4; ++m) _Pragma("unroll") for (int k = 0; k < 2; ++k) dst[m][k] = *(const LAS bf16x8*)(lds + PG8_SA(b, h) + aoff + m * 2048 + k * 1024); } while (0)
; #define PG8_LDB(dst, b, h) do { _Pragma("unroll") for (int n = 0; n < 2; ++n) _Pragma("unroll") for (int k = 0; k < 2; ++k) dst[n][k] = *(const LAS bf16x8*)(lds + PG8_SB(b, h) + boff + n * 2048 + k * 1024); } while (0)
; #define PG8_WAIT_V(n) asm volatile("s_waitcnt vmcnt(" #n ")" ::: "memory")
; #define PG8_WAIT_L(n) asm volatile("s_waitcnt lgkmcnt(" #n ")" ::: "memory")
; #define PG8_BAR __builtin_amdgcn_s_barrier()
; #define PG8_SCHED __builtin_amdgcn_sched_barrier(0)
; template <class Epi>
; __device__ __forceinline__ void gemm_phase(LAS unsigned char* lds, const Gemm g_in, const StaticOrder& S, const Epi& E) {
;     ...
;         const bool has_next = S.next(ui + 1, nxt);
;         const char* nA = has_next ? (const char*)g.A + (size_t)nxt.pm * tsA : cA; const char* nB = has_next ? (const char*)g.Bt + (size_t)nxt.pn * tsB : cB;
;         for (int t = 0; t < nt; t += 2) {
;             const bool last = (t == nt - 2);
;             const char* a1 = cA + (size_t)(t + 1) * kstep;
;             const char* a2 = last ? nA : cA + (size_t)(t + 2) * kstep; const char* b2 = last ? nB : cB + (size_t)(t + 2) * kstep;
;             const char* a3 = a2 + kstep; const char* b3 = b2 + kstep;
;             PG8_LDB(B0, 0, 0); PG8_LDB(B1, 0, 1); PG8_SCHED; PG8_LDA(At, 0, 0); PG8_STAGE(PG8_SA(1, 1), a1 + hsA, A);
;             PG8_WAIT_V(8); PG8_WAIT_L(0); PG8_BAR; PG8_MMA(0, 0, At, B0); PG8_MMA(0, 1, At, B1); PG8_BAR; PG8_SCHED;
;             PG8_LDA(At, 0, 1); PG8_STAGE(PG8_SB(0, 0), b2, B); PG8_STAGE(PG8_SB(0, 1), b2 + hsB, B); PG8_STAGE(PG8_SA(0, 0), a2, A);
;             PG8_WAIT_V(8); PG8_WAIT_L(0); PG8_BAR; PG8_MMA(1, 0, At, B0); PG8_MMA(1, 1, At, B1); PG8_BAR; PG8_SCHED;
.LBB0_1254:
	ds_read_b128 v[130:133], v169
	ds_read_b128 v[134:137], v169 offset:1024
	ds_read_b128 v[138:141], v169 offset:2048
	ds_read_b128 v[142:145], v169 offset:3072
	ds_read_b128 v[146:149], v170
	ds_read_b128 v[154:157], v170 offset:1024
	ds_read_b128 v[158:161], v170 offset:2048
	ds_read_b128 v[162:165], v170 offset:3072
	s_add_i32 s62, s28, 2
	s_add_u32 s30, s26, 0xfff40080
	s_addc_u32 s29, s27, -1
	s_cmp_eq_u32 s55, s28
	s_cselect_b32 s28, s21, s30
	s_cselect_b32 s29, s19, s29
	s_cselect_b32 s34, s59, s60
	s_cselect_b32 s35, s58, s61
	s_add_u32 s30, s28, 0x80
	s_addc_u32 s31, s29, 0
	ds_read_b128 v[174:177], v171
	ds_read_b128 v[184:187], v171 offset:1024
	ds_read_b128 v[188:191], v171 offset:2048
	ds_read_b128 v[192:195], v171 offset:3072
	ds_read_b128 v[196:199], v171 offset:4096
	ds_read_b128 v[204:207], v171 offset:5120
	ds_read_b128 v[208:211], v171 offset:6144
	ds_read_b128 v[212:215], v171 offset:7168
	s_add_u32 s64, s26, 0xfffc0000
	s_addc_u32 s65, s27, -1
	s_mov_b32 m0, s56
	s_nop 0
	global_load_lds_dwordx4 v1, s[64:65]
	s_nop 0
	s_mov_b32 m0, s57
	s_nop 0
	global_load_lds_dwordx4 v1, s[26:27]
	s_waitcnt vmcnt(8)
	s_waitcnt lgkmcnt(0)
	s_barrier
	s_waitcnt lgkmcnt(7)
	v_mfma_f32_16x16x32_bf16 v[126:129], v[130:133], v[174:177], v[126:129]
	v_mfma_f32_16x16x32_bf16 v[122:125], v[138:141], v[174:177], v[122:125]
	s_waitcnt lgkmcnt(5)
	v_mfma_f32_16x16x32_bf16 v[110:113], v[130:133], v[188:191], v[110:113]
	v_mfma_f32_16x16x32_bf16 v[106:109], v[138:141], v[188:191], v[106:109]
	s_waitcnt lgkmcnt(3)
	v_mfma_f32_16x16x32_bf16 v[94:97], v[130:133], v[196:199], v[94:97]
	v_mfma_f32_16x16x32_bf16 v[90:93], v[138:141], v[196:199], v[90:93]
	s_waitcnt lgkmcnt(1)
	v_mfma_f32_16x16x32_bf16 v[78:81], v[130:133], v[208:211], v[78:81]
	v_mfma_f32_16x16x32_bf16 v[74:77], v[138:141], v[208:211], v[74:77]
	v_mfma_f32_16x16x32_bf16 v[126:129], v[134:137], v[184:187], v[126:129]
	v_mfma_f32_16x16x32_bf16 v[122:125], v[142:145], v[184:187], v[122:125]
	v_mfma_f32_16x16x32_bf16 v[110:113], v[134:137], v[192:195], v[110:113]
	v_mfma_f32_16x16x32_bf16 v[106:109], v[142:145], v[192:195], v[106:109]
	v_mfma_f32_16x16x32_bf16 v[94:97], v[134:137], v[204:207], v[94:97]
	v_mfma_f32_16x16x32_bf16 v[90:93], v[142:145], v[204:207], v[90:93]
	s_waitcnt lgkmcnt(0)
	v_mfma_f32_16x16x32_bf16 v[78:81], v[134:137], v[212:215], v[78:81]
	v_mfma_f32_16x16x32_bf16 v[74:77], v[142:145], v[212:215], v[74:77]
	v_mfma_f32_16x16x32_bf16 v[118:121], v[146:149], v[174:177], v[118:121]
	v_mfma_f32_16x16x32_bf16 v[114:117], v[158:161], v[174:177], v[114:117]
	v_mfma_f32_16x16x32_bf16 v[102:105], v[146:149], v[188:191], v[102:105]
	v_mfma_f32_16x16x32_bf16 v[98:101], v[158:161], v[188:191], v[98:101]
	v_mfma_f32_16x16x32_bf16 v[86:89], v[146:149], v[196:199], v[86:89]
	v_mfma_f32_16x16x32_bf16 v[82:85], v[158:161], v[196:199], v[82:85]
	v_mfma_f32_16x16x32_bf16 v[70:73], v[146:149], v[208:211], v[70:73]
	v_mfma_f32_16x16x32_bf16 v[66:69], v[158:161], v[208:211], v[66:69]
	v_mfma_f32_16x16x32_bf16 v[118:121], v[154:157], v[184:187], v[118:121]
	v_mfma_f32_16x16x32_bf16 v[114:117], v[162:165], v[184:187], v[114:117]
	v_mfma_f32_16x16x32_bf16 v[102:105], v[154:157], v[192:195], v[102:105]
	v_mfma_f32_16x16x32_bf16 v[98:101], v[162:165], v[192:195], v[98:101]
	v_mfma_f32_16x16x32_bf16 v[86:89], v[154:157], v[204:207], v[86:89]
	v_mfma_f32_16x16x32_bf16 v[82:85], v[162:165], v[204:207], v[82:85]
	v_mfma_f32_16x16x32_bf16 v[70:73], v[154:157], v[212:215], v[70:73]
	v_mfma_f32_16x16x32_bf16 v[66:69], v[162:165], v[212:215], v[66:69]
	s_barrier
	s_add_u32 s64, s34, 0x40000
	ds_read_b128 v[174:177], v171 offset:16384
	ds_read_b128 v[184:187], v171 offset:17408
	ds_read_b128 v[188:191], v171 offset:18432
	ds_read_b128 v[192:195], v171 offset:19456
	ds_read_b128 v[196:199], v171 offset:20480
	ds_read_b128 v[204:207], v171 offset:21504
	ds_read_b128 v[208:211], v171 offset:22528
	ds_read_b128 v[212:215], v171 offset:23552
	s_mov_b32 m0, s42
	s_nop 0
	global_load_lds_dwordx4 v166, s[34:35]
	s_addc_u32 s65, s35, 0
	s_mov_b32 m0, s43
	s_nop 0
	global_load_lds_dwordx4 v166, s[64:65]
	s_add_u32 s64, s34, 0x80000
	s_addc_u32 s65, s35, 0
	s_mov_b32 m0, s44
	s_nop 0
	global_load_lds_dwordx4 v166, s[64:65]
	s_add_u32 s64, s34, 0xc0000
	s_addc_u32 s65, s35, 0
	s_mov_b32 m0, s45
	s_nop 0
	global_load_lds_dwordx4 v166, s[64:65]
	s_add_u32 s64, s28, 0x40000
	s_mov_b32 m0, s41
	s_nop 0
	global_load_lds_dwordx4 v1, s[28:29]
	s_addc_u32 s65, s29, 0
	s_mov_b32 m0, s46
	s_nop 0
	global_load_lds_dwordx4 v1, s[64:65]
	s_waitcnt vmcnt(8)
	s_waitcnt lgkmcnt(0)
	s_barrier
; #define PG8_STAGE(bufoff, gbase, X) do { _Pragma("unroll") for (int _i = 0; _i < 2; ++_i) { \
;         const char* gp_ = (const char*)(gbase) + (_i ? rs##X : (size_t)0); const unsigned la_ = (unsigned)(size_t)(lds + (bufoff) + ldsw + _i * 8192); \
;         asm volatile("s_mov_b32 m0, %2\n\ts_nop 0\n\tglobal_load_lds_dwordx4 %0, %1" :: "v"(voff##X), "s"(gp_), "s"(la_) : "memory", "m0"); } } while (0)
; #define PG8_LDA(dst, b, h) do { _Pragma("unroll") for (int m = 0; m < 4; ++m) _Pragma("unroll") for (int k = 0; k < 2; ++k) dst[m][k] = *(const LAS bf16x8*)(lds + PG8_SA(b, h) + aoff + m * 2048 + k * 1024); } while (0)
; #define PG8_LDB(dst, b, h) do { _Pragma("unroll") for (int n = 0; n < 2; ++n) _Pragma("unroll") for (int k = 0; k < 2; ++k) dst[n][k] = *(const LAS bf16x8*)(lds + PG8_SB(b, h) + boff + n * 2048 + k * 1024); } while (0)
; #define PG8_WAIT_V(n) asm volatile("s_waitcnt vmcnt(" #n ")" ::: "memory")
; #define PG8_WAIT_L(n) asm volatile("s_waitcnt lgkmcnt(" #n ")" ::: "memory")
; #define PG8_BAR __builtin_amdgcn_s_barrier()
; #define PG8_SCHED __builtin_amdgcn_sched_barrier(0)
; template <class Epi>
; __device__ __forceinline__ void gemm_phase(LAS unsigned char* lds, const Gemm g_in, const StaticOrder& S, const Epi& E) {
;     ...
;             PG8_WAIT_V(8); PG8_WAIT_L(0); PG8_BAR; PG8_MMA(1, 0, At, B0); PG8_MMA(1, 1, At, B1); PG8_BAR; PG8_SCHED;
;             PG8_LDB(B0, 1, 0); PG8_LDB(B1, 1, 1); PG8_SCHED; PG8_LDA(At, 1, 0); PG8_STAGE(PG8_SA(0, 1), a2 + hsA, A);
;             PG8_WAIT_V(8); PG8_WAIT_L(0); PG8_BAR; PG8_MMA(0, 0, At, B0); PG8_MMA(0, 1, At, B1); PG8_BAR; PG8_SCHED;
	s_waitcnt lgkmcnt(7)
	v_mfma_f32_16x16x32_bf16 v[62:65], v[130:133], v[174:177], v[62:65]
	v_mfma_f32_16x16x32_bf16 v[58:61], v[138:141], v[174:177], v[58:61]
	s_waitcnt lgkmcnt(5)
	v_mfma_f32_16x16x32_bf16 v[46:49], v[130:133], v[188:191], v[46:49]
	v_mfma_f32_16x16x32_bf16 v[42:45], v[138:141], v[188:191], v[42:45]
	s_waitcnt lgkmcnt(3)
	v_mfma_f32_16x16x32_bf16 v[30:33], v[130:133], v[196:199], v[30:33]
	v_mfma_f32_16x16x32_bf16 v[26:29], v[138:141], v[196:199], v[26:29]
	s_waitcnt lgkmcnt(1)
	v_mfma_f32_16x16x32_bf16 v[14:17], v[130:133], v[208:211], v[14:17]
	v_mfma_f32_16x16x32_bf16 v[10:13], v[138:141], v[208:211], v[10:13]
	v_mfma_f32_16x16x32_bf16 v[62:65], v[134:137], v[184:187], v[62:65]
	v_mfma_f32_16x16x32_bf16 v[58:61], v[142:145], v[184:187], v[58:61]
	v_mfma_f32_16x16x32_bf16 v[46:49], v[134:137], v[192:195], v[46:49]
	v_mfma_f32_16x16x32_bf16 v[42:45], v[142:145], v[192:195], v[42:45]
	v_mfma_f32_16x16x32_bf16 v[30:33], v[134:137], v[204:207], v[30:33]
	v_mfma_f32_16x16x32_bf16 v[26:29], v[142:145], v[204:207], v[26:29]
	s_waitcnt lgkmcnt(0)
	v_mfma_f32_16x16x32_bf16 v[14:17], v[134:137], v[212:215], v[14:17]
	v_mfma_f32_16x16x32_bf16 v[10:13], v[142:145], v[212:215], v[10:13]
	v_mfma_f32_16x16x32_bf16 v[54:57], v[146:149], v[174:177], v[54:57]
	v_mfma_f32_16x16x32_bf16 v[50:53], v[158:161], v[174:177], v[50:53]
	v_mfma_f32_16x16x32_bf16 v[38:41], v[146:149], v[188:191], v[38:41]
	v_mfma_f32_16x16x32_bf16 v[34:37], v[158:161], v[188:191], v[34:37]
	v_mfma_f32_16x16x32_bf16 v[22:25], v[146:149], v[196:199], v[22:25]
	v_mfma_f32_16x16x32_bf16 v[18:21], v[158:161], v[196:199], v[18:21]
	v_mfma_f32_16x16x32_bf16 v[6:9], v[146:149], v[208:211], v[6:9]
	v_mfma_f32_16x16x32_bf16 v[2:5], v[158:161], v[208:211], v[2:5]
	v_mfma_f32_16x16x32_bf16 v[54:57], v[154:157], v[184:187], v[54:57]
	v_mfma_f32_16x16x32_bf16 v[50:53], v[162:165], v[184:187], v[50:53]
	v_mfma_f32_16x16x32_bf16 v[38:41], v[154:157], v[192:195], v[38:41]
	v_mfma_f32_16x16x32_bf16 v[34:37], v[162:165], v[192:195], v[34:37]
	v_mfma_f32_16x16x32_bf16 v[22:25], v[154:157], v[204:207], v[22:25]
	v_mfma_f32_16x16x32_bf16 v[18:21], v[162:165], v[204:207], v[18:21]
	v_mfma_f32_16x16x32_bf16 v[6:9], v[154:157], v[212:215], v[6:9]
	v_mfma_f32_16x16x32_bf16 v[2:5], v[162:165], v[212:215], v[2:5]
	s_barrier
	ds_read_b128 v[130:133], v172
	ds_read_b128 v[134:137], v172 offset:1024
	ds_read_b128 v[138:141], v172 offset:2048
	ds_read_b128 v[142:145], v172 offset:3072
	ds_read_b128 v[146:149], v173
	ds_read_b128 v[154:157], v173 offset:1024
	ds_read_b128 v[158:161], v173 offset:2048
	ds_read_b128 v[162:165], v173 offset:3072
	ds_read_b128 v[174:177], v171 offset:32768
	ds_read_b128 v[184:187], v171 offset:33792
	ds_read_b128 v[188:191], v171 offset:34816
	ds_read_b128 v[192:195], v171 offset:35840
	ds_read_b128 v[196:199], v171 offset:36864
	ds_read_b128 v[204:207], v171 offset:37888
	ds_read_b128 v[208:211], v171 offset:38912
	ds_read_b128 v[212:215], v171 offset:39936
	s_add_u32 s64, s28, 0x80000
	s_addc_u32 s65, s29, 0
	s_mov_b32 m0, s47
	s_nop 0
	global_load_lds_dwordx4 v1, s[64:65]
	s_add_u32 s64, s28, 0xc0000
	s_addc_u32 s65, s29, 0
	s_mov_b32 m0, s48
	s_nop 0
	global_load_lds_dwordx4 v1, s[64:65]
	s_waitcnt vmcnt(8)
	s_waitcnt lgkmcnt(0)
	s_barrier
	s_waitcnt lgkmcnt(7)
	v_mfma_f32_16x16x32_bf16 v[126:129], v[130:133], v[174:177], v[126:129]
	v_mfma_f32_16x16x32_bf16 v[122:125], v[138:141], v[174:177], v[122:125]
	s_waitcnt lgkmcnt(5)
	v_mfma_f32_16x16x32_bf16 v[110:113], v[130:133], v[188:191], v[110:113]
	v_mfma_f32_16x16x32_bf16 v[106:109], v[138:141], v[188:191], v[106:109]
	s_waitcnt lgkmcnt(3)
	v_mfma_f32_16x16x32_bf16 v[94:97], v[130:133], v[196:199], v[94:97]
	v_mfma_f32_16x16x32_bf16 v[90:93], v[138:141], v[196:199], v[90:93]
	s_waitcnt lgkmcnt(1)
	v_mfma_f32_16x16x32_bf16 v[78:81], v[130:133], v[208:211], v[78:81]
	v_mfma_f32_16x16x32_bf16 v[74:77], v[138:141], v[208:211], v[74:77]
	v_mfma_f32_16x16x32_bf16 v[126:129], v[134:137], v[184:187], v[126:129]
	v_mfma_f32_16x16x32_bf16 v[122:125], v[142:145], v[184:187], v[122:125]
	v_mfma_f32_16x16x32_bf16 v[110:113], v[134:137], v[192:195], v[110:113]
	v_mfma_f32_16x16x32_bf16 v[106:109], v[142:145], v[192:195], v[106:109]
	v_mfma_f32_16x16x32_bf16 v[94:97], v[134:137], v[204:207], v[94:97]
	v_mfma_f32_16x16x32_bf16 v[90:93], v[142:145], v[204:207], v[90:93]
	s_waitcnt lgkmcnt(0)
	v_mfma_f32_16x16x32_bf16 v[78:81], v[134:137], v[212:215], v[78:81]
	v_mfma_f32_16x16x32_bf16 v[74:77], v[142:145], v[212:215], v[74:77]
	v_mfma_f32_16x16x32_bf16 v[118:121], v[146:149], v[174:177], v[118:121]
	v_mfma_f32_16x16x32_bf16 v[114:117], v[158:161], v[174:177], v[114:117]
	v_mfma_f32_16x16x32_bf16 v[102:105], v[146:149], v[188:191], v[102:105]
	v_mfma_f32_16x16x32_bf16 v[98:101], v[158:161], v[188:191], v[98:101]
	v_mfma_f32_16x16x32_bf16 v[86:89], v[146:149], v[196:199], v[86:89]
	v_mfma_f32_16x16x32_bf16 v[82:85], v[158:161], v[196:199], v[82:85]
	v_mfma_f32_16x16x32_bf16 v[70:73], v[146:149], v[208:211], v[70:73]
	v_mfma_f32_16x16x32_bf16 v[66:69], v[158:161], v[208:211], v[66:69]
	v_mfma_f32_16x16x32_bf16 v[118:121], v[154:157], v[184:187], v[118:121]
	v_mfma_f32_16x16x32_bf16 v[114:117], v[162:165], v[184:187], v[114:117]
	v_mfma_f32_16x16x32_bf16 v[102:105], v[154:157], v[192:195], v[102:105]
	v_mfma_f32_16x16x32_bf16 v[98:101], v[162:165], v[192:195], v[98:101]
	v_mfma_f32_16x16x32_bf16 v[86:89], v[154:157], v[204:207], v[86:89]
	v_mfma_f32_16x16x32_bf16 v[82:85], v[162:165], v[204:207], v[82:85]
	v_mfma_f32_16x16x32_bf16 v[70:73], v[154:157], v[212:215], v[70:73]
	v_mfma_f32_16x16x32_bf16 v[66:69], v[162:165], v[212:215], v[66:69]
	s_barrier
; #define PG8_STAGE(bufoff, gbase, X) do { _Pragma("unroll") for (int _i = 0; _i < 2; ++_i) { \
;         const char* gp_ = (const char*)(gbase) + (_i ? rs##X : (size_t)0); const unsigned la_ = (unsigned)(size_t)(lds + (bufoff) + ldsw + _i * 8192); \
;         asm volatile("s_mov_b32 m0, %2\n\ts_nop 0\n\tglobal_load_lds_dwordx4 %0, %1" :: "v"(voff##X), "s"(gp_), "s"(la_) : "memory", "m0"); } } while (0)
; #define PG8_LDA(dst, b, h) do { _Pragma("unroll") for (int m = 0; m < 4; ++m) _Pragma("unroll") for (int k = 0; k < 2; ++k) dst[m][k] = *(const LAS bf16x8*)(lds + PG8_SA(b, h) + aoff + m * 2048 + k * 1024); } while (0)
; #define PG8_WAIT_V(n) asm volatile("s_waitcnt vmcnt(" #n ")" ::: "memory")
; #define PG8_WAIT_L(n) asm volatile("s_waitcnt lgkmcnt(" #n ")" ::: "memory")
; #define PG8_BAR __builtin_amdgcn_s_barrier()
; #define PG8_SCHED __builtin_amdgcn_sched_barrier(0)
; template <class Epi>
; __device__ __forceinline__ void gemm_phase(LAS unsigned char* lds, const Gemm g_in, const StaticOrder& S, const Epi& E) {
;     ...
;             PG8_LDA(At, 1, 1); PG8_STAGE(PG8_SB(1, 0), b3, B); PG8_STAGE(PG8_SB(1, 1), b3 + hsB, B); PG8_STAGE(PG8_SA(1, 0), a3, A);
;             PG8_WAIT_V(8); PG8_WAIT_L(0); PG8_BAR; PG8_MMA(1, 0, At, B0); PG8_MMA(1, 1, At, B1); PG8_BAR; PG8_SCHED;
;         }
	s_add_u32 s64, s34, 0x80
	s_addc_u32 s65, s35, 0
	ds_read_b128 v[174:177], v171 offset:49152
	ds_read_b128 v[184:187], v171 offset:50176
	ds_read_b128 v[188:191], v171 offset:51200
	ds_read_b128 v[192:195], v171 offset:52224
	ds_read_b128 v[196:199], v171 offset:53248
	ds_read_b128 v[204:207], v171 offset:54272
	ds_read_b128 v[208:211], v171 offset:55296
	ds_read_b128 v[212:215], v171 offset:56320
	s_mov_b32 m0, s49
	s_nop 0
	global_load_lds_dwordx4 v166, s[64:65]
	s_add_u32 s64, s34, 0x40080
	s_addc_u32 s65, s35, 0
	s_mov_b32 m0, s50
	s_nop 0
	global_load_lds_dwordx4 v166, s[64:65]
	s_add_u32 s64, s34, 0x80080
	s_addc_u32 s65, s35, 0
	s_mov_b32 m0, s53
	s_nop 0
	global_load_lds_dwordx4 v166, s[64:65]
	s_add_u32 s34, s34, 0xc0080
	s_addc_u32 s35, s35, 0
	s_mov_b32 m0, s54
	s_nop 0
	global_load_lds_dwordx4 v166, s[34:35]
	s_add_u32 s28, s28, 0x40080
	s_mov_b32 m0, s51
	s_nop 0
	global_load_lds_dwordx4 v1, s[30:31]
	s_addc_u32 s29, s29, 0
	s_mov_b32 m0, s52
	s_nop 0
	global_load_lds_dwordx4 v1, s[28:29]
	s_waitcnt vmcnt(8)
	s_waitcnt lgkmcnt(0)
	s_barrier
	s_waitcnt lgkmcnt(7)
	v_mfma_f32_16x16x32_bf16 v[62:65], v[130:133], v[174:177], v[62:65]
	v_mfma_f32_16x16x32_bf16 v[58:61], v[138:141], v[174:177], v[58:61]
	s_waitcnt lgkmcnt(5)
	v_mfma_f32_16x16x32_bf16 v[46:49], v[130:133], v[188:191], v[46:49]
	v_mfma_f32_16x16x32_bf16 v[42:45], v[138:141], v[188:191], v[42:45]
	s_waitcnt lgkmcnt(3)
	v_mfma_f32_16x16x32_bf16 v[30:33], v[130:133], v[196:199], v[30:33]
	v_mfma_f32_16x16x32_bf16 v[26:29], v[138:141], v[196:199], v[26:29]
	s_waitcnt lgkmcnt(1)
	v_mfma_f32_16x16x32_bf16 v[14:17], v[130:133], v[208:211], v[14:17]
	v_mfma_f32_16x16x32_bf16 v[10:13], v[138:141], v[208:211], v[10:13]
	v_mfma_f32_16x16x32_bf16 v[62:65], v[134:137], v[184:187], v[62:65]
	v_mfma_f32_16x16x32_bf16 v[58:61], v[142:145], v[184:187], v[58:61]
	v_mfma_f32_16x16x32_bf16 v[46:49], v[134:137], v[192:195], v[46:49]
	v_mfma_f32_16x16x32_bf16 v[42:45], v[142:145], v[192:195], v[42:45]
	v_mfma_f32_16x16x32_bf16 v[30:33], v[134:137], v[204:207], v[30:33]
	v_mfma_f32_16x16x32_bf16 v[26:29], v[142:145], v[204:207], v[26:29]
	s_waitcnt lgkmcnt(0)
	v_mfma_f32_16x16x32_bf16 v[14:17], v[134:137], v[212:215], v[14:17]
	v_mfma_f32_16x16x32_bf16 v[10:13], v[142:145], v[212:215], v[10:13]
	v_mfma_f32_16x16x32_bf16 v[54:57], v[146:149], v[174:177], v[54:57]
	v_mfma_f32_16x16x32_bf16 v[50:53], v[158:161], v[174:177], v[50:53]
	v_mfma_f32_16x16x32_bf16 v[38:41], v[146:149], v[188:191], v[38:41]
	v_mfma_f32_16x16x32_bf16 v[34:37], v[158:161], v[188:191], v[34:37]
	v_mfma_f32_16x16x32_bf16 v[22:25], v[146:149], v[196:199], v[22:25]
	v_mfma_f32_16x16x32_bf16 v[18:21], v[158:161], v[196:199], v[18:21]
	v_mfma_f32_16x16x32_bf16 v[6:9], v[146:149], v[208:211], v[6:9]
	v_mfma_f32_16x16x32_bf16 v[2:5], v[158:161], v[208:211], v[2:5]
	v_mfma_f32_16x16x32_bf16 v[54:57], v[154:157], v[184:187], v[54:57]
	v_mfma_f32_16x16x32_bf16 v[50:53], v[162:165], v[184:187], v[50:53]
	v_mfma_f32_16x16x32_bf16 v[38:41], v[154:157], v[192:195], v[38:41]
	v_mfma_f32_16x16x32_bf16 v[34:37], v[162:165], v[192:195], v[34:37]
	v_mfma_f32_16x16x32_bf16 v[22:25], v[154:157], v[204:207], v[22:25]
	v_mfma_f32_16x16x32_bf16 v[18:21], v[162:165], v[204:207], v[18:21]
	v_mfma_f32_16x16x32_bf16 v[6:9], v[154:157], v[212:215], v[6:9]
	v_mfma_f32_16x16x32_bf16 v[2:5], v[162:165], v[212:215], v[2:5]
	s_barrier
	s_add_u32 s60, s60, 0x100
	s_addc_u32 s61, s61, 0
	s_add_u32 s26, s26, 0x100
	s_addc_u32 s27, s27, 0
	s_cmp_ge_i32 s62, s38
	s_mov_b32 s28, s62
	s_cbranch_scc0 .LBB0_1254
	s_and_b64 vcc, exec, s[16:17]
	s_cbranch_vccz .LBB0_1257

; #define PG8_STAGE(bufoff, gbase, X) do { _Pragma("unroll") for (int _i = 0; _i < 2; ++_i) { \
;         const char* gp_ = (const char*)(gbase) + (_i ? rs##X : (size_t)0); const unsigned la_ = (unsigned)(size_t)(lds + (bufoff) + ldsw + _i * 8192); \
;         asm volatile("s_mov_b32 m0, %2\n\ts_nop 0\n\tglobal_load_lds_dwordx4 %0, %1" :: "v"(voff##X), "s"(gp_), "s"(la_) : "memory", "m0"); } } while (0)
; #define PG8_LDA(dst, b, h) do { _Pragma("unroll") for (int m = 0; m < 4; ++m) _Pragma("unroll") for (int k = 0; k < 2; ++k) dst[m][k] = *(const LAS bf16x8*)(lds + PG8_SA(b, h) + aoff + m * 2048 + k * 1024); } while (0)
; #define PG8_LDB(dst, b, h) do { _Pragma("unroll") for (int n = 0; n < 2; ++n) _Pragma("unroll") for (int k = 0; k < 2; ++k) dst[n][k] = *(const LAS bf16x8*)(lds + PG8_SB(b, h) + boff + n * 2048 + k * 1024); } while (0)
; #define PG8_WAIT_V(n) asm volatile("s_waitcnt vmcnt(" #n ")" ::: "memory")
; #define PG8_WAIT_L(n) asm volatile("s_waitcnt lgkmcnt(" #n ")" ::: "memory")
; #define PG8_BAR __builtin_amdgcn_s_barrier()
; #define PG8_SCHED __builtin_amdgcn_sched_barrier(0)
; template <class Epi>
; __device__ __forceinline__ void gemm_phase(LAS unsigned char* lds, const Gemm g_in, const StaticOrder& S, const Epi& E) {
;     ...
;         const bool has_next = S.next(ui + 1, nxt);
;         const char* nA = has_next ? (const char*)g.A + (size_t)nxt.pm * tsA : cA; const char* nB = has_next ? (const char*)g.Bt + (size_t)nxt.pn * tsB : cB;
;         for (int t = 0; t < nt; t += 2) {
;             const bool last = (t == nt - 2);
;             const char* a1 = cA + (size_t)(t + 1) * kstep;
;             const char* a2 = last ? nA : cA + (size_t)(t + 2) * kstep; const char* b2 = last ? nB : cB + (size_t)(t + 2) * kstep;
;             const char* a3 = a2 + kstep; const char* b3 = b2 + kstep;
;             PG8_LDB(B0, 0, 0); PG8_LDB(B1, 0, 1); PG8_SCHED; PG8_LDA(At, 0, 0); PG8_STAGE(PG8_SA(1, 1), a1 + hsA, A);
;             PG8_WAIT_V(8); PG8_WAIT_L(0); PG8_BAR; PG8_MMA(0, 0, At, B0); PG8_MMA(0, 1, At, B1); PG8_BAR; PG8_SCHED;
;             PG8_LDA(At, 0, 1); PG8_STAGE(PG8_SB(0, 0), b2, B); PG8_STAGE(PG8_SB(0, 1), b2 + hsB, B); PG8_STAGE(PG8_SA(0, 0), a2, A);
;             PG8_WAIT_V(8); PG8_WAIT_L(0); PG8_BAR; PG8_MMA(1, 0, At, B0); PG8_MMA(1, 1, At, B1); PG8_BAR; PG8_SCHED;
.LBB0_1285:
	ds_read_b128 v[130:133], v205
	ds_read_b128 v[134:137], v205 offset:1024
	ds_read_b128 v[138:141], v205 offset:2048
	ds_read_b128 v[142:145], v205 offset:3072
	ds_read_b128 v[146:149], v206
	ds_read_b128 v[150:153], v206 offset:1024
	ds_read_b128 v[154:157], v206 offset:2048
	ds_read_b128 v[158:161], v206 offset:3072
	s_add_i32 s66, s34, 2
	s_add_u32 s36, s30, 0xfff40080
	s_addc_u32 s35, s31, -1
	s_cmp_eq_u32 s58, s34
	s_cselect_b32 s34, s25, s36
	s_cselect_b32 s35, s23, s35
	s_cselect_b32 s38, s63, s64
	s_cselect_b32 s39, s62, s65
	s_add_u32 s36, s34, 0x80
	s_addc_u32 s37, s35, 0
	ds_read_b128 v[162:165], v207
	ds_read_b128 v[166:169], v207 offset:1024
	ds_read_b128 v[170:173], v207 offset:2048
	ds_read_b128 v[174:177], v207 offset:3072
	ds_read_b128 v[188:191], v207 offset:4096
	ds_read_b128 v[192:195], v207 offset:5120
	ds_read_b128 v[196:199], v207 offset:6144
	ds_read_b128 v[212:215], v207 offset:7168
	s_add_u32 s68, s30, 0xfffc0000
	s_addc_u32 s69, s31, -1
	s_mov_b32 m0, s59
	s_nop 0
	global_load_lds_dwordx4 v1, s[68:69]
	s_nop 0
	s_mov_b32 m0, s60
	s_nop 0
	global_load_lds_dwordx4 v1, s[30:31]
	s_waitcnt vmcnt(8)
	s_waitcnt lgkmcnt(0)
	s_barrier
	s_waitcnt lgkmcnt(7)
	v_mfma_f32_16x16x32_bf16 v[126:129], v[130:133], v[162:165], v[126:129]
	v_mfma_f32_16x16x32_bf16 v[122:125], v[138:141], v[162:165], v[122:125]
	s_waitcnt lgkmcnt(5)
	v_mfma_f32_16x16x32_bf16 v[110:113], v[130:133], v[170:173], v[110:113]
	v_mfma_f32_16x16x32_bf16 v[106:109], v[138:141], v[170:173], v[106:109]
	s_waitcnt lgkmcnt(3)
	v_mfma_f32_16x16x32_bf16 v[94:97], v[130:133], v[188:191], v[94:97]
	v_mfma_f32_16x16x32_bf16 v[90:93], v[138:141], v[188:191], v[90:93]
	s_waitcnt lgkmcnt(1)
	v_mfma_f32_16x16x32_bf16 v[78:81], v[130:133], v[196:199], v[78:81]
	v_mfma_f32_16x16x32_bf16 v[74:77], v[138:141], v[196:199], v[74:77]
	v_mfma_f32_16x16x32_bf16 v[126:129], v[134:137], v[166:169], v[126:129]
	v_mfma_f32_16x16x32_bf16 v[122:125], v[142:145], v[166:169], v[122:125]
	v_mfma_f32_16x16x32_bf16 v[110:113], v[134:137], v[174:177], v[110:113]
	v_mfma_f32_16x16x32_bf16 v[106:109], v[142:145], v[174:177], v[106:109]
	v_mfma_f32_16x16x32_bf16 v[94:97], v[134:137], v[192:195], v[94:97]
	v_mfma_f32_16x16x32_bf16 v[90:93], v[142:145], v[192:195], v[90:93]
	s_waitcnt lgkmcnt(0)
	v_mfma_f32_16x16x32_bf16 v[78:81], v[134:137], v[212:215], v[78:81]
	v_mfma_f32_16x16x32_bf16 v[74:77], v[142:145], v[212:215], v[74:77]
	v_mfma_f32_16x16x32_bf16 v[118:121], v[146:149], v[162:165], v[118:121]
	v_mfma_f32_16x16x32_bf16 v[114:117], v[154:157], v[162:165], v[114:117]
	v_mfma_f32_16x16x32_bf16 v[102:105], v[146:149], v[170:173], v[102:105]
	v_mfma_f32_16x16x32_bf16 v[98:101], v[154:157], v[170:173], v[98:101]
	v_mfma_f32_16x16x32_bf16 v[86:89], v[146:149], v[188:191], v[86:89]
	v_mfma_f32_16x16x32_bf16 v[82:85], v[154:157], v[188:191], v[82:85]
	v_mfma_f32_16x16x32_bf16 v[70:73], v[146:149], v[196:199], v[70:73]
	v_mfma_f32_16x16x32_bf16 v[66:69], v[154:157], v[196:199], v[66:69]
	v_mfma_f32_16x16x32_bf16 v[118:121], v[150:153], v[166:169], v[118:121]
	v_mfma_f32_16x16x32_bf16 v[114:117], v[158:161], v[166:169], v[114:117]
	v_mfma_f32_16x16x32_bf16 v[102:105], v[150:153], v[174:177], v[102:105]
	v_mfma_f32_16x16x32_bf16 v[98:101], v[158:161], v[174:177], v[98:101]
	v_mfma_f32_16x16x32_bf16 v[86:89], v[150:153], v[192:195], v[86:89]
	v_mfma_f32_16x16x32_bf16 v[82:85], v[158:161], v[192:195], v[82:85]
	v_mfma_f32_16x16x32_bf16 v[70:73], v[150:153], v[212:215], v[70:73]
	v_mfma_f32_16x16x32_bf16 v[66:69], v[158:161], v[212:215], v[66:69]
	s_barrier
	s_add_u32 s68, s38, 0x40000
	ds_read_b128 v[162:165], v207 offset:16384
	ds_read_b128 v[166:169], v207 offset:17408
	ds_read_b128 v[170:173], v207 offset:18432
	ds_read_b128 v[174:177], v207 offset:19456
	ds_read_b128 v[188:191], v207 offset:20480
	ds_read_b128 v[192:195], v207 offset:21504
	ds_read_b128 v[196:199], v207 offset:22528
	ds_read_b128 v[212:215], v207 offset:23552
	s_mov_b32 m0, s45
	s_nop 0
	global_load_lds_dwordx4 v179, s[38:39]
	s_addc_u32 s69, s39, 0
	s_mov_b32 m0, s46
	s_nop 0
	global_load_lds_dwordx4 v179, s[68:69]
	s_add_u32 s68, s38, 0x80000
	s_addc_u32 s69, s39, 0
	s_mov_b32 m0, s47
	s_nop 0
	global_load_lds_dwordx4 v179, s[68:69]
	s_add_u32 s68, s38, 0xc0000
	s_addc_u32 s69, s39, 0
	s_mov_b32 m0, s48
	s_nop 0
	global_load_lds_dwordx4 v179, s[68:69]
	s_add_u32 s68, s34, 0x40000
	s_mov_b32 m0, s44
	s_nop 0
	global_load_lds_dwordx4 v1, s[34:35]
	s_addc_u32 s69, s35, 0
	s_mov_b32 m0, s49
	s_nop 0
	global_load_lds_dwordx4 v1, s[68:69]
	s_waitcnt vmcnt(8)
	s_waitcnt lgkmcnt(0)
	s_barrier
; #define PG8_STAGE(bufoff, gbase, X) do { _Pragma("unroll") for (int _i = 0; _i < 2; ++_i) { \
;         const char* gp_ = (const char*)(gbase) + (_i ? rs##X : (size_t)0); const unsigned la_ = (unsigned)(size_t)(lds + (bufoff) + ldsw + _i * 8192); \
;         asm volatile("s_mov_b32 m0, %2\n\ts_nop 0\n\tglobal_load_lds_dwordx4 %0, %1" :: "v"(voff##X), "s"(gp_), "s"(la_) : "memory", "m0"); } } while (0)
; #define PG8_LDA(dst, b, h) do { _Pragma("unroll") for (int m = 0; m < 4; ++m) _Pragma("unroll") for (int k = 0; k < 2; ++k) dst[m][k] = *(const LAS bf16x8*)(lds + PG8_SA(b, h) + aoff + m * 2048 + k * 1024); } while (0)
; #define PG8_LDB(dst, b, h) do { _Pragma("unroll") for (int n = 0; n < 2; ++n) _Pragma("unroll") for (int k = 0; k < 2; ++k) dst[n][k] = *(const LAS bf16x8*)(lds + PG8_SB(b, h) + boff + n * 2048 + k * 1024); } while (0)
; #define PG8_WAIT_V(n) asm volatile("s_waitcnt vmcnt(" #n ")" ::: "memory")
; #define PG8_WAIT_L(n) asm volatile("s_waitcnt lgkmcnt(" #n ")" ::: "memory")
; #define PG8_BAR __builtin_amdgcn_s_barrier()
; #define PG8_SCHED __builtin_amdgcn_sched_barrier(0)
; template <class Epi>
; __device__ __forceinline__ void gemm_phase(LAS unsigned char* lds, const Gemm g_in, const StaticOrder& S, const Epi& E) {
;     ...
;             PG8_WAIT_V(8); PG8_WAIT_L(0); PG8_BAR; PG8_MMA(1, 0, At, B0); PG8_MMA(1, 1, At, B1); PG8_BAR; PG8_SCHED;
;             PG8_LDB(B0, 1, 0); PG8_LDB(B1, 1, 1); PG8_SCHED; PG8_LDA(At, 1, 0); PG8_STAGE(PG8_SA(0, 1), a2 + hsA, A);
;             PG8_WAIT_V(8); PG8_WAIT_L(0); PG8_BAR; PG8_MMA(0, 0, At, B0); PG8_MMA(0, 1, At, B1); PG8_BAR; PG8_SCHED;
	s_waitcnt lgkmcnt(7)
	v_mfma_f32_16x16x32_bf16 v[62:65], v[130:133], v[162:165], v[62:65]
	v_mfma_f32_16x16x32_bf16 v[58:61], v[138:141], v[162:165], v[58:61]
	s_waitcnt lgkmcnt(5)
	v_mfma_f32_16x16x32_bf16 v[46:49], v[130:133], v[170:173], v[46:49]
	v_mfma_f32_16x16x32_bf16 v[42:45], v[138:141], v[170:173], v[42:45]
	s_waitcnt lgkmcnt(3)
	v_mfma_f32_16x16x32_bf16 v[30:33], v[130:133], v[188:191], v[30:33]
	v_mfma_f32_16x16x32_bf16 v[26:29], v[138:141], v[188:191], v[26:29]
	s_waitcnt lgkmcnt(1)
	v_mfma_f32_16x16x32_bf16 v[14:17], v[130:133], v[196:199], v[14:17]
	v_mfma_f32_16x16x32_bf16 v[10:13], v[138:141], v[196:199], v[10:13]
	v_mfma_f32_16x16x32_bf16 v[62:65], v[134:137], v[166:169], v[62:65]
	v_mfma_f32_16x16x32_bf16 v[58:61], v[142:145], v[166:169], v[58:61]
	v_mfma_f32_16x16x32_bf16 v[46:49], v[134:137], v[174:177], v[46:49]
	v_mfma_f32_16x16x32_bf16 v[42:45], v[142:145], v[174:177], v[42:45]
	v_mfma_f32_16x16x32_bf16 v[30:33], v[134:137], v[192:195], v[30:33]
	v_mfma_f32_16x16x32_bf16 v[26:29], v[142:145], v[192:195], v[26:29]
	s_waitcnt lgkmcnt(0)
	v_mfma_f32_16x16x32_bf16 v[14:17], v[134:137], v[212:215], v[14:17]
	v_mfma_f32_16x16x32_bf16 v[10:13], v[142:145], v[212:215], v[10:13]
	v_mfma_f32_16x16x32_bf16 v[54:57], v[146:149], v[162:165], v[54:57]
	v_mfma_f32_16x16x32_bf16 v[50:53], v[154:157], v[162:165], v[50:53]
	v_mfma_f32_16x16x32_bf16 v[38:41], v[146:149], v[170:173], v[38:41]
	v_mfma_f32_16x16x32_bf16 v[34:37], v[154:157], v[170:173], v[34:37]
	v_mfma_f32_16x16x32_bf16 v[22:25], v[146:149], v[188:191], v[22:25]
	v_mfma_f32_16x16x32_bf16 v[18:21], v[154:157], v[188:191], v[18:21]
	v_mfma_f32_16x16x32_bf16 v[6:9], v[146:149], v[196:199], v[6:9]
	v_mfma_f32_16x16x32_bf16 v[2:5], v[154:157], v[196:199], v[2:5]
	v_mfma_f32_16x16x32_bf16 v[54:57], v[150:153], v[166:169], v[54:57]
	v_mfma_f32_16x16x32_bf16 v[50:53], v[158:161], v[166:169], v[50:53]
	v_mfma_f32_16x16x32_bf16 v[38:41], v[150:153], v[174:177], v[38:41]
	v_mfma_f32_16x16x32_bf16 v[34:37], v[158:161], v[174:177], v[34:37]
	v_mfma_f32_16x16x32_bf16 v[22:25], v[150:153], v[192:195], v[22:25]
	v_mfma_f32_16x16x32_bf16 v[18:21], v[158:161], v[192:195], v[18:21]
	v_mfma_f32_16x16x32_bf16 v[6:9], v[150:153], v[212:215], v[6:9]
	v_mfma_f32_16x16x32_bf16 v[2:5], v[158:161], v[212:215], v[2:5]
	s_barrier
	ds_read_b128 v[130:133], v208
	ds_read_b128 v[134:137], v208 offset:1024
	ds_read_b128 v[138:141], v208 offset:2048
	ds_read_b128 v[142:145], v208 offset:3072
	ds_read_b128 v[146:149], v209
	ds_read_b128 v[150:153], v209 offset:1024
	ds_read_b128 v[154:157], v209 offset:2048
	ds_read_b128 v[158:161], v209 offset:3072
	ds_read_b128 v[162:165], v207 offset:32768
	ds_read_b128 v[166:169], v207 offset:33792
	ds_read_b128 v[170:173], v207 offset:34816
	ds_read_b128 v[174:177], v207 offset:35840
	ds_read_b128 v[188:191], v207 offset:36864
	ds_read_b128 v[192:195], v207 offset:37888
	ds_read_b128 v[196:199], v207 offset:38912
	ds_read_b128 v[212:215], v207 offset:39936
	s_add_u32 s68, s34, 0x80000
	s_addc_u32 s69, s35, 0
	s_mov_b32 m0, s50
	s_nop 0
	global_load_lds_dwordx4 v1, s[68:69]
	s_add_u32 s68, s34, 0xc0000
	s_addc_u32 s69, s35, 0
	s_mov_b32 m0, s51
	s_nop 0
	global_load_lds_dwordx4 v1, s[68:69]
	s_waitcnt vmcnt(8)
	s_waitcnt lgkmcnt(0)
	s_barrier
	s_waitcnt lgkmcnt(7)
	v_mfma_f32_16x16x32_bf16 v[126:129], v[130:133], v[162:165], v[126:129]
	v_mfma_f32_16x16x32_bf16 v[122:125], v[138:141], v[162:165], v[122:125]
	s_waitcnt lgkmcnt(5)
	v_mfma_f32_16x16x32_bf16 v[110:113], v[130:133], v[170:173], v[110:113]
	v_mfma_f32_16x16x32_bf16 v[106:109], v[138:141], v[170:173], v[106:109]
	s_waitcnt lgkmcnt(3)
	v_mfma_f32_16x16x32_bf16 v[94:97], v[130:133], v[188:191], v[94:97]
	v_mfma_f32_16x16x32_bf16 v[90:93], v[138:141], v[188:191], v[90:93]
	s_waitcnt lgkmcnt(1)
	v_mfma_f32_16x16x32_bf16 v[78:81], v[130:133], v[196:199], v[78:81]
	v_mfma_f32_16x16x32_bf16 v[74:77], v[138:141], v[196:199], v[74:77]
	v_mfma_f32_16x16x32_bf16 v[126:129], v[134:137], v[166:169], v[126:129]
	v_mfma_f32_16x16x32_bf16 v[122:125], v[142:145], v[166:169], v[122:125]
	v_mfma_f32_16x16x32_bf16 v[110:113], v[134:137], v[174:177], v[110:113]
	v_mfma_f32_16x16x32_bf16 v[106:109], v[142:145], v[174:177], v[106:109]
	v_mfma_f32_16x16x32_bf16 v[94:97], v[134:137], v[192:195], v[94:97]
	v_mfma_f32_16x16x32_bf16 v[90:93], v[142:145], v[192:195], v[90:93]
	s_waitcnt lgkmcnt(0)
	v_mfma_f32_16x16x32_bf16 v[78:81], v[134:137], v[212:215], v[78:81]
	v_mfma_f32_16x16x32_bf16 v[74:77], v[142:145], v[212:215], v[74:77]
	v_mfma_f32_16x16x32_bf16 v[118:121], v[146:149], v[162:165], v[118:121]
	v_mfma_f32_16x16x32_bf16 v[114:117], v[154:157], v[162:165], v[114:117]
	v_mfma_f32_16x16x32_bf16 v[102:105], v[146:149], v[170:173], v[102:105]
	v_mfma_f32_16x16x32_bf16 v[98:101], v[154:157], v[170:173], v[98:101]
	v_mfma_f32_16x16x32_bf16 v[86:89], v[146:149], v[188:191], v[86:89]
	v_mfma_f32_16x16x32_bf16 v[82:85], v[154:157], v[188:191], v[82:85]
	v_mfma_f32_16x16x32_bf16 v[70:73], v[146:149], v[196:199], v[70:73]
	v_mfma_f32_16x16x32_bf16 v[66:69], v[154:157], v[196:199], v[66:69]
	v_mfma_f32_16x16x32_bf16 v[118:121], v[150:153], v[166:169], v[118:121]
	v_mfma_f32_16x16x32_bf16 v[114:117], v[158:161], v[166:169], v[114:117]
	v_mfma_f32_16x16x32_bf16 v[102:105], v[150:153], v[174:177], v[102:105]
	v_mfma_f32_16x16x32_bf16 v[98:101], v[158:161], v[174:177], v[98:101]
	v_mfma_f32_16x16x32_bf16 v[86:89], v[150:153], v[192:195], v[86:89]
	v_mfma_f32_16x16x32_bf16 v[82:85], v[158:161], v[192:195], v[82:85]
	v_mfma_f32_16x16x32_bf16 v[70:73], v[150:153], v[212:215], v[70:73]
	v_mfma_f32_16x16x32_bf16 v[66:69], v[158:161], v[212:215], v[66:69]
	s_barrier
; #define PG8_STAGE(bufoff, gbase, X) do { _Pragma("unroll") for (int _i = 0; _i < 2; ++_i) { \
;         const char* gp_ = (const char*)(gbase) + (_i ? rs##X : (size_t)0); const unsigned la_ = (unsigned)(size_t)(lds + (bufoff) + ldsw + _i * 8192); \
;         asm volatile("s_mov_b32 m0, %2\n\ts_nop 0\n\tglobal_load_lds_dwordx4 %0, %1" :: "v"(voff##X), "s"(gp_), "s"(la_) : "memory", "m0"); } } while (0)
; #define PG8_LDA(dst, b, h) do { _Pragma("unroll") for (int m = 0; m < 4; ++m) _Pragma("unroll") for (int k = 0; k < 2; ++k) dst[m][k] = *(const LAS bf16x8*)(lds + PG8_SA(b, h) + aoff + m * 2048 + k * 1024); } while (0)
; #define PG8_WAIT_V(n) asm volatile("s_waitcnt vmcnt(" #n ")" ::: "memory")
; #define PG8_WAIT_L(n) asm volatile("s_waitcnt lgkmcnt(" #n ")" ::: "memory")
; #define PG8_BAR __builtin_amdgcn_s_barrier()
; #define PG8_SCHED __builtin_amdgcn_sched_barrier(0)
; template <class Epi>
; __device__ __forceinline__ void gemm_phase(LAS unsigned char* lds, const Gemm g_in, const StaticOrder& S, const Epi& E) {
;     ...
;             PG8_LDA(At, 1, 1); PG8_STAGE(PG8_SB(1, 0), b3, B); PG8_STAGE(PG8_SB(1, 1), b3 + hsB, B); PG8_STAGE(PG8_SA(1, 0), a3, A);
;             PG8_WAIT_V(8); PG8_WAIT_L(0); PG8_BAR; PG8_MMA(1, 0, At, B0); PG8_MMA(1, 1, At, B1); PG8_BAR; PG8_SCHED;
;         }
	s_add_u32 s68, s38, 0x80
	s_addc_u32 s69, s39, 0
	ds_read_b128 v[162:165], v207 offset:49152
	ds_read_b128 v[166:169], v207 offset:50176
	ds_read_b128 v[170:173], v207 offset:51200
	ds_read_b128 v[174:177], v207 offset:52224
	ds_read_b128 v[188:191], v207 offset:53248
	ds_read_b128 v[192:195], v207 offset:54272
	ds_read_b128 v[196:199], v207 offset:55296
	ds_read_b128 v[212:215], v207 offset:56320
	s_mov_b32 m0, s52
	s_nop 0
	global_load_lds_dwordx4 v179, s[68:69]
	s_add_u32 s68, s38, 0x40080
	s_addc_u32 s69, s39, 0
	s_mov_b32 m0, s53
	s_nop 0
	global_load_lds_dwordx4 v179, s[68:69]
	s_add_u32 s68, s38, 0x80080
	s_addc_u32 s69, s39, 0
	s_mov_b32 m0, s56
	s_nop 0
	global_load_lds_dwordx4 v179, s[68:69]
	s_add_u32 s38, s38, 0xc0080
	s_addc_u32 s39, s39, 0
	s_mov_b32 m0, s57
	s_nop 0
	global_load_lds_dwordx4 v179, s[38:39]
	s_add_u32 s34, s34, 0x40080
	s_mov_b32 m0, s54
	s_nop 0
	global_load_lds_dwordx4 v1, s[36:37]
	s_addc_u32 s35, s35, 0
	s_mov_b32 m0, s55
	s_nop 0
	global_load_lds_dwordx4 v1, s[34:35]
	s_waitcnt vmcnt(8)
	s_waitcnt lgkmcnt(0)
	s_barrier
	s_waitcnt lgkmcnt(7)
	v_mfma_f32_16x16x32_bf16 v[62:65], v[130:133], v[162:165], v[62:65]
	v_mfma_f32_16x16x32_bf16 v[58:61], v[138:141], v[162:165], v[58:61]
	s_waitcnt lgkmcnt(5)
	v_mfma_f32_16x16x32_bf16 v[46:49], v[130:133], v[170:173], v[46:49]
	v_mfma_f32_16x16x32_bf16 v[42:45], v[138:141], v[170:173], v[42:45]
	s_waitcnt lgkmcnt(3)
	v_mfma_f32_16x16x32_bf16 v[30:33], v[130:133], v[188:191], v[30:33]
	v_mfma_f32_16x16x32_bf16 v[26:29], v[138:141], v[188:191], v[26:29]
	s_waitcnt lgkmcnt(1)
	v_mfma_f32_16x16x32_bf16 v[14:17], v[130:133], v[196:199], v[14:17]
	v_mfma_f32_16x16x32_bf16 v[10:13], v[138:141], v[196:199], v[10:13]
	v_mfma_f32_16x16x32_bf16 v[62:65], v[134:137], v[166:169], v[62:65]
	v_mfma_f32_16x16x32_bf16 v[58:61], v[142:145], v[166:169], v[58:61]
	v_mfma_f32_16x16x32_bf16 v[46:49], v[134:137], v[174:177], v[46:49]
	v_mfma_f32_16x16x32_bf16 v[42:45], v[142:145], v[174:177], v[42:45]
	v_mfma_f32_16x16x32_bf16 v[30:33], v[134:137], v[192:195], v[30:33]
	v_mfma_f32_16x16x32_bf16 v[26:29], v[142:145], v[192:195], v[26:29]
	s_waitcnt lgkmcnt(0)
	v_mfma_f32_16x16x32_bf16 v[14:17], v[134:137], v[212:215], v[14:17]
	v_mfma_f32_16x16x32_bf16 v[10:13], v[142:145], v[212:215], v[10:13]
	v_mfma_f32_16x16x32_bf16 v[54:57], v[146:149], v[162:165], v[54:57]
	v_mfma_f32_16x16x32_bf16 v[50:53], v[154:157], v[162:165], v[50:53]
	v_mfma_f32_16x16x32_bf16 v[38:41], v[146:149], v[170:173], v[38:41]
	v_mfma_f32_16x16x32_bf16 v[34:37], v[154:157], v[170:173], v[34:37]
	v_mfma_f32_16x16x32_bf16 v[22:25], v[146:149], v[188:191], v[22:25]
	v_mfma_f32_16x16x32_bf16 v[18:21], v[154:157], v[188:191], v[18:21]
	v_mfma_f32_16x16x32_bf16 v[6:9], v[146:149], v[196:199], v[6:9]
	v_mfma_f32_16x16x32_bf16 v[2:5], v[154:157], v[196:199], v[2:5]
	v_mfma_f32_16x16x32_bf16 v[54:57], v[150:153], v[166:169], v[54:57]
	v_mfma_f32_16x16x32_bf16 v[50:53], v[158:161], v[166:169], v[50:53]
	v_mfma_f32_16x16x32_bf16 v[38:41], v[150:153], v[174:177], v[38:41]
	v_mfma_f32_16x16x32_bf16 v[34:37], v[158:161], v[174:177], v[34:37]
	v_mfma_f32_16x16x32_bf16 v[22:25], v[150:153], v[192:195], v[22:25]
	v_mfma_f32_16x16x32_bf16 v[18:21], v[158:161], v[192:195], v[18:21]
	v_mfma_f32_16x16x32_bf16 v[6:9], v[150:153], v[212:215], v[6:9]
	v_mfma_f32_16x16x32_bf16 v[2:5], v[158:161], v[212:215], v[2:5]
	s_barrier
	s_add_u32 s64, s64, 0x100
	s_addc_u32 s65, s65, 0
	s_add_u32 s30, s30, 0x100
	s_addc_u32 s31, s31, 0
	s_cmp_ge_i32 s66, s41
	s_mov_b32 s34, s66
	s_cbranch_scc0 .LBB0_1285
	s_and_b64 vcc, exec, s[16:17]
	s_cbranch_vccz .LBB0_1288

; #define PG8_STAGE(bufoff, gbase, X) do { _Pragma("unroll") for (int _i = 0; _i < 2; ++_i) { \
;         const char* gp_ = (const char*)(gbase) + (_i ? rs##X : (size_t)0); const unsigned la_ = (unsigned)(size_t)(lds + (bufoff) + ldsw + _i * 8192); \
;         asm volatile("s_mov_b32 m0, %2\n\ts_nop 0\n\tglobal_load_lds_dwordx4 %0, %1" :: "v"(voff##X), "s"(gp_), "s"(la_) : "memory", "m0"); } } while (0)
; #define PG8_LDA(dst, b, h) do { _Pragma("unroll") for (int m = 0; m < 4; ++m) _Pragma("unroll") for (int k = 0; k < 2; ++k) dst[m][k] = *(const LAS bf16x8*)(lds + PG8_SA(b, h) + aoff + m * 2048 + k * 1024); } while (0)
; #define PG8_LDB(dst, b, h) do { _Pragma("unroll") for (int n = 0; n < 2; ++n) _Pragma("unroll") for (int k = 0; k < 2; ++k) dst[n][k] = *(const LAS bf16x8*)(lds + PG8_SB(b, h) + boff + n * 2048 + k * 1024); } while (0)
; #define PG8_WAIT_V(n) asm volatile("s_waitcnt vmcnt(" #n ")" ::: "memory")
; #define PG8_WAIT_L(n) asm volatile("s_waitcnt lgkmcnt(" #n ")" ::: "memory")
; #define PG8_BAR __builtin_amdgcn_s_barrier()
; #define PG8_SCHED __builtin_amdgcn_sched_barrier(0)
; template <class Epi>
; __device__ __forceinline__ void gemm_phase(LAS unsigned char* lds, const Gemm g_in, const StaticOrder& S, const Epi& E) {
;     ...
;         const bool has_next = S.next(ui + 1, nxt);
;         const char* nA = has_next ? (const char*)g.A + (size_t)nxt.pm * tsA : cA; const char* nB = has_next ? (const char*)g.Bt + (size_t)nxt.pn * tsB : cB;
;         for (int t = 0; t < nt; t += 2) {
;             const bool last = (t == nt - 2);
;             const char* a1 = cA + (size_t)(t + 1) * kstep;
;             const char* a2 = last ? nA : cA + (size_t)(t + 2) * kstep; const char* b2 = last ? nB : cB + (size_t)(t + 2) * kstep;
;             const char* a3 = a2 + kstep; const char* b3 = b2 + kstep;
;             PG8_LDB(B0, 0, 0); PG8_LDB(B1, 0, 1); PG8_SCHED; PG8_LDA(At, 0, 0); PG8_STAGE(PG8_SA(1, 1), a1 + hsA, A);
;             PG8_WAIT_V(8); PG8_WAIT_L(0); PG8_BAR; PG8_MMA(0, 0, At, B0); PG8_MMA(0, 1, At, B1); PG8_BAR; PG8_SCHED;
;             PG8_LDA(At, 0, 1); PG8_STAGE(PG8_SB(0, 0), b2, B); PG8_STAGE(PG8_SB(0, 1), b2 + hsB, B); PG8_STAGE(PG8_SA(0, 0), a2, A);
;             PG8_WAIT_V(8); PG8_WAIT_L(0); PG8_BAR; PG8_MMA(1, 0, At, B0); PG8_MMA(1, 1, At, B1); PG8_BAR; PG8_SCHED;
.LBB0_1368:
	v_add_u32_e32 v147, 0x10000, v145
	ds_read_b128 v[134:137], v147
	ds_read_b128 v[138:141], v147 offset:1024
	ds_read_b128 v[148:151], v147 offset:2048
	ds_read_b128 v[152:155], v147 offset:3072
	v_add_u32_e32 v147, 0x14000, v145
	ds_read_b128 v[156:159], v147
	ds_read_b128 v[160:163], v147 offset:1024
	ds_read_b128 v[164:167], v147 offset:2048
	ds_read_b128 v[168:171], v147 offset:3072
	s_add_i32 s70, s40, 2
	s_add_u32 s42, s38, 0xfff40080
	s_addc_u32 s41, s39, -1
	s_cmp_eq_u32 s63, s40
	s_cselect_b32 s40, s31, s42
	s_cselect_b32 s41, s29, s41
	s_cselect_b32 s44, s67, s68
	s_cselect_b32 s45, s66, s69
	s_add_u32 s42, s40, 0x80
	s_addc_u32 s43, s41, 0
	ds_read_b128 v[172:175], v146
	ds_read_b128 v[184:187], v146 offset:1024
	ds_read_b128 v[188:191], v146 offset:2048
	ds_read_b128 v[192:195], v146 offset:3072
	ds_read_b128 v[196:199], v146 offset:4096
	ds_read_b128 v[204:207], v146 offset:5120
	ds_read_b128 v[208:211], v146 offset:6144
	ds_read_b128 v[212:215], v146 offset:7168
	s_add_u32 s72, s38, 0xfffc0000
	s_addc_u32 s73, s39, -1
	s_mov_b32 m0, s64
	s_nop 0
	global_load_lds_dwordx4 v1, s[72:73]
	s_nop 0
	s_mov_b32 m0, s65
	s_nop 0
	global_load_lds_dwordx4 v1, s[38:39]
	s_waitcnt vmcnt(8)
	s_waitcnt lgkmcnt(0)
	s_barrier
	s_waitcnt lgkmcnt(7)
	v_mfma_i32_16x16x64_i8 v[126:129], v[134:137], v[172:175], v[126:129]
	v_mfma_i32_16x16x64_i8 v[122:125], v[148:151], v[172:175], v[122:125]
	s_waitcnt lgkmcnt(5)
	v_mfma_i32_16x16x64_i8 v[118:121], v[134:137], v[188:191], v[118:121]
	v_mfma_i32_16x16x64_i8 v[110:113], v[148:151], v[188:191], v[110:113]
	s_waitcnt lgkmcnt(3)
	v_mfma_i32_16x16x64_i8 v[102:105], v[134:137], v[196:199], v[102:105]
	v_mfma_i32_16x16x64_i8 v[94:97], v[148:151], v[196:199], v[94:97]
	s_waitcnt lgkmcnt(1)
	v_mfma_i32_16x16x64_i8 v[86:89], v[134:137], v[208:211], v[86:89]
	v_mfma_i32_16x16x64_i8 v[78:81], v[148:151], v[208:211], v[78:81]
	v_mfma_i32_16x16x64_i8 v[126:129], v[138:141], v[184:187], v[126:129]
	v_mfma_i32_16x16x64_i8 v[122:125], v[152:155], v[184:187], v[122:125]
	v_mfma_i32_16x16x64_i8 v[118:121], v[138:141], v[192:195], v[118:121]
	v_mfma_i32_16x16x64_i8 v[110:113], v[152:155], v[192:195], v[110:113]
	v_mfma_i32_16x16x64_i8 v[102:105], v[138:141], v[204:207], v[102:105]
	v_mfma_i32_16x16x64_i8 v[94:97], v[152:155], v[204:207], v[94:97]
	s_waitcnt lgkmcnt(0)
	v_mfma_i32_16x16x64_i8 v[86:89], v[138:141], v[212:215], v[86:89]
	v_mfma_i32_16x16x64_i8 v[78:81], v[152:155], v[212:215], v[78:81]
	v_mfma_i32_16x16x64_i8 v[114:117], v[156:159], v[172:175], v[114:117]
	v_mfma_i32_16x16x64_i8 v[106:109], v[164:167], v[172:175], v[106:109]
	v_mfma_i32_16x16x64_i8 v[98:101], v[156:159], v[188:191], v[98:101]
	v_mfma_i32_16x16x64_i8 v[90:93], v[164:167], v[188:191], v[90:93]
	v_mfma_i32_16x16x64_i8 v[82:85], v[156:159], v[196:199], v[82:85]
	v_mfma_i32_16x16x64_i8 v[74:77], v[164:167], v[196:199], v[74:77]
	v_mfma_i32_16x16x64_i8 v[70:73], v[156:159], v[208:211], v[70:73]
	v_mfma_i32_16x16x64_i8 v[66:69], v[164:167], v[208:211], v[66:69]
	v_mfma_i32_16x16x64_i8 v[114:117], v[160:163], v[184:187], v[114:117]
	v_mfma_i32_16x16x64_i8 v[106:109], v[168:171], v[184:187], v[106:109]
	v_mfma_i32_16x16x64_i8 v[98:101], v[160:163], v[192:195], v[98:101]
	v_mfma_i32_16x16x64_i8 v[90:93], v[168:171], v[192:195], v[90:93]
	v_mfma_i32_16x16x64_i8 v[82:85], v[160:163], v[204:207], v[82:85]
	v_mfma_i32_16x16x64_i8 v[74:77], v[168:171], v[204:207], v[74:77]
	v_mfma_i32_16x16x64_i8 v[70:73], v[160:163], v[212:215], v[70:73]
	v_mfma_i32_16x16x64_i8 v[66:69], v[168:171], v[212:215], v[66:69]
	s_barrier
	s_add_u32 s72, s44, 0x40000
	ds_read_b128 v[172:175], v146 offset:16384
	ds_read_b128 v[184:187], v146 offset:17408
	ds_read_b128 v[188:191], v146 offset:18432
	ds_read_b128 v[192:195], v146 offset:19456
	ds_read_b128 v[196:199], v146 offset:20480
	ds_read_b128 v[204:207], v146 offset:21504
	ds_read_b128 v[208:211], v146 offset:22528
	ds_read_b128 v[212:215], v146 offset:23552
	s_mov_b32 m0, s50
	s_nop 0
	global_load_lds_dwordx4 v142, s[44:45]
	s_addc_u32 s73, s45, 0
	s_mov_b32 m0, s51
	s_nop 0
	global_load_lds_dwordx4 v142, s[72:73]
	s_add_u32 s72, s44, 0x80000
	s_addc_u32 s73, s45, 0
	s_mov_b32 m0, s52
	s_nop 0
	global_load_lds_dwordx4 v142, s[72:73]
	s_add_u32 s72, s44, 0xc0000
	s_addc_u32 s73, s45, 0
	s_mov_b32 m0, s53
	s_nop 0
	global_load_lds_dwordx4 v142, s[72:73]
	s_add_u32 s72, s40, 0x40000
	s_mov_b32 m0, s49
	s_nop 0
	global_load_lds_dwordx4 v1, s[40:41]
	s_addc_u32 s73, s41, 0
	s_mov_b32 m0, s54
	s_nop 0
	global_load_lds_dwordx4 v1, s[72:73]
	s_waitcnt vmcnt(8)
	s_waitcnt lgkmcnt(0)
	s_barrier
; #define PG8_STAGE(bufoff, gbase, X) do { _Pragma("unroll") for (int _i = 0; _i < 2; ++_i) { \
;         const char* gp_ = (const char*)(gbase) + (_i ? rs##X : (size_t)0); const unsigned la_ = (unsigned)(size_t)(lds + (bufoff) + ldsw + _i * 8192); \
;         asm volatile("s_mov_b32 m0, %2\n\ts_nop 0\n\tglobal_load_lds_dwordx4 %0, %1" :: "v"(voff##X), "s"(gp_), "s"(la_) : "memory", "m0"); } } while (0)
; #define PG8_LDA(dst, b, h) do { _Pragma("unroll") for (int m = 0; m < 4; ++m) _Pragma("unroll") for (int k = 0; k < 2; ++k) dst[m][k] = *(const LAS bf16x8*)(lds + PG8_SA(b, h) + aoff + m * 2048 + k * 1024); } while (0)
; #define PG8_LDB(dst, b, h) do { _Pragma("unroll") for (int n = 0; n < 2; ++n) _Pragma("unroll") for (int k = 0; k < 2; ++k) dst[n][k] = *(const LAS bf16x8*)(lds + PG8_SB(b, h) + boff + n * 2048 + k * 1024); } while (0)
; #define PG8_WAIT_V(n) asm volatile("s_waitcnt vmcnt(" #n ")" ::: "memory")
; #define PG8_WAIT_L(n) asm volatile("s_waitcnt lgkmcnt(" #n ")" ::: "memory")
; #define PG8_BAR __builtin_amdgcn_s_barrier()
; #define PG8_SCHED __builtin_amdgcn_sched_barrier(0)
; template <class Epi>
; __device__ __forceinline__ void gemm_phase(LAS unsigned char* lds, const Gemm g_in, const StaticOrder& S, const Epi& E) {
;     ...
;             PG8_WAIT_V(8); PG8_WAIT_L(0); PG8_BAR; PG8_MMA(1, 0, At, B0); PG8_MMA(1, 1, At, B1); PG8_BAR; PG8_SCHED;
;             PG8_LDB(B0, 1, 0); PG8_LDB(B1, 1, 1); PG8_SCHED; PG8_LDA(At, 1, 0); PG8_STAGE(PG8_SA(0, 1), a2 + hsA, A);
;             PG8_WAIT_V(8); PG8_WAIT_L(0); PG8_BAR; PG8_MMA(0, 0, At, B0); PG8_MMA(0, 1, At, B1); PG8_BAR; PG8_SCHED;
	s_waitcnt lgkmcnt(7)
	v_mfma_i32_16x16x64_i8 v[62:65], v[134:137], v[172:175], v[62:65]
	v_mfma_i32_16x16x64_i8 v[58:61], v[148:151], v[172:175], v[58:61]
	s_waitcnt lgkmcnt(5)
	v_mfma_i32_16x16x64_i8 v[54:57], v[134:137], v[188:191], v[54:57]
	v_mfma_i32_16x16x64_i8 v[46:49], v[148:151], v[188:191], v[46:49]
	s_waitcnt lgkmcnt(3)
	v_mfma_i32_16x16x64_i8 v[38:41], v[134:137], v[196:199], v[38:41]
	v_mfma_i32_16x16x64_i8 v[30:33], v[148:151], v[196:199], v[30:33]
	s_waitcnt lgkmcnt(1)
	v_mfma_i32_16x16x64_i8 v[22:25], v[134:137], v[208:211], v[22:25]
	v_mfma_i32_16x16x64_i8 v[14:17], v[148:151], v[208:211], v[14:17]
	v_mfma_i32_16x16x64_i8 v[62:65], v[138:141], v[184:187], v[62:65]
	v_mfma_i32_16x16x64_i8 v[58:61], v[152:155], v[184:187], v[58:61]
	v_mfma_i32_16x16x64_i8 v[54:57], v[138:141], v[192:195], v[54:57]
	v_mfma_i32_16x16x64_i8 v[46:49], v[152:155], v[192:195], v[46:49]
	v_mfma_i32_16x16x64_i8 v[38:41], v[138:141], v[204:207], v[38:41]
	v_mfma_i32_16x16x64_i8 v[30:33], v[152:155], v[204:207], v[30:33]
	s_waitcnt lgkmcnt(0)
	v_mfma_i32_16x16x64_i8 v[22:25], v[138:141], v[212:215], v[22:25]
	v_mfma_i32_16x16x64_i8 v[14:17], v[152:155], v[212:215], v[14:17]
	v_mfma_i32_16x16x64_i8 v[50:53], v[156:159], v[172:175], v[50:53]
	v_mfma_i32_16x16x64_i8 v[42:45], v[164:167], v[172:175], v[42:45]
	v_mfma_i32_16x16x64_i8 v[34:37], v[156:159], v[188:191], v[34:37]
	v_mfma_i32_16x16x64_i8 v[26:29], v[164:167], v[188:191], v[26:29]
	v_mfma_i32_16x16x64_i8 v[18:21], v[156:159], v[196:199], v[18:21]
	v_mfma_i32_16x16x64_i8 v[10:13], v[164:167], v[196:199], v[10:13]
	v_mfma_i32_16x16x64_i8 v[6:9], v[156:159], v[208:211], v[6:9]
	v_mfma_i32_16x16x64_i8 v[2:5], v[164:167], v[208:211], v[2:5]
	v_mfma_i32_16x16x64_i8 v[50:53], v[160:163], v[184:187], v[50:53]
	v_mfma_i32_16x16x64_i8 v[42:45], v[168:171], v[184:187], v[42:45]
	v_mfma_i32_16x16x64_i8 v[34:37], v[160:163], v[192:195], v[34:37]
	v_mfma_i32_16x16x64_i8 v[26:29], v[168:171], v[192:195], v[26:29]
	v_mfma_i32_16x16x64_i8 v[18:21], v[160:163], v[204:207], v[18:21]
	v_mfma_i32_16x16x64_i8 v[10:13], v[168:171], v[204:207], v[10:13]
	v_mfma_i32_16x16x64_i8 v[6:9], v[160:163], v[212:215], v[6:9]
	v_mfma_i32_16x16x64_i8 v[2:5], v[168:171], v[212:215], v[2:5]
	s_barrier
	v_add_u32_e32 v147, 0x18000, v145
	ds_read_b128 v[134:137], v147
	ds_read_b128 v[138:141], v147 offset:1024
	ds_read_b128 v[148:151], v147 offset:2048
	ds_read_b128 v[152:155], v147 offset:3072
	v_add_u32_e32 v147, 0x1c000, v145
	ds_read_b128 v[156:159], v147
	ds_read_b128 v[160:163], v147 offset:1024
	ds_read_b128 v[164:167], v147 offset:2048
	ds_read_b128 v[168:171], v147 offset:3072
	ds_read_b128 v[172:175], v146 offset:32768
	ds_read_b128 v[184:187], v146 offset:33792
	ds_read_b128 v[188:191], v146 offset:34816
	ds_read_b128 v[192:195], v146 offset:35840
	ds_read_b128 v[196:199], v146 offset:36864
	ds_read_b128 v[204:207], v146 offset:37888
	ds_read_b128 v[208:211], v146 offset:38912
	ds_read_b128 v[212:215], v146 offset:39936
	s_add_u32 s72, s40, 0x80000
	s_addc_u32 s73, s41, 0
	s_mov_b32 m0, s55
	s_nop 0
	global_load_lds_dwordx4 v1, s[72:73]
	s_add_u32 s72, s40, 0xc0000
	s_addc_u32 s73, s41, 0
	s_mov_b32 m0, s56
	s_nop 0
	global_load_lds_dwordx4 v1, s[72:73]
	s_waitcnt vmcnt(8)
	s_waitcnt lgkmcnt(0)
	s_barrier
	s_waitcnt lgkmcnt(7)
	v_mfma_i32_16x16x64_i8 v[126:129], v[134:137], v[172:175], v[126:129]
	v_mfma_i32_16x16x64_i8 v[122:125], v[148:151], v[172:175], v[122:125]
	s_waitcnt lgkmcnt(5)
	v_mfma_i32_16x16x64_i8 v[118:121], v[134:137], v[188:191], v[118:121]
	v_mfma_i32_16x16x64_i8 v[110:113], v[148:151], v[188:191], v[110:113]
	s_waitcnt lgkmcnt(3)
	v_mfma_i32_16x16x64_i8 v[102:105], v[134:137], v[196:199], v[102:105]
	v_mfma_i32_16x16x64_i8 v[94:97], v[148:151], v[196:199], v[94:97]
	s_waitcnt lgkmcnt(1)
	v_mfma_i32_16x16x64_i8 v[86:89], v[134:137], v[208:211], v[86:89]
	v_mfma_i32_16x16x64_i8 v[78:81], v[148:151], v[208:211], v[78:81]
	v_mfma_i32_16x16x64_i8 v[126:129], v[138:141], v[184:187], v[126:129]
	v_mfma_i32_16x16x64_i8 v[122:125], v[152:155], v[184:187], v[122:125]
	v_mfma_i32_16x16x64_i8 v[118:121], v[138:141], v[192:195], v[118:121]
	v_mfma_i32_16x16x64_i8 v[110:113], v[152:155], v[192:195], v[110:113]
	v_mfma_i32_16x16x64_i8 v[102:105], v[138:141], v[204:207], v[102:105]
	v_mfma_i32_16x16x64_i8 v[94:97], v[152:155], v[204:207], v[94:97]
	s_waitcnt lgkmcnt(0)
	v_mfma_i32_16x16x64_i8 v[86:89], v[138:141], v[212:215], v[86:89]
	v_mfma_i32_16x16x64_i8 v[78:81], v[152:155], v[212:215], v[78:81]
	v_mfma_i32_16x16x64_i8 v[114:117], v[156:159], v[172:175], v[114:117]
	v_mfma_i32_16x16x64_i8 v[106:109], v[164:167], v[172:175], v[106:109]
	v_mfma_i32_16x16x64_i8 v[98:101], v[156:159], v[188:191], v[98:101]
	v_mfma_i32_16x16x64_i8 v[90:93], v[164:167], v[188:191], v[90:93]
	v_mfma_i32_16x16x64_i8 v[82:85], v[156:159], v[196:199], v[82:85]
	v_mfma_i32_16x16x64_i8 v[74:77], v[164:167], v[196:199], v[74:77]
	v_mfma_i32_16x16x64_i8 v[70:73], v[156:159], v[208:211], v[70:73]
	v_mfma_i32_16x16x64_i8 v[66:69], v[164:167], v[208:211], v[66:69]
	v_mfma_i32_16x16x64_i8 v[114:117], v[160:163], v[184:187], v[114:117]
	v_mfma_i32_16x16x64_i8 v[106:109], v[168:171], v[184:187], v[106:109]
	v_mfma_i32_16x16x64_i8 v[98:101], v[160:163], v[192:195], v[98:101]
	v_mfma_i32_16x16x64_i8 v[90:93], v[168:171], v[192:195], v[90:93]
	v_mfma_i32_16x16x64_i8 v[82:85], v[160:163], v[204:207], v[82:85]
	v_mfma_i32_16x16x64_i8 v[74:77], v[168:171], v[204:207], v[74:77]
	v_mfma_i32_16x16x64_i8 v[70:73], v[160:163], v[212:215], v[70:73]
	v_mfma_i32_16x16x64_i8 v[66:69], v[168:171], v[212:215], v[66:69]
	s_barrier
; #define PG8_STAGE(bufoff, gbase, X) do { _Pragma("unroll") for (int _i = 0; _i < 2; ++_i) { \
;         const char* gp_ = (const char*)(gbase) + (_i ? rs##X : (size_t)0); const unsigned la_ = (unsigned)(size_t)(lds + (bufoff) + ldsw + _i * 8192); \
;         asm volatile("s_mov_b32 m0, %2\n\ts_nop 0\n\tglobal_load_lds_dwordx4 %0, %1" :: "v"(voff##X), "s"(gp_), "s"(la_) : "memory", "m0"); } } while (0)
; #define PG8_LDA(dst, b, h) do { _Pragma("unroll") for (int m = 0; m < 4; ++m) _Pragma("unroll") for (int k = 0; k < 2; ++k) dst[m][k] = *(const LAS bf16x8*)(lds + PG8_SA(b, h) + aoff + m * 2048 + k * 1024); } while (0)
; #define PG8_WAIT_V(n) asm volatile("s_waitcnt vmcnt(" #n ")" ::: "memory")
; #define PG8_WAIT_L(n) asm volatile("s_waitcnt lgkmcnt(" #n ")" ::: "memory")
; #define PG8_BAR __builtin_amdgcn_s_barrier()
; #define PG8_SCHED __builtin_amdgcn_sched_barrier(0)
; template <class Epi>
; __device__ __forceinline__ void gemm_phase(LAS unsigned char* lds, const Gemm g_in, const StaticOrder& S, const Epi& E) {
;     ...
;             PG8_LDA(At, 1, 1); PG8_STAGE(PG8_SB(1, 0), b3, B); PG8_STAGE(PG8_SB(1, 1), b3 + hsB, B); PG8_STAGE(PG8_SA(1, 0), a3, A);
;             PG8_WAIT_V(8); PG8_WAIT_L(0); PG8_BAR; PG8_MMA(1, 0, At, B0); PG8_MMA(1, 1, At, B1); PG8_BAR; PG8_SCHED;
;         }
;     __device__ __forceinline__ void operator()(const f32x4 (&acc)[2][2][4][2], const Unit& u, int wr, int wc, int fr, int fq) const {
;     ...
;                     for (int bj = 0; bj < 2; ++bj) { f32x4 a0 = acc[ai][bj][m][0], a1 = acc[ai][bj][m][1];
;                         if (IN == 2) { a0 = __builtin_convertvector(__builtin_bit_cast(i32x4, a0), f32x4); a1 = __builtin_convertvector(__builtin_bit_cast(i32x4, a1), f32x4); }
;                         const f32x4 v0 = bv[m][bj][0] * ALPHA + a0 * scale, v1 = bv[m][bj][1] * ALPHA + a1 * scale;
	s_add_u32 s72, s44, 0x80
	s_addc_u32 s73, s45, 0
	ds_read_b128 v[172:175], v146 offset:49152
	ds_read_b128 v[184:187], v146 offset:50176
	ds_read_b128 v[188:191], v146 offset:51200
	ds_read_b128 v[192:195], v146 offset:52224
	ds_read_b128 v[196:199], v146 offset:53248
	ds_read_b128 v[204:207], v146 offset:54272
	ds_read_b128 v[208:211], v146 offset:55296
	ds_read_b128 v[212:215], v146 offset:56320
	s_mov_b32 m0, s57
	s_nop 0
	global_load_lds_dwordx4 v142, s[72:73]
	s_add_u32 s72, s44, 0x40080
	s_addc_u32 s73, s45, 0
	s_mov_b32 m0, s58
	s_nop 0
	global_load_lds_dwordx4 v142, s[72:73]
	s_add_u32 s72, s44, 0x80080
	s_addc_u32 s73, s45, 0
	s_mov_b32 m0, s61
	s_nop 0
	global_load_lds_dwordx4 v142, s[72:73]
	s_add_u32 s44, s44, 0xc0080
	s_addc_u32 s45, s45, 0
	s_mov_b32 m0, s62
	s_nop 0
	global_load_lds_dwordx4 v142, s[44:45]
	s_add_u32 s40, s40, 0x40080
	s_mov_b32 m0, s59
	s_nop 0
	global_load_lds_dwordx4 v1, s[42:43]
	s_addc_u32 s41, s41, 0
	s_mov_b32 m0, s60
	s_nop 0
	global_load_lds_dwordx4 v1, s[40:41]
	s_waitcnt vmcnt(8)
	s_waitcnt lgkmcnt(0)
	s_barrier
	s_waitcnt lgkmcnt(7)
	v_mfma_i32_16x16x64_i8 v[62:65], v[134:137], v[172:175], v[62:65]
	v_mfma_i32_16x16x64_i8 v[58:61], v[148:151], v[172:175], v[58:61]
	s_waitcnt lgkmcnt(5)
	v_mfma_i32_16x16x64_i8 v[54:57], v[134:137], v[188:191], v[54:57]
	v_mfma_i32_16x16x64_i8 v[46:49], v[148:151], v[188:191], v[46:49]
	s_waitcnt lgkmcnt(3)
	v_mfma_i32_16x16x64_i8 v[38:41], v[134:137], v[196:199], v[38:41]
	v_mfma_i32_16x16x64_i8 v[30:33], v[148:151], v[196:199], v[30:33]
	s_waitcnt lgkmcnt(1)
	v_mfma_i32_16x16x64_i8 v[22:25], v[134:137], v[208:211], v[22:25]
	v_mfma_i32_16x16x64_i8 v[14:17], v[148:151], v[208:211], v[14:17]
	v_mfma_i32_16x16x64_i8 v[62:65], v[138:141], v[184:187], v[62:65]
	v_mfma_i32_16x16x64_i8 v[58:61], v[152:155], v[184:187], v[58:61]
	v_mfma_i32_16x16x64_i8 v[54:57], v[138:141], v[192:195], v[54:57]
	v_mfma_i32_16x16x64_i8 v[46:49], v[152:155], v[192:195], v[46:49]
	v_mfma_i32_16x16x64_i8 v[38:41], v[138:141], v[204:207], v[38:41]
	v_mfma_i32_16x16x64_i8 v[30:33], v[152:155], v[204:207], v[30:33]
	s_waitcnt lgkmcnt(0)
	v_mfma_i32_16x16x64_i8 v[22:25], v[138:141], v[212:215], v[22:25]
	v_mfma_i32_16x16x64_i8 v[14:17], v[152:155], v[212:215], v[14:17]
	v_mfma_i32_16x16x64_i8 v[50:53], v[156:159], v[172:175], v[50:53]
	v_mfma_i32_16x16x64_i8 v[42:45], v[164:167], v[172:175], v[42:45]
	v_mfma_i32_16x16x64_i8 v[34:37], v[156:159], v[188:191], v[34:37]
	v_mfma_i32_16x16x64_i8 v[26:29], v[164:167], v[188:191], v[26:29]
	v_mfma_i32_16x16x64_i8 v[18:21], v[156:159], v[196:199], v[18:21]
	v_mfma_i32_16x16x64_i8 v[10:13], v[164:167], v[196:199], v[10:13]
	v_mfma_i32_16x16x64_i8 v[6:9], v[156:159], v[208:211], v[6:9]
	v_mfma_i32_16x16x64_i8 v[2:5], v[164:167], v[208:211], v[2:5]
	v_mfma_i32_16x16x64_i8 v[50:53], v[160:163], v[184:187], v[50:53]
	v_mfma_i32_16x16x64_i8 v[42:45], v[168:171], v[184:187], v[42:45]
	v_mfma_i32_16x16x64_i8 v[34:37], v[160:163], v[192:195], v[34:37]
	v_mfma_i32_16x16x64_i8 v[26:29], v[168:171], v[192:195], v[26:29]
	v_mfma_i32_16x16x64_i8 v[18:21], v[160:163], v[204:207], v[18:21]
	v_mfma_i32_16x16x64_i8 v[10:13], v[168:171], v[204:207], v[10:13]
	v_mfma_i32_16x16x64_i8 v[6:9], v[160:163], v[212:215], v[6:9]
	v_mfma_i32_16x16x64_i8 v[2:5], v[168:171], v[212:215], v[2:5]
	s_barrier
	s_add_u32 s68, s68, 0x100
	s_addc_u32 s69, s69, 0
	s_add_u32 s38, s38, 0x100
	s_addc_u32 s39, s39, 0
	s_cmp_ge_i32 s70, s46
	s_mov_b32 s40, s70
	s_cbranch_scc0 .LBB0_1368
	v_cvt_f32_i32_e32 v127, v127
	v_cvt_f32_i32_e32 v126, v126
	v_cvt_f32_i32_e32 v129, v129
	v_cvt_f32_i32_e32 v128, v128
	v_cvt_f32_i32_e32 v135, v123
	v_cvt_f32_i32_e32 v125, v125
	v_cvt_f32_i32_e32 v124, v124
	v_cvt_f32_i32_e32 v134, v122
	v_cvt_f32_i32_e32 v115, v115
	v_cvt_f32_i32_e32 v114, v114
	v_cvt_f32_i32_e32 v117, v117
	v_cvt_f32_i32_e32 v116, v116
	v_cvt_f32_i32_e32 v107, v107
	v_cvt_f32_i32_e32 v109, v109
	v_cvt_f32_i32_e32 v108, v108
	v_cvt_f32_i32_e32 v106, v106
	v_pk_mul_f32 v[122:123], v[128:129], s[16:17] op_sel_hi:[1,0]
	v_pk_mul_f32 v[128:129], v[126:127], s[16:17] op_sel_hi:[1,0]
	v_pk_mul_f32 v[126:127], v[124:125], s[16:17] op_sel_hi:[1,0]
	v_pk_mul_f32 v[124:125], v[134:135], s[16:17] op_sel_hi:[1,0]
	v_pk_mul_f32 v[140:141], v[116:117], s[16:17] op_sel_hi:[1,0]
	v_pk_mul_f32 v[138:139], v[114:115], s[16:17] op_sel_hi:[1,0]
	v_pk_mul_f32 v[136:137], v[108:109], s[16:17] op_sel_hi:[1,0]
	v_pk_mul_f32 v[134:135], v[106:107], s[16:17] op_sel_hi:[1,0]
	v_cvt_f32_i32_e32 v107, v119
	v_cvt_f32_i32_e32 v106, v118
	v_cvt_f32_i32_e32 v109, v121
	v_cvt_f32_i32_e32 v108, v120
	v_cvt_f32_i32_e32 v115, v111
	v_cvt_f32_i32_e32 v117, v113
	v_cvt_f32_i32_e32 v116, v112
	v_cvt_f32_i32_e32 v114, v110
	v_cvt_f32_i32_e32 v99, v99
	v_cvt_f32_i32_e32 v98, v98
	v_cvt_f32_i32_e32 v101, v101
	v_cvt_f32_i32_e32 v100, v100
	v_cvt_f32_i32_e32 v91, v91
	v_cvt_f32_i32_e32 v93, v93
	v_cvt_f32_i32_e32 v92, v92
	v_cvt_f32_i32_e32 v90, v90
	v_pk_mul_f32 v[112:113], v[108:109], s[16:17] op_sel_hi:[1,0]
	v_pk_mul_f32 v[110:111], v[106:107], s[16:17] op_sel_hi:[1,0]
	v_pk_mul_f32 v[108:109], v[116:117], s[16:17] op_sel_hi:[1,0]
	v_pk_mul_f32 v[106:107], v[114:115], s[16:17] op_sel_hi:[1,0]
	v_pk_mul_f32 v[120:121], v[100:101], s[16:17] op_sel_hi:[1,0]
	v_pk_mul_f32 v[118:119], v[98:99], s[16:17] op_sel_hi:[1,0]
	v_pk_mul_f32 v[116:117], v[92:93], s[16:17] op_sel_hi:[1,0]
	v_pk_mul_f32 v[114:115], v[90:91], s[16:17] op_sel_hi:[1,0]
	v_cvt_f32_i32_e32 v91, v103
	v_cvt_f32_i32_e32 v90, v102
;     __device__ __forceinline__ void operator()(const f32x4 (&acc)[2][2][4][2], const Unit& u, int wr, int wc, int fr, int fq) const {
;     ...
;                     for (int bj = 0; bj < 2; ++bj) { f32x4 a0 = acc[ai][bj][m][0], a1 = acc[ai][bj][m][1];
;                         if (IN == 2) { a0 = __builtin_convertvector(__builtin_bit_cast(i32x4, a0), f32x4); a1 = __builtin_convertvector(__builtin_bit_cast(i32x4, a1), f32x4); }
;                         const f32x4 v0 = bv[m][bj][0] * ALPHA + a0 * scale, v1 = bv[m][bj][1] * ALPHA + a1 * scale;
	v_cvt_f32_i32_e32 v93, v105
	v_cvt_f32_i32_e32 v92, v104
	v_cvt_f32_i32_e32 v99, v95
	v_cvt_f32_i32_e32 v101, v97
	v_cvt_f32_i32_e32 v100, v96
	v_cvt_f32_i32_e32 v98, v94
	v_cvt_f32_i32_e32 v83, v83
	v_cvt_f32_i32_e32 v82, v82
	v_cvt_f32_i32_e32 v85, v85
	v_cvt_f32_i32_e32 v84, v84
	v_cvt_f32_i32_e32 v75, v75
	v_cvt_f32_i32_e32 v77, v77
	v_cvt_f32_i32_e32 v76, v76
	v_cvt_f32_i32_e32 v74, v74
	v_pk_mul_f32 v[96:97], v[92:93], s[16:17] op_sel_hi:[1,0]
	v_pk_mul_f32 v[94:95], v[90:91], s[16:17] op_sel_hi:[1,0]
	v_pk_mul_f32 v[92:93], v[100:101], s[16:17] op_sel_hi:[1,0]
	v_pk_mul_f32 v[90:91], v[98:99], s[16:17] op_sel_hi:[1,0]
	v_pk_mul_f32 v[104:105], v[84:85], s[16:17] op_sel_hi:[1,0]
	v_pk_mul_f32 v[102:103], v[82:83], s[16:17] op_sel_hi:[1,0]
	v_pk_mul_f32 v[100:101], v[76:77], s[16:17] op_sel_hi:[1,0]
	v_pk_mul_f32 v[98:99], v[74:75], s[16:17] op_sel_hi:[1,0]
	v_cvt_f32_i32_e32 v75, v87
	v_cvt_f32_i32_e32 v74, v86
	v_cvt_f32_i32_e32 v77, v89
	v_cvt_f32_i32_e32 v76, v88
	v_cvt_f32_i32_e32 v83, v79
	v_cvt_f32_i32_e32 v85, v81
	v_cvt_f32_i32_e32 v84, v80
	v_cvt_f32_i32_e32 v82, v78
	v_cvt_f32_i32_e32 v71, v71
	v_cvt_f32_i32_e32 v70, v70
	v_cvt_f32_i32_e32 v73, v73
	v_cvt_f32_i32_e32 v72, v72
	v_cvt_f32_i32_e32 v67, v67
	v_cvt_f32_i32_e32 v69, v69
	v_cvt_f32_i32_e32 v68, v68
	v_cvt_f32_i32_e32 v66, v66
	v_cvt_f32_i32_e32 v51, v51
	v_cvt_f32_i32_e32 v50, v50
	v_cvt_f32_i32_e32 v53, v53
	v_cvt_f32_i32_e32 v52, v52
	v_cvt_f32_i32_e32 v43, v43
	v_cvt_f32_i32_e32 v45, v45
	v_cvt_f32_i32_e32 v44, v44
	v_cvt_f32_i32_e32 v42, v42
	v_pk_mul_f32 v[80:81], v[76:77], s[16:17] op_sel_hi:[1,0]
	v_pk_mul_f32 v[78:79], v[74:75], s[16:17] op_sel_hi:[1,0]
	v_pk_mul_f32 v[76:77], v[84:85], s[16:17] op_sel_hi:[1,0]
	v_pk_mul_f32 v[74:75], v[82:83], s[16:17] op_sel_hi:[1,0]
	v_pk_mul_f32 v[88:89], v[72:73], s[16:17] op_sel_hi:[1,0]
	v_pk_mul_f32 v[86:87], v[70:71], s[16:17] op_sel_hi:[1,0]
	v_pk_mul_f32 v[84:85], v[68:69], s[16:17] op_sel_hi:[1,0]
	v_pk_mul_f32 v[82:83], v[66:67], s[16:17] op_sel_hi:[1,0]
	v_pk_mul_f32 v[72:73], v[52:53], s[16:17] op_sel_hi:[1,0]
	v_pk_mul_f32 v[70:71], v[50:51], s[16:17] op_sel_hi:[1,0]
	v_pk_mul_f32 v[68:69], v[44:45], s[16:17] op_sel_hi:[1,0]
	v_pk_mul_f32 v[66:67], v[42:43], s[16:17] op_sel_hi:[1,0]
	v_cvt_f32_i32_e32 v43, v55
	v_cvt_f32_i32_e32 v42, v54
	v_cvt_f32_i32_e32 v45, v57
	v_cvt_f32_i32_e32 v44, v56
	v_cvt_f32_i32_e32 v51, v47
	v_cvt_f32_i32_e32 v53, v49
	v_cvt_f32_i32_e32 v52, v48
	v_cvt_f32_i32_e32 v50, v46
	v_cvt_f32_i32_e32 v35, v35
	v_cvt_f32_i32_e32 v34, v34
	v_cvt_f32_i32_e32 v37, v37
	v_cvt_f32_i32_e32 v36, v36
	v_cvt_f32_i32_e32 v27, v27
	v_cvt_f32_i32_e32 v29, v29
	v_cvt_f32_i32_e32 v28, v28
	v_cvt_f32_i32_e32 v26, v26
	v_pk_mul_f32 v[48:49], v[44:45], s[16:17] op_sel_hi:[1,0]
	v_pk_mul_f32 v[46:47], v[42:43], s[16:17] op_sel_hi:[1,0]
	v_pk_mul_f32 v[44:45], v[52:53], s[16:17] op_sel_hi:[1,0]
	v_pk_mul_f32 v[42:43], v[50:51], s[16:17] op_sel_hi:[1,0]
	v_pk_mul_f32 v[56:57], v[36:37], s[16:17] op_sel_hi:[1,0]
	v_pk_mul_f32 v[54:55], v[34:35], s[16:17] op_sel_hi:[1,0]
	v_pk_mul_f32 v[52:53], v[28:29], s[16:17] op_sel_hi:[1,0]
	v_pk_mul_f32 v[50:51], v[26:27], s[16:17] op_sel_hi:[1,0]
	v_cvt_f32_i32_e32 v27, v39
	v_cvt_f32_i32_e32 v26, v38
	v_cvt_f32_i32_e32 v29, v41
	v_cvt_f32_i32_e32 v28, v40
	v_cvt_f32_i32_e32 v35, v31
	v_cvt_f32_i32_e32 v37, v33
	v_cvt_f32_i32_e32 v36, v32
	v_cvt_f32_i32_e32 v34, v30
	v_cvt_f32_i32_e32 v19, v19
	v_cvt_f32_i32_e32 v18, v18
	v_cvt_f32_i32_e32 v21, v21
	v_cvt_f32_i32_e32 v20, v20
	v_cvt_f32_i32_e32 v11, v11
	v_cvt_f32_i32_e32 v13, v13
	v_cvt_f32_i32_e32 v12, v12
	v_cvt_f32_i32_e32 v10, v10
	v_cvt_f32_i32_e32 v63, v63
	v_cvt_f32_i32_e32 v62, v62
	v_cvt_f32_i32_e32 v65, v65
	v_cvt_f32_i32_e32 v64, v64
	v_cvt_f32_i32_e32 v59, v59
	v_cvt_f32_i32_e32 v61, v61
	v_cvt_f32_i32_e32 v60, v60
	v_cvt_f32_i32_e32 v58, v58
	v_pk_mul_f32 v[32:33], v[28:29], s[16:17] op_sel_hi:[1,0]
	v_pk_mul_f32 v[30:31], v[26:27], s[16:17] op_sel_hi:[1,0]
	v_pk_mul_f32 v[28:29], v[36:37], s[16:17] op_sel_hi:[1,0]
	v_pk_mul_f32 v[26:27], v[34:35], s[16:17] op_sel_hi:[1,0]
	v_pk_mul_f32 v[36:37], v[20:21], s[16:17] op_sel_hi:[1,0]
	v_pk_mul_f32 v[34:35], v[18:19], s[16:17] op_sel_hi:[1,0]
	v_pk_mul_f32 v[20:21], v[12:13], s[16:17] op_sel_hi:[1,0]
	v_pk_mul_f32 v[18:19], v[10:11], s[16:17] op_sel_hi:[1,0]
	v_cvt_f32_i32_e32 v11, v23
	v_cvt_f32_i32_e32 v10, v22
	v_cvt_f32_i32_e32 v13, v25
	v_cvt_f32_i32_e32 v12, v24
	v_cvt_f32_i32_e32 v23, v15
	v_cvt_f32_i32_e32 v25, v17
	v_cvt_f32_i32_e32 v24, v16
	v_cvt_f32_i32_e32 v22, v14
	v_cvt_f32_i32_e32 v7, v7
	v_cvt_f32_i32_e32 v6, v6
	v_cvt_f32_i32_e32 v9, v9
	v_cvt_f32_i32_e32 v8, v8
	v_cvt_f32_i32_e32 v3, v3
	v_cvt_f32_i32_e32 v5, v5
	v_cvt_f32_i32_e32 v4, v4
	v_cvt_f32_i32_e32 v2, v2
	v_pk_mul_f32 v[64:65], v[64:65], s[16:17] op_sel_hi:[1,0]
	v_pk_mul_f32 v[62:63], v[62:63], s[16:17] op_sel_hi:[1,0]
	v_pk_mul_f32 v[60:61], v[60:61], s[16:17] op_sel_hi:[1,0]
	v_pk_mul_f32 v[58:59], v[58:59], s[16:17] op_sel_hi:[1,0]
	v_pk_mul_f32 v[16:17], v[12:13], s[16:17] op_sel_hi:[1,0]
	v_pk_mul_f32 v[14:15], v[10:11], s[16:17] op_sel_hi:[1,0]
	v_pk_mul_f32 v[12:13], v[24:25], s[16:17] op_sel_hi:[1,0]
	v_pk_mul_f32 v[10:11], v[22:23], s[16:17] op_sel_hi:[1,0]
	v_pk_mul_f32 v[8:9], v[8:9], s[16:17] op_sel_hi:[1,0]
	v_pk_mul_f32 v[6:7], v[6:7], s[16:17] op_sel_hi:[1,0]
	v_pk_mul_f32 v[4:5], v[4:5], s[16:17] op_sel_hi:[1,0]
	v_pk_mul_f32 v[2:3], v[2:3], s[16:17] op_sel_hi:[1,0]
	s_and_b64 vcc, exec, s[14:15]
	s_cbranch_vccz .LBB0_1371

; #define PG8_STAGE(bufoff, gbase, X) do { _Pragma("unroll") for (int _i = 0; _i < 2; ++_i) { \
;         const char* gp_ = (const char*)(gbase) + (_i ? rs##X : (size_t)0); const unsigned la_ = (unsigned)(size_t)(lds + (bufoff) + ldsw + _i * 8192); \
;         asm volatile("s_mov_b32 m0, %2\n\ts_nop 0\n\tglobal_load_lds_dwordx4 %0, %1" :: "v"(voff##X), "s"(gp_), "s"(la_) : "memory", "m0"); } } while (0)
; #define PG8_LDA(dst, b, h) do { _Pragma("unroll") for (int m = 0; m < 4; ++m) _Pragma("unroll") for (int k = 0; k < 2; ++k) dst[m][k] = *(const LAS bf16x8*)(lds + PG8_SA(b, h) + aoff + m * 2048 + k * 1024); } while (0)
; #define PG8_LDB(dst, b, h) do { _Pragma("unroll") for (int n = 0; n < 2; ++n) _Pragma("unroll") for (int k = 0; k < 2; ++k) dst[n][k] = *(const LAS bf16x8*)(lds + PG8_SB(b, h) + boff + n * 2048 + k * 1024); } while (0)
; #define PG8_WAIT_V(n) asm volatile("s_waitcnt vmcnt(" #n ")" ::: "memory")
; #define PG8_WAIT_L(n) asm volatile("s_waitcnt lgkmcnt(" #n ")" ::: "memory")
; #define PG8_BAR __builtin_amdgcn_s_barrier()
; #define PG8_SCHED __builtin_amdgcn_sched_barrier(0)
; template <class Epi>
; __device__ __forceinline__ void gemm_phase(LAS unsigned char* lds, const Gemm g_in, const StaticOrder& S, const Epi& E) {
;     ...
;         const bool has_next = S.next(ui + 1, nxt);
;         const char* nA = has_next ? (const char*)g.A + (size_t)nxt.pm * tsA : cA; const char* nB = has_next ? (const char*)g.Bt + (size_t)nxt.pn * tsB : cB;
;         for (int t = 0; t < nt; t += 2) {
;             const bool last = (t == nt - 2);
;             const char* a1 = cA + (size_t)(t + 1) * kstep;
;             const char* a2 = last ? nA : cA + (size_t)(t + 2) * kstep; const char* b2 = last ? nB : cB + (size_t)(t + 2) * kstep;
;             const char* a3 = a2 + kstep; const char* b3 = b2 + kstep;
;             PG8_LDB(B0, 0, 0); PG8_LDB(B1, 0, 1); PG8_SCHED; PG8_LDA(At, 0, 0); PG8_STAGE(PG8_SA(1, 1), a1 + hsA, A);
;             PG8_WAIT_V(8); PG8_WAIT_L(0); PG8_BAR; PG8_MMA(0, 0, At, B0); PG8_MMA(0, 1, At, B1); PG8_BAR; PG8_SCHED;
;             PG8_LDA(At, 0, 1); PG8_STAGE(PG8_SB(0, 0), b2, B); PG8_STAGE(PG8_SB(0, 1), b2 + hsB, B); PG8_STAGE(PG8_SA(0, 0), a2, A);
;             PG8_WAIT_V(8); PG8_WAIT_L(0); PG8_BAR; PG8_MMA(1, 0, At, B0); PG8_MMA(1, 1, At, B1); PG8_BAR; PG8_SCHED;
.LBB0_1510:
	v_add_u32_e32 v139, 0x10000, v137
	ds_read_b128 v[140:143], v139
	ds_read_b128 v[144:147], v139 offset:1024
	ds_read_b128 v[148:151], v139 offset:2048
	ds_read_b128 v[152:155], v139 offset:3072
	v_add_u32_e32 v139, 0x14000, v137
	ds_read_b128 v[156:159], v139
	ds_read_b128 v[160:163], v139 offset:1024
	ds_read_b128 v[164:167], v139 offset:2048
	ds_read_b128 v[168:171], v139 offset:3072
	s_add_i32 s64, s28, 2
	s_add_u32 s30, s26, 0xfff40080
	s_addc_u32 s29, s27, -1
	s_cmp_eq_u32 s56, s28
	s_cselect_b32 s28, s21, s30
	s_cselect_b32 s29, s19, s29
	s_cselect_b32 s34, s61, s62
	s_cselect_b32 s35, s60, s63
	s_add_u32 s30, s28, 0x80
	s_addc_u32 s31, s29, 0
	ds_read_b128 v[172:175], v138
	ds_read_b128 v[182:185], v138 offset:1024
	ds_read_b128 v[186:189], v138 offset:2048
	ds_read_b128 v[190:193], v138 offset:3072
	ds_read_b128 v[194:197], v138 offset:4096
	ds_read_b128 v[198:201], v138 offset:5120
	ds_read_b128 v[204:207], v138 offset:6144
	ds_read_b128 v[208:211], v138 offset:7168
	s_add_u32 s66, s26, 0xfffc0000
	s_addc_u32 s67, s27, -1
	s_mov_b32 m0, s57
	s_nop 0
	global_load_lds_dwordx4 v1, s[66:67]
	s_nop 0
	s_mov_b32 m0, s58
	s_nop 0
	global_load_lds_dwordx4 v1, s[26:27]
	s_waitcnt vmcnt(8)
	s_waitcnt lgkmcnt(0)
	s_barrier
	s_waitcnt lgkmcnt(7)
	v_mfma_i32_16x16x64_i8 v[126:129], v[140:143], v[172:175], v[126:129]
	v_mfma_i32_16x16x64_i8 v[118:121], v[148:151], v[172:175], v[118:121]
	s_waitcnt lgkmcnt(5)
	v_mfma_i32_16x16x64_i8 v[110:113], v[140:143], v[186:189], v[110:113]
	v_mfma_i32_16x16x64_i8 v[102:105], v[148:151], v[186:189], v[102:105]
	s_waitcnt lgkmcnt(3)
	v_mfma_i32_16x16x64_i8 v[94:97], v[140:143], v[194:197], v[94:97]
	v_mfma_i32_16x16x64_i8 v[86:89], v[148:151], v[194:197], v[86:89]
	s_waitcnt lgkmcnt(1)
	v_mfma_i32_16x16x64_i8 v[78:81], v[140:143], v[204:207], v[78:81]
	v_mfma_i32_16x16x64_i8 v[70:73], v[148:151], v[204:207], v[70:73]
	v_mfma_i32_16x16x64_i8 v[126:129], v[144:147], v[182:185], v[126:129]
	v_mfma_i32_16x16x64_i8 v[118:121], v[152:155], v[182:185], v[118:121]
	v_mfma_i32_16x16x64_i8 v[110:113], v[144:147], v[190:193], v[110:113]
	v_mfma_i32_16x16x64_i8 v[102:105], v[152:155], v[190:193], v[102:105]
	v_mfma_i32_16x16x64_i8 v[94:97], v[144:147], v[198:201], v[94:97]
	v_mfma_i32_16x16x64_i8 v[86:89], v[152:155], v[198:201], v[86:89]
	s_waitcnt lgkmcnt(0)
	v_mfma_i32_16x16x64_i8 v[78:81], v[144:147], v[208:211], v[78:81]
	v_mfma_i32_16x16x64_i8 v[70:73], v[152:155], v[208:211], v[70:73]
	v_mfma_i32_16x16x64_i8 v[122:125], v[156:159], v[172:175], v[122:125]
	v_mfma_i32_16x16x64_i8 v[114:117], v[164:167], v[172:175], v[114:117]
	v_mfma_i32_16x16x64_i8 v[106:109], v[156:159], v[186:189], v[106:109]
	v_mfma_i32_16x16x64_i8 v[98:101], v[164:167], v[186:189], v[98:101]
	v_mfma_i32_16x16x64_i8 v[90:93], v[156:159], v[194:197], v[90:93]
	v_mfma_i32_16x16x64_i8 v[82:85], v[164:167], v[194:197], v[82:85]
	v_mfma_i32_16x16x64_i8 v[74:77], v[156:159], v[204:207], v[74:77]
	v_mfma_i32_16x16x64_i8 v[66:69], v[164:167], v[204:207], v[66:69]
	v_mfma_i32_16x16x64_i8 v[122:125], v[160:163], v[182:185], v[122:125]
	v_mfma_i32_16x16x64_i8 v[114:117], v[168:171], v[182:185], v[114:117]
	v_mfma_i32_16x16x64_i8 v[106:109], v[160:163], v[190:193], v[106:109]
	v_mfma_i32_16x16x64_i8 v[98:101], v[168:171], v[190:193], v[98:101]
	v_mfma_i32_16x16x64_i8 v[90:93], v[160:163], v[198:201], v[90:93]
	v_mfma_i32_16x16x64_i8 v[82:85], v[168:171], v[198:201], v[82:85]
	v_mfma_i32_16x16x64_i8 v[74:77], v[160:163], v[208:211], v[74:77]
	v_mfma_i32_16x16x64_i8 v[66:69], v[168:171], v[208:211], v[66:69]
	s_barrier
	s_add_u32 s66, s34, 0x40000
	ds_read_b128 v[172:175], v138 offset:16384
	ds_read_b128 v[182:185], v138 offset:17408
	ds_read_b128 v[186:189], v138 offset:18432
	ds_read_b128 v[190:193], v138 offset:19456
	ds_read_b128 v[194:197], v138 offset:20480
	ds_read_b128 v[198:201], v138 offset:21504
	ds_read_b128 v[204:207], v138 offset:22528
	ds_read_b128 v[208:211], v138 offset:23552
	s_mov_b32 m0, s41
	s_nop 0
	global_load_lds_dwordx4 v134, s[34:35]
	s_addc_u32 s67, s35, 0
	s_mov_b32 m0, s42
	s_nop 0
	global_load_lds_dwordx4 v134, s[66:67]
	s_add_u32 s66, s34, 0x80000
	s_addc_u32 s67, s35, 0
	s_mov_b32 m0, s43
	s_nop 0
	global_load_lds_dwordx4 v134, s[66:67]
	s_add_u32 s66, s34, 0xc0000
	s_addc_u32 s67, s35, 0
	s_mov_b32 m0, s44
	s_nop 0
	global_load_lds_dwordx4 v134, s[66:67]
	s_add_u32 s66, s28, 0x40000
	s_mov_b32 m0, s40
	s_nop 0
	global_load_lds_dwordx4 v1, s[28:29]
	s_addc_u32 s67, s29, 0
	s_mov_b32 m0, s45
	s_nop 0
	global_load_lds_dwordx4 v1, s[66:67]
	s_waitcnt vmcnt(8)
	s_waitcnt lgkmcnt(0)
	s_barrier
; #define PG8_STAGE(bufoff, gbase, X) do { _Pragma("unroll") for (int _i = 0; _i < 2; ++_i) { \
;         const char* gp_ = (const char*)(gbase) + (_i ? rs##X : (size_t)0); const unsigned la_ = (unsigned)(size_t)(lds + (bufoff) + ldsw + _i * 8192); \
;         asm volatile("s_mov_b32 m0, %2\n\ts_nop 0\n\tglobal_load_lds_dwordx4 %0, %1" :: "v"(voff##X), "s"(gp_), "s"(la_) : "memory", "m0"); } } while (0)
; #define PG8_LDA(dst, b, h) do { _Pragma("unroll") for (int m = 0; m < 4; ++m) _Pragma("unroll") for (int k = 0; k < 2; ++k) dst[m][k] = *(const LAS bf16x8*)(lds + PG8_SA(b, h) + aoff + m * 2048 + k * 1024); } while (0)
; #define PG8_LDB(dst, b, h) do { _Pragma("unroll") for (int n = 0; n < 2; ++n) _Pragma("unroll") for (int k = 0; k < 2; ++k) dst[n][k] = *(const LAS bf16x8*)(lds + PG8_SB(b, h) + boff + n * 2048 + k * 1024); } while (0)
; #define PG8_WAIT_V(n) asm volatile("s_waitcnt vmcnt(" #n ")" ::: "memory")
; #define PG8_WAIT_L(n) asm volatile("s_waitcnt lgkmcnt(" #n ")" ::: "memory")
; #define PG8_BAR __builtin_amdgcn_s_barrier()
; #define PG8_SCHED __builtin_amdgcn_sched_barrier(0)
; template <class Epi>
; __device__ __forceinline__ void gemm_phase(LAS unsigned char* lds, const Gemm g_in, const StaticOrder& S, const Epi& E) {
;     ...
;             PG8_WAIT_V(8); PG8_WAIT_L(0); PG8_BAR; PG8_MMA(1, 0, At, B0); PG8_MMA(1, 1, At, B1); PG8_BAR; PG8_SCHED;
;             PG8_LDB(B0, 1, 0); PG8_LDB(B1, 1, 1); PG8_SCHED; PG8_LDA(At, 1, 0); PG8_STAGE(PG8_SA(0, 1), a2 + hsA, A);
;             PG8_WAIT_V(8); PG8_WAIT_L(0); PG8_BAR; PG8_MMA(0, 0, At, B0); PG8_MMA(0, 1, At, B1); PG8_BAR; PG8_SCHED;
	s_waitcnt lgkmcnt(7)
	v_mfma_i32_16x16x64_i8 v[62:65], v[140:143], v[172:175], v[62:65]
	v_mfma_i32_16x16x64_i8 v[54:57], v[148:151], v[172:175], v[54:57]
	s_waitcnt lgkmcnt(5)
	v_mfma_i32_16x16x64_i8 v[46:49], v[140:143], v[186:189], v[46:49]
	v_mfma_i32_16x16x64_i8 v[38:41], v[148:151], v[186:189], v[38:41]
	s_waitcnt lgkmcnt(3)
	v_mfma_i32_16x16x64_i8 v[30:33], v[140:143], v[194:197], v[30:33]
	v_mfma_i32_16x16x64_i8 v[22:25], v[148:151], v[194:197], v[22:25]
	s_waitcnt lgkmcnt(1)
	v_mfma_i32_16x16x64_i8 v[14:17], v[140:143], v[204:207], v[14:17]
	v_mfma_i32_16x16x64_i8 v[6:9], v[148:151], v[204:207], v[6:9]
	v_mfma_i32_16x16x64_i8 v[62:65], v[144:147], v[182:185], v[62:65]
	v_mfma_i32_16x16x64_i8 v[54:57], v[152:155], v[182:185], v[54:57]
	v_mfma_i32_16x16x64_i8 v[46:49], v[144:147], v[190:193], v[46:49]
	v_mfma_i32_16x16x64_i8 v[38:41], v[152:155], v[190:193], v[38:41]
	v_mfma_i32_16x16x64_i8 v[30:33], v[144:147], v[198:201], v[30:33]
	v_mfma_i32_16x16x64_i8 v[22:25], v[152:155], v[198:201], v[22:25]
	s_waitcnt lgkmcnt(0)
	v_mfma_i32_16x16x64_i8 v[14:17], v[144:147], v[208:211], v[14:17]
	v_mfma_i32_16x16x64_i8 v[6:9], v[152:155], v[208:211], v[6:9]
	v_mfma_i32_16x16x64_i8 v[58:61], v[156:159], v[172:175], v[58:61]
	v_mfma_i32_16x16x64_i8 v[50:53], v[164:167], v[172:175], v[50:53]
	v_mfma_i32_16x16x64_i8 v[42:45], v[156:159], v[186:189], v[42:45]
	v_mfma_i32_16x16x64_i8 v[34:37], v[164:167], v[186:189], v[34:37]
	v_mfma_i32_16x16x64_i8 v[26:29], v[156:159], v[194:197], v[26:29]
	v_mfma_i32_16x16x64_i8 v[18:21], v[164:167], v[194:197], v[18:21]
	v_mfma_i32_16x16x64_i8 v[10:13], v[156:159], v[204:207], v[10:13]
	v_mfma_i32_16x16x64_i8 v[2:5], v[164:167], v[204:207], v[2:5]
	v_mfma_i32_16x16x64_i8 v[58:61], v[160:163], v[182:185], v[58:61]
	v_mfma_i32_16x16x64_i8 v[50:53], v[168:171], v[182:185], v[50:53]
	v_mfma_i32_16x16x64_i8 v[42:45], v[160:163], v[190:193], v[42:45]
	v_mfma_i32_16x16x64_i8 v[34:37], v[168:171], v[190:193], v[34:37]
	v_mfma_i32_16x16x64_i8 v[26:29], v[160:163], v[198:201], v[26:29]
	v_mfma_i32_16x16x64_i8 v[18:21], v[168:171], v[198:201], v[18:21]
	v_mfma_i32_16x16x64_i8 v[10:13], v[160:163], v[208:211], v[10:13]
	v_mfma_i32_16x16x64_i8 v[2:5], v[168:171], v[208:211], v[2:5]
	s_barrier
	v_add_u32_e32 v139, 0x18000, v137
	ds_read_b128 v[140:143], v139
	ds_read_b128 v[144:147], v139 offset:1024
	ds_read_b128 v[148:151], v139 offset:2048
	ds_read_b128 v[152:155], v139 offset:3072
	v_add_u32_e32 v139, 0x1c000, v137
	ds_read_b128 v[156:159], v139
	ds_read_b128 v[160:163], v139 offset:1024
	ds_read_b128 v[164:167], v139 offset:2048
	ds_read_b128 v[168:171], v139 offset:3072
	ds_read_b128 v[172:175], v138 offset:32768
	ds_read_b128 v[182:185], v138 offset:33792
	ds_read_b128 v[186:189], v138 offset:34816
	ds_read_b128 v[190:193], v138 offset:35840
	ds_read_b128 v[194:197], v138 offset:36864
	ds_read_b128 v[198:201], v138 offset:37888
	ds_read_b128 v[204:207], v138 offset:38912
	ds_read_b128 v[208:211], v138 offset:39936
	s_add_u32 s66, s28, 0x80000
	s_addc_u32 s67, s29, 0
	s_mov_b32 m0, s46
	s_nop 0
	global_load_lds_dwordx4 v1, s[66:67]
	s_add_u32 s66, s28, 0xc0000
	s_addc_u32 s67, s29, 0
	s_mov_b32 m0, s47
	s_nop 0
	global_load_lds_dwordx4 v1, s[66:67]
	s_waitcnt vmcnt(8)
	s_waitcnt lgkmcnt(0)
	s_barrier
	s_waitcnt lgkmcnt(7)
	v_mfma_i32_16x16x64_i8 v[126:129], v[140:143], v[172:175], v[126:129]
	v_mfma_i32_16x16x64_i8 v[118:121], v[148:151], v[172:175], v[118:121]
	s_waitcnt lgkmcnt(5)
	v_mfma_i32_16x16x64_i8 v[110:113], v[140:143], v[186:189], v[110:113]
	v_mfma_i32_16x16x64_i8 v[102:105], v[148:151], v[186:189], v[102:105]
	s_waitcnt lgkmcnt(3)
	v_mfma_i32_16x16x64_i8 v[94:97], v[140:143], v[194:197], v[94:97]
	v_mfma_i32_16x16x64_i8 v[86:89], v[148:151], v[194:197], v[86:89]
	s_waitcnt lgkmcnt(1)
	v_mfma_i32_16x16x64_i8 v[78:81], v[140:143], v[204:207], v[78:81]
	v_mfma_i32_16x16x64_i8 v[70:73], v[148:151], v[204:207], v[70:73]
	v_mfma_i32_16x16x64_i8 v[126:129], v[144:147], v[182:185], v[126:129]
	v_mfma_i32_16x16x64_i8 v[118:121], v[152:155], v[182:185], v[118:121]
	v_mfma_i32_16x16x64_i8 v[110:113], v[144:147], v[190:193], v[110:113]
	v_mfma_i32_16x16x64_i8 v[102:105], v[152:155], v[190:193], v[102:105]
	v_mfma_i32_16x16x64_i8 v[94:97], v[144:147], v[198:201], v[94:97]
	v_mfma_i32_16x16x64_i8 v[86:89], v[152:155], v[198:201], v[86:89]
	s_waitcnt lgkmcnt(0)
	v_mfma_i32_16x16x64_i8 v[78:81], v[144:147], v[208:211], v[78:81]
	v_mfma_i32_16x16x64_i8 v[70:73], v[152:155], v[208:211], v[70:73]
	v_mfma_i32_16x16x64_i8 v[122:125], v[156:159], v[172:175], v[122:125]
	v_mfma_i32_16x16x64_i8 v[114:117], v[164:167], v[172:175], v[114:117]
	v_mfma_i32_16x16x64_i8 v[106:109], v[156:159], v[186:189], v[106:109]
	v_mfma_i32_16x16x64_i8 v[98:101], v[164:167], v[186:189], v[98:101]
	v_mfma_i32_16x16x64_i8 v[90:93], v[156:159], v[194:197], v[90:93]
	v_mfma_i32_16x16x64_i8 v[82:85], v[164:167], v[194:197], v[82:85]
	v_mfma_i32_16x16x64_i8 v[74:77], v[156:159], v[204:207], v[74:77]
	v_mfma_i32_16x16x64_i8 v[66:69], v[164:167], v[204:207], v[66:69]
	v_mfma_i32_16x16x64_i8 v[122:125], v[160:163], v[182:185], v[122:125]
	v_mfma_i32_16x16x64_i8 v[114:117], v[168:171], v[182:185], v[114:117]
	v_mfma_i32_16x16x64_i8 v[106:109], v[160:163], v[190:193], v[106:109]
	v_mfma_i32_16x16x64_i8 v[98:101], v[168:171], v[190:193], v[98:101]
	v_mfma_i32_16x16x64_i8 v[90:93], v[160:163], v[198:201], v[90:93]
	v_mfma_i32_16x16x64_i8 v[82:85], v[168:171], v[198:201], v[82:85]
	v_mfma_i32_16x16x64_i8 v[74:77], v[160:163], v[208:211], v[74:77]
	v_mfma_i32_16x16x64_i8 v[66:69], v[168:171], v[208:211], v[66:69]
	s_barrier
; #define PG8_STAGE(bufoff, gbase, X) do { _Pragma("unroll") for (int _i = 0; _i < 2; ++_i) { \
;         const char* gp_ = (const char*)(gbase) + (_i ? rs##X : (size_t)0); const unsigned la_ = (unsigned)(size_t)(lds + (bufoff) + ldsw + _i * 8192); \
;         asm volatile("s_mov_b32 m0, %2\n\ts_nop 0\n\tglobal_load_lds_dwordx4 %0, %1" :: "v"(voff##X), "s"(gp_), "s"(la_) : "memory", "m0"); } } while (0)
; #define PG8_LDA(dst, b, h) do { _Pragma("unroll") for (int m = 0; m < 4; ++m) _Pragma("unroll") for (int k = 0; k < 2; ++k) dst[m][k] = *(const LAS bf16x8*)(lds + PG8_SA(b, h) + aoff + m * 2048 + k * 1024); } while (0)
; #define PG8_WAIT_V(n) asm volatile("s_waitcnt vmcnt(" #n ")" ::: "memory")
; #define PG8_WAIT_L(n) asm volatile("s_waitcnt lgkmcnt(" #n ")" ::: "memory")
; #define PG8_BAR __builtin_amdgcn_s_barrier()
; #define PG8_SCHED __builtin_amdgcn_sched_barrier(0)
; template <class Epi>
; __device__ __forceinline__ void gemm_phase(LAS unsigned char* lds, const Gemm g_in, const StaticOrder& S, const Epi& E) {
;     ...
;             PG8_LDA(At, 1, 1); PG8_STAGE(PG8_SB(1, 0), b3, B); PG8_STAGE(PG8_SB(1, 1), b3 + hsB, B); PG8_STAGE(PG8_SA(1, 0), a3, A);
;             PG8_WAIT_V(8); PG8_WAIT_L(0); PG8_BAR; PG8_MMA(1, 0, At, B0); PG8_MMA(1, 1, At, B1); PG8_BAR; PG8_SCHED;
;         }
	s_add_u32 s66, s34, 0x80
	s_addc_u32 s67, s35, 0
	ds_read_b128 v[172:175], v138 offset:49152
	ds_read_b128 v[182:185], v138 offset:50176
	ds_read_b128 v[186:189], v138 offset:51200
	ds_read_b128 v[190:193], v138 offset:52224
	ds_read_b128 v[194:197], v138 offset:53248
	ds_read_b128 v[198:201], v138 offset:54272
	ds_read_b128 v[204:207], v138 offset:55296
	ds_read_b128 v[208:211], v138 offset:56320
	s_mov_b32 m0, s50
	s_nop 0
	global_load_lds_dwordx4 v134, s[66:67]
	s_add_u32 s66, s34, 0x40080
	s_addc_u32 s67, s35, 0
	s_mov_b32 m0, s51
	s_nop 0
	global_load_lds_dwordx4 v134, s[66:67]
	s_add_u32 s66, s34, 0x80080
	s_addc_u32 s67, s35, 0
	s_mov_b32 m0, s54
	s_nop 0
	global_load_lds_dwordx4 v134, s[66:67]
	s_add_u32 s34, s34, 0xc0080
	s_addc_u32 s35, s35, 0
	s_mov_b32 m0, s55
	s_nop 0
	global_load_lds_dwordx4 v134, s[34:35]
	s_add_u32 s28, s28, 0x40080
	s_mov_b32 m0, s52
	s_nop 0
	global_load_lds_dwordx4 v1, s[30:31]
	s_addc_u32 s29, s29, 0
	s_mov_b32 m0, s53
	s_nop 0
	global_load_lds_dwordx4 v1, s[28:29]
	s_waitcnt vmcnt(8)
	s_waitcnt lgkmcnt(0)
	s_barrier
	s_waitcnt lgkmcnt(7)
	v_mfma_i32_16x16x64_i8 v[62:65], v[140:143], v[172:175], v[62:65]
	v_mfma_i32_16x16x64_i8 v[54:57], v[148:151], v[172:175], v[54:57]
	s_waitcnt lgkmcnt(5)
	v_mfma_i32_16x16x64_i8 v[46:49], v[140:143], v[186:189], v[46:49]
	v_mfma_i32_16x16x64_i8 v[38:41], v[148:151], v[186:189], v[38:41]
	s_waitcnt lgkmcnt(3)
	v_mfma_i32_16x16x64_i8 v[30:33], v[140:143], v[194:197], v[30:33]
	v_mfma_i32_16x16x64_i8 v[22:25], v[148:151], v[194:197], v[22:25]
	s_waitcnt lgkmcnt(1)
	v_mfma_i32_16x16x64_i8 v[14:17], v[140:143], v[204:207], v[14:17]
	v_mfma_i32_16x16x64_i8 v[6:9], v[148:151], v[204:207], v[6:9]
	v_mfma_i32_16x16x64_i8 v[62:65], v[144:147], v[182:185], v[62:65]
	v_mfma_i32_16x16x64_i8 v[54:57], v[152:155], v[182:185], v[54:57]
	v_mfma_i32_16x16x64_i8 v[46:49], v[144:147], v[190:193], v[46:49]
	v_mfma_i32_16x16x64_i8 v[38:41], v[152:155], v[190:193], v[38:41]
	v_mfma_i32_16x16x64_i8 v[30:33], v[144:147], v[198:201], v[30:33]
	v_mfma_i32_16x16x64_i8 v[22:25], v[152:155], v[198:201], v[22:25]
	s_waitcnt lgkmcnt(0)
	v_mfma_i32_16x16x64_i8 v[14:17], v[144:147], v[208:211], v[14:17]
	v_mfma_i32_16x16x64_i8 v[6:9], v[152:155], v[208:211], v[6:9]
	v_mfma_i32_16x16x64_i8 v[58:61], v[156:159], v[172:175], v[58:61]
	v_mfma_i32_16x16x64_i8 v[50:53], v[164:167], v[172:175], v[50:53]
	v_mfma_i32_16x16x64_i8 v[42:45], v[156:159], v[186:189], v[42:45]
	v_mfma_i32_16x16x64_i8 v[34:37], v[164:167], v[186:189], v[34:37]
	v_mfma_i32_16x16x64_i8 v[26:29], v[156:159], v[194:197], v[26:29]
	v_mfma_i32_16x16x64_i8 v[18:21], v[164:167], v[194:197], v[18:21]
	v_mfma_i32_16x16x64_i8 v[10:13], v[156:159], v[204:207], v[10:13]
	v_mfma_i32_16x16x64_i8 v[2:5], v[164:167], v[204:207], v[2:5]
	v_mfma_i32_16x16x64_i8 v[58:61], v[160:163], v[182:185], v[58:61]
	v_mfma_i32_16x16x64_i8 v[50:53], v[168:171], v[182:185], v[50:53]
	v_mfma_i32_16x16x64_i8 v[42:45], v[160:163], v[190:193], v[42:45]
	v_mfma_i32_16x16x64_i8 v[34:37], v[168:171], v[190:193], v[34:37]
	v_mfma_i32_16x16x64_i8 v[26:29], v[160:163], v[198:201], v[26:29]
	v_mfma_i32_16x16x64_i8 v[18:21], v[168:171], v[198:201], v[18:21]
	v_mfma_i32_16x16x64_i8 v[10:13], v[160:163], v[208:211], v[10:13]
	v_mfma_i32_16x16x64_i8 v[2:5], v[168:171], v[208:211], v[2:5]
	s_barrier
	s_add_u32 s62, s62, 0x100
	s_addc_u32 s63, s63, 0
	s_add_u32 s26, s26, 0x100
	s_addc_u32 s27, s27, 0
	s_cmp_ge_i32 s64, s37
	s_mov_b32 s28, s64
	s_cbranch_scc0 .LBB0_1510
	s_and_b64 vcc, exec, s[14:15]
	s_cbranch_vccz .LBB0_1513

; #define PG8_STAGE(bufoff, gbase, X) do { _Pragma("unroll") for (int _i = 0; _i < 2; ++_i) { \
;         const char* gp_ = (const char*)(gbase) + (_i ? rs##X : (size_t)0); const unsigned la_ = (unsigned)(size_t)(lds + (bufoff) + ldsw + _i * 8192); \
;         asm volatile("s_mov_b32 m0, %2\n\ts_nop 0\n\tglobal_load_lds_dwordx4 %0, %1" :: "v"(voff##X), "s"(gp_), "s"(la_) : "memory", "m0"); } } while (0)
; #define PG8_LDA(dst, b, h) do { _Pragma("unroll") for (int m = 0; m < 4; ++m) _Pragma("unroll") for (int k = 0; k < 2; ++k) dst[m][k] = *(const LAS bf16x8*)(lds + PG8_SA(b, h) + aoff + m * 2048 + k * 1024); } while (0)
; #define PG8_LDB(dst, b, h) do { _Pragma("unroll") for (int n = 0; n < 2; ++n) _Pragma("unroll") for (int k = 0; k < 2; ++k) dst[n][k] = *(const LAS bf16x8*)(lds + PG8_SB(b, h) + boff + n * 2048 + k * 1024); } while (0)
; #define PG8_WAIT_V(n) asm volatile("s_waitcnt vmcnt(" #n ")" ::: "memory")
; template <class Epi>
; __device__ __forceinline__ void gemm_phase(LAS unsigned char* lds, const Gemm g_in, const StaticOrder& S, const Epi& E) {
;     ...
;         const bool has_next = S.next(ui + 1, nxt);
;         const char* nA = has_next ? (const char*)g.A + (size_t)nxt.pm * tsA : cA; const char* nB = has_next ? (const char*)g.Bt + (size_t)nxt.pn * tsB : cB;
;         for (int t = 0; t < nt; t += 2) {
;             const bool last = (t == nt - 2);
;             const char* a1 = cA + (size_t)(t + 1) * kstep;
;             const char* a2 = last ? nA : cA + (size_t)(t + 2) * kstep; const char* b2 = last ? nB : cB + (size_t)(t + 2) * kstep;
;             const char* a3 = a2 + kstep; const char* b3 = b2 + kstep;
;             PG8_LDB(B0, 0, 0); PG8_LDB(B1, 0, 1); PG8_SCHED; PG8_LDA(At, 0, 0); PG8_STAGE(PG8_SA(1, 1), a1 + hsA, A);
;             PG8_WAIT_V(8); PG8_WAIT_L(0); PG8_BAR; PG8_MMA(0, 0, At, B0); PG8_MMA(0, 1, At, B1); PG8_BAR; PG8_SCHED;
;             PG8_LDA(At, 0, 1); PG8_STAGE(PG8_SB(0, 0), b2, B); PG8_STAGE(PG8_SB(0, 1), b2 + hsB, B); PG8_STAGE(PG8_SA(0, 0), a2, A);
;             PG8_WAIT_V(8); PG8_WAIT_L(0); PG8_BAR; PG8_MMA(1, 0, At, B0); PG8_MMA(1, 1, At, B1); PG8_BAR; PG8_SCHED;
;             PG8_LDB(B0, 1, 0); PG8_LDB(B1, 1, 1); PG8_SCHED; PG8_LDA(At, 1, 0); PG8_STAGE(PG8_SA(0, 1), a2 + hsA, A);
;             PG8_WAIT_V(8); PG8_WAIT_L(0); PG8_BAR; PG8_MMA(0, 0, At, B0); PG8_MMA(0, 1, At, B1); PG8_BAR; PG8_SCHED;
.LBB0_1590:
	ds_read_b128 v[26:29], v198
	ds_read_b128 v[30:33], v198 offset:1024
	ds_read_b128 v[18:21], v198 offset:2048
	ds_read_b128 v[22:25], v198 offset:3072
	ds_read_b128 v[10:13], v199
	ds_read_b128 v[14:17], v199 offset:1024
	ds_read_b128 v[2:5], v199 offset:2048
	ds_read_b128 v[6:9], v199 offset:3072
	s_add_i32 s70, s38, 2
	s_add_u32 s40, s0, 0xffdfc080
	s_addc_u32 s39, s1, -1
	s_cmp_eq_u32 s61, s38
	s_cselect_b32 s38, s12, s40
	s_cselect_b32 s39, s13, s39
	s_cselect_b32 s42, s36, s68
	s_cselect_b32 s43, s37, s69
	s_add_u32 s40, s38, 0x80
	s_addc_u32 s41, s39, 0
	ds_read_b128 v[166:169], v200
	ds_read_b128 v[170:173], v200 offset:1024
	ds_read_b128 v[180:183], v200 offset:2048
	ds_read_b128 v[184:187], v200 offset:3072
	ds_read_b128 v[188:191], v200 offset:4096
	ds_read_b128 v[192:195], v200 offset:5120
	ds_read_b128 v[204:207], v200 offset:6144
	ds_read_b128 v[208:211], v200 offset:7168
	s_add_u32 s72, s0, 0xfff54000
	s_addc_u32 s73, s1, -1
	s_mov_b32 m0, s62
	s_nop 0
	global_load_lds_dwordx4 v1, s[72:73]
	s_nop 0
	s_mov_b32 m0, s63
	s_nop 0
	global_load_lds_dwordx4 v1, s[0:1]
	s_waitcnt vmcnt(8)
	s_waitcnt lgkmcnt(0)
	s_barrier
	s_waitcnt lgkmcnt(0)
	v_mfma_f32_16x16x128_f8f6f4 v[82:85], v[26:33], v[166:173], v[82:85]
	v_mfma_f32_16x16x128_f8f6f4 v[110:113], v[18:25], v[166:173], v[110:113]
	s_waitcnt lgkmcnt(4)
	v_mfma_f32_16x16x128_f8f6f4 v[78:81], v[26:33], v[180:187], v[78:81]
	v_mfma_f32_16x16x128_f8f6f4 v[74:77], v[18:25], v[180:187], v[74:77]
	s_waitcnt lgkmcnt(2)
	v_mfma_f32_16x16x128_f8f6f4 v[62:65], v[26:33], v[188:195], v[62:65]
	v_mfma_f32_16x16x128_f8f6f4 v[58:61], v[18:25], v[188:195], v[58:61]
	s_waitcnt lgkmcnt(0)
	v_mfma_f32_16x16x128_f8f6f4 v[46:49], v[26:33], v[204:211], v[46:49]
	v_mfma_f32_16x16x128_f8f6f4 v[42:45], v[18:25], v[204:211], v[42:45]
	v_mfma_f32_16x16x128_f8f6f4 v[158:161], v[10:17], v[166:173], v[158:161]
	v_mfma_f32_16x16x128_f8f6f4 v[154:157], v[2:9], v[166:173], v[154:157]
	v_mfma_f32_16x16x128_f8f6f4 v[142:145], v[10:17], v[180:187], v[142:145]
	v_mfma_f32_16x16x128_f8f6f4 v[138:141], v[2:9], v[180:187], v[138:141]
	v_mfma_f32_16x16x128_f8f6f4 v[126:129], v[10:17], v[188:195], v[126:129]
	v_mfma_f32_16x16x128_f8f6f4 v[122:125], v[2:9], v[188:195], v[122:125]
	v_mfma_f32_16x16x128_f8f6f4 v[106:109], v[10:17], v[204:211], v[106:109]
	v_mfma_f32_16x16x128_f8f6f4 v[102:105], v[2:9], v[204:211], v[102:105]
	s_barrier
	s_add_u32 s72, s42, 0xac000
	ds_read_b128 v[166:169], v200 offset:16384
	ds_read_b128 v[170:173], v200 offset:17408
	ds_read_b128 v[180:183], v200 offset:18432
	ds_read_b128 v[184:187], v200 offset:19456
	ds_read_b128 v[188:191], v200 offset:20480
	ds_read_b128 v[192:195], v200 offset:21504
	ds_read_b128 v[204:207], v200 offset:22528
	ds_read_b128 v[208:211], v200 offset:23552
	s_mov_b32 m0, s48
	s_nop 0
	global_load_lds_dwordx4 v179, s[42:43]
	s_addc_u32 s73, s43, 0
	s_mov_b32 m0, s49
	s_nop 0
	global_load_lds_dwordx4 v179, s[72:73]
	s_add_u32 s72, s42, 0x158000
	s_addc_u32 s73, s43, 0
	s_mov_b32 m0, s50
	s_nop 0
	global_load_lds_dwordx4 v179, s[72:73]
	s_add_u32 s72, s42, 0x204000
	s_addc_u32 s73, s43, 0
	s_mov_b32 m0, s51
	s_nop 0
	global_load_lds_dwordx4 v179, s[72:73]
	s_add_u32 s72, s38, 0xac000
	s_mov_b32 m0, s47
	s_nop 0
	global_load_lds_dwordx4 v1, s[38:39]
	s_addc_u32 s73, s39, 0
	s_mov_b32 m0, s52
	s_nop 0
	global_load_lds_dwordx4 v1, s[72:73]
	s_waitcnt vmcnt(8)
	s_waitcnt lgkmcnt(0)
	s_barrier
	s_waitcnt lgkmcnt(0)
	v_mfma_f32_16x16x128_f8f6f4 v[98:101], v[26:33], v[166:173], v[98:101]
	v_mfma_f32_16x16x128_f8f6f4 v[94:97], v[18:25], v[166:173], v[94:97]
	s_waitcnt lgkmcnt(4)
	v_mfma_f32_16x16x128_f8f6f4 v[70:73], v[26:33], v[180:187], v[70:73]
	v_mfma_f32_16x16x128_f8f6f4 v[66:69], v[18:25], v[180:187], v[66:69]
	s_waitcnt lgkmcnt(2)
	v_mfma_f32_16x16x128_f8f6f4 v[54:57], v[26:33], v[188:195], v[54:57]
	v_mfma_f32_16x16x128_f8f6f4 v[50:53], v[18:25], v[188:195], v[50:53]
	s_waitcnt lgkmcnt(0)
	v_mfma_f32_16x16x128_f8f6f4 v[38:41], v[26:33], v[204:211], v[38:41]
	v_mfma_f32_16x16x128_f8f6f4 v[34:37], v[18:25], v[204:211], v[34:37]
	v_mfma_f32_16x16x128_f8f6f4 v[150:153], v[10:17], v[166:173], v[150:153]
	v_mfma_f32_16x16x128_f8f6f4 v[146:149], v[2:9], v[166:173], v[146:149]
	v_mfma_f32_16x16x128_f8f6f4 v[134:137], v[10:17], v[180:187], v[134:137]
	v_mfma_f32_16x16x128_f8f6f4 v[130:133], v[2:9], v[180:187], v[130:133]
	v_mfma_f32_16x16x128_f8f6f4 v[118:121], v[10:17], v[188:195], v[118:121]
	v_mfma_f32_16x16x128_f8f6f4 v[114:117], v[2:9], v[188:195], v[114:117]
	v_mfma_f32_16x16x128_f8f6f4 v[90:93], v[10:17], v[204:211], v[90:93]
	v_mfma_f32_16x16x128_f8f6f4 v[86:89], v[2:9], v[204:211], v[86:89]
	s_barrier
	ds_read_b128 v[18:21], v201
	ds_read_b128 v[22:25], v201 offset:1024
	ds_read_b128 v[26:29], v201 offset:2048
	ds_read_b128 v[30:33], v201 offset:3072
	ds_read_b128 v[10:13], v203
	ds_read_b128 v[14:17], v203 offset:1024
	ds_read_b128 v[2:5], v203 offset:2048
	ds_read_b128 v[6:9], v203 offset:3072
	ds_read_b128 v[166:169], v200 offset:32768
	ds_read_b128 v[170:173], v200 offset:33792
	ds_read_b128 v[180:183], v200 offset:34816
	ds_read_b128 v[184:187], v200 offset:35840
	ds_read_b128 v[188:191], v200 offset:36864
	ds_read_b128 v[192:195], v200 offset:37888
	ds_read_b128 v[204:207], v200 offset:38912
	ds_read_b128 v[208:211], v200 offset:39936
	s_add_u32 s72, s38, 0x158000
	s_addc_u32 s73, s39, 0
	s_mov_b32 m0, s53
	s_nop 0
	global_load_lds_dwordx4 v1, s[72:73]
	s_add_u32 s72, s38, 0x204000
	s_addc_u32 s73, s39, 0
	s_mov_b32 m0, s54
	s_nop 0
	global_load_lds_dwordx4 v1, s[72:73]
	s_waitcnt vmcnt(8)
	s_waitcnt lgkmcnt(0)
	s_barrier
; #define PG8_STAGE(bufoff, gbase, X) do { _Pragma("unroll") for (int _i = 0; _i < 2; ++_i) { \
;         const char* gp_ = (const char*)(gbase) + (_i ? rs##X : (size_t)0); const unsigned la_ = (unsigned)(size_t)(lds + (bufoff) + ldsw + _i * 8192); \
;         asm volatile("s_mov_b32 m0, %2\n\ts_nop 0\n\tglobal_load_lds_dwordx4 %0, %1" :: "v"(voff##X), "s"(gp_), "s"(la_) : "memory", "m0"); } } while (0)
; #define PG8_LDA(dst, b, h) do { _Pragma("unroll") for (int m = 0; m < 4; ++m) _Pragma("unroll") for (int k = 0; k < 2; ++k) dst[m][k] = *(const LAS bf16x8*)(lds + PG8_SA(b, h) + aoff + m * 2048 + k * 1024); } while (0)
; #define PG8_WAIT_V(n) asm volatile("s_waitcnt vmcnt(" #n ")" ::: "memory")
; #define PG8_WAIT_L(n) asm volatile("s_waitcnt lgkmcnt(" #n ")" ::: "memory")
; #define PG8_BAR __builtin_amdgcn_s_barrier()
; #define PG8_SCHED __builtin_amdgcn_sched_barrier(0)
; template <class Epi>
; __device__ __forceinline__ void gemm_phase(LAS unsigned char* lds, const Gemm g_in, const StaticOrder& S, const Epi& E) {
;     ...
;             PG8_WAIT_V(8); PG8_WAIT_L(0); PG8_BAR; PG8_MMA(0, 0, At, B0); PG8_MMA(0, 1, At, B1); PG8_BAR; PG8_SCHED;
;             PG8_LDA(At, 1, 1); PG8_STAGE(PG8_SB(1, 0), b3, B); PG8_STAGE(PG8_SB(1, 1), b3 + hsB, B); PG8_STAGE(PG8_SA(1, 0), a3, A);
;             PG8_WAIT_V(8); PG8_WAIT_L(0); PG8_BAR; PG8_MMA(1, 0, At, B0); PG8_MMA(1, 1, At, B1); PG8_BAR; PG8_SCHED;
;         }
	s_waitcnt lgkmcnt(0)
	v_mfma_f32_16x16x128_f8f6f4 v[82:85], v[18:25], v[166:173], v[82:85]
	v_mfma_f32_16x16x128_f8f6f4 v[110:113], v[26:33], v[166:173], v[110:113]
	s_waitcnt lgkmcnt(4)
	v_mfma_f32_16x16x128_f8f6f4 v[78:81], v[18:25], v[180:187], v[78:81]
	v_mfma_f32_16x16x128_f8f6f4 v[74:77], v[26:33], v[180:187], v[74:77]
	s_waitcnt lgkmcnt(2)
	v_mfma_f32_16x16x128_f8f6f4 v[62:65], v[18:25], v[188:195], v[62:65]
	v_mfma_f32_16x16x128_f8f6f4 v[58:61], v[26:33], v[188:195], v[58:61]
	s_waitcnt lgkmcnt(0)
	v_mfma_f32_16x16x128_f8f6f4 v[46:49], v[18:25], v[204:211], v[46:49]
	v_mfma_f32_16x16x128_f8f6f4 v[42:45], v[26:33], v[204:211], v[42:45]
	v_mfma_f32_16x16x128_f8f6f4 v[158:161], v[10:17], v[166:173], v[158:161]
	v_mfma_f32_16x16x128_f8f6f4 v[154:157], v[2:9], v[166:173], v[154:157]
	v_mfma_f32_16x16x128_f8f6f4 v[142:145], v[10:17], v[180:187], v[142:145]
	v_mfma_f32_16x16x128_f8f6f4 v[138:141], v[2:9], v[180:187], v[138:141]
	v_mfma_f32_16x16x128_f8f6f4 v[126:129], v[10:17], v[188:195], v[126:129]
	v_mfma_f32_16x16x128_f8f6f4 v[122:125], v[2:9], v[188:195], v[122:125]
	v_mfma_f32_16x16x128_f8f6f4 v[106:109], v[10:17], v[204:211], v[106:109]
	v_mfma_f32_16x16x128_f8f6f4 v[102:105], v[2:9], v[204:211], v[102:105]
	s_barrier
	s_add_u32 s72, s42, 0x80
	s_addc_u32 s73, s43, 0
	ds_read_b128 v[166:169], v200 offset:49152
	ds_read_b128 v[170:173], v200 offset:50176
	ds_read_b128 v[180:183], v200 offset:51200
	ds_read_b128 v[184:187], v200 offset:52224
	ds_read_b128 v[188:191], v200 offset:53248
	ds_read_b128 v[192:195], v200 offset:54272
	ds_read_b128 v[204:207], v200 offset:55296
	ds_read_b128 v[208:211], v200 offset:56320
	s_mov_b32 m0, s55
	s_nop 0
	global_load_lds_dwordx4 v179, s[72:73]
	s_add_u32 s72, s42, 0xac080
	s_addc_u32 s73, s43, 0
	s_mov_b32 m0, s56
	s_nop 0
	global_load_lds_dwordx4 v179, s[72:73]
	s_add_u32 s72, s42, 0x158080
	s_addc_u32 s73, s43, 0
	s_mov_b32 m0, s59
	s_nop 0
	global_load_lds_dwordx4 v179, s[72:73]
	s_add_u32 s42, s42, 0x204080
	s_addc_u32 s43, s43, 0
	s_mov_b32 m0, s60
	s_nop 0
	global_load_lds_dwordx4 v179, s[42:43]
	s_add_u32 s38, s38, 0xac080
	s_mov_b32 m0, s57
	s_nop 0
	global_load_lds_dwordx4 v1, s[40:41]
	s_addc_u32 s39, s39, 0
	s_mov_b32 m0, s58
	s_nop 0
	global_load_lds_dwordx4 v1, s[38:39]
	s_waitcnt vmcnt(8)
	s_waitcnt lgkmcnt(0)
	s_barrier
	s_waitcnt lgkmcnt(0)
	v_mfma_f32_16x16x128_f8f6f4 v[98:101], v[18:25], v[166:173], v[98:101]
	v_mfma_f32_16x16x128_f8f6f4 v[94:97], v[26:33], v[166:173], v[94:97]
	s_waitcnt lgkmcnt(4)
	v_mfma_f32_16x16x128_f8f6f4 v[70:73], v[18:25], v[180:187], v[70:73]
	v_mfma_f32_16x16x128_f8f6f4 v[66:69], v[26:33], v[180:187], v[66:69]
	s_waitcnt lgkmcnt(2)
	v_mfma_f32_16x16x128_f8f6f4 v[54:57], v[18:25], v[188:195], v[54:57]
	v_mfma_f32_16x16x128_f8f6f4 v[50:53], v[26:33], v[188:195], v[50:53]
	s_waitcnt lgkmcnt(0)
	v_mfma_f32_16x16x128_f8f6f4 v[38:41], v[18:25], v[204:211], v[38:41]
	v_mfma_f32_16x16x128_f8f6f4 v[34:37], v[26:33], v[204:211], v[34:37]
	v_mfma_f32_16x16x128_f8f6f4 v[150:153], v[10:17], v[166:173], v[150:153]
	v_mfma_f32_16x16x128_f8f6f4 v[146:149], v[2:9], v[166:173], v[146:149]
	v_mfma_f32_16x16x128_f8f6f4 v[134:137], v[10:17], v[180:187], v[134:137]
	v_mfma_f32_16x16x128_f8f6f4 v[130:133], v[2:9], v[180:187], v[130:133]
	v_mfma_f32_16x16x128_f8f6f4 v[118:121], v[10:17], v[188:195], v[118:121]
	v_mfma_f32_16x16x128_f8f6f4 v[114:117], v[2:9], v[188:195], v[114:117]
	v_mfma_f32_16x16x128_f8f6f4 v[90:93], v[10:17], v[204:211], v[90:93]
	v_mfma_f32_16x16x128_f8f6f4 v[86:89], v[2:9], v[204:211], v[86:89]
	s_barrier
	s_add_u32 s68, s68, 0x100
	s_addc_u32 s69, s69, 0
	s_add_u32 s0, s0, 0x100
	s_addc_u32 s1, s1, 0
	s_cmp_ge_i32 s70, s44
	s_mov_b32 s38, s70
	s_cbranch_scc0 .LBB0_1590
;     __device__ __forceinline__ void operator()(const f32x4 (&acc)[2][2][4][2], const Unit& u, int wr, int wc, int fr, int fq) const {
;     ...
;                     for (int bj = 0; bj < 2; ++bj) { f32x4 a0 = acc[ai][bj][m][0], a1 = acc[ai][bj][m][1];
;                         if (IN == 2) { a0 = __builtin_convertvector(__builtin_bit_cast(i32x4, a0), f32x4); a1 = __builtin_convertvector(__builtin_bit_cast(i32x4, a1), f32x4); }
;                         const f32x4 v0 = bv[m][bj][0] * ALPHA + a0 * scale, v1 = bv[m][bj][1] * ALPHA + a1 * scale;
	v_pk_mul_f32 v[194:195], v[84:85], s[22:23] op_sel_hi:[1,0]
	v_pk_mul_f32 v[192:193], v[82:83], s[22:23] op_sel_hi:[1,0]
	v_pk_mul_f32 v[190:191], v[112:113], s[22:23] op_sel_hi:[1,0]
	v_pk_mul_f32 v[188:189], v[110:111], s[22:23] op_sel_hi:[1,0]
	v_pk_mul_f32 v[184:185], v[160:161], s[22:23] op_sel_hi:[1,0]
	v_pk_mul_f32 v[180:181], v[158:159], s[22:23] op_sel_hi:[1,0]
	v_pk_mul_f32 v[174:175], v[156:157], s[22:23] op_sel_hi:[1,0]
	v_pk_mul_f32 v[170:171], v[154:155], s[22:23] op_sel_hi:[1,0]
	v_pk_mul_f32 v[186:187], v[80:81], s[22:23] op_sel_hi:[1,0]
	v_pk_mul_f32 v[182:183], v[78:79], s[22:23] op_sel_hi:[1,0]
	v_pk_mul_f32 v[176:177], v[76:77], s[22:23] op_sel_hi:[1,0]
	v_pk_mul_f32 v[172:173], v[74:75], s[22:23] op_sel_hi:[1,0]
	v_pk_mul_f32 v[166:167], v[144:145], s[22:23] op_sel_hi:[1,0]
	v_pk_mul_f32 v[158:159], v[142:143], s[22:23] op_sel_hi:[1,0]
	v_pk_mul_f32 v[154:155], v[140:141], s[22:23] op_sel_hi:[1,0]
	v_pk_mul_f32 v[142:143], v[138:139], s[22:23] op_sel_hi:[1,0]
	v_pk_mul_f32 v[168:169], v[64:65], s[22:23] op_sel_hi:[1,0]
	v_pk_mul_f32 v[160:161], v[62:63], s[22:23] op_sel_hi:[1,0]
	v_pk_mul_f32 v[156:157], v[60:61], s[22:23] op_sel_hi:[1,0]
	v_pk_mul_f32 v[144:145], v[58:59], s[22:23] op_sel_hi:[1,0]
	v_pk_mul_f32 v[138:139], v[128:129], s[22:23] op_sel_hi:[1,0]
	v_pk_mul_f32 v[126:127], v[126:127], s[22:23] op_sel_hi:[1,0]
	v_pk_mul_f32 v[124:125], v[124:125], s[22:23] op_sel_hi:[1,0]
	v_pk_mul_f32 v[110:111], v[122:123], s[22:23] op_sel_hi:[1,0]
	v_pk_mul_f32 v[140:141], v[48:49], s[22:23] op_sel_hi:[1,0]
	v_pk_mul_f32 v[128:129], v[46:47], s[22:23] op_sel_hi:[1,0]
	v_pk_mul_f32 v[122:123], v[44:45], s[22:23] op_sel_hi:[1,0]
	v_pk_mul_f32 v[112:113], v[42:43], s[22:23] op_sel_hi:[1,0]
	v_pk_mul_f32 v[108:109], v[108:109], s[22:23] op_sel_hi:[1,0]
	v_pk_mul_f32 v[106:107], v[106:107], s[22:23] op_sel_hi:[1,0]
	v_pk_mul_f32 v[104:105], v[104:105], s[22:23] op_sel_hi:[1,0]
	v_pk_mul_f32 v[102:103], v[102:103], s[22:23] op_sel_hi:[1,0]
	v_pk_mul_f32 v[84:85], v[100:101], s[22:23] op_sel_hi:[1,0]
	v_pk_mul_f32 v[82:83], v[98:99], s[22:23] op_sel_hi:[1,0]
	v_pk_mul_f32 v[80:81], v[96:97], s[22:23] op_sel_hi:[1,0]
	v_pk_mul_f32 v[78:79], v[94:95], s[22:23] op_sel_hi:[1,0]
	v_pk_mul_f32 v[76:77], v[152:153], s[22:23] op_sel_hi:[1,0]
	v_pk_mul_f32 v[74:75], v[150:151], s[22:23] op_sel_hi:[1,0]
	v_pk_mul_f32 v[62:63], v[148:149], s[22:23] op_sel_hi:[1,0]
	v_pk_mul_f32 v[58:59], v[146:147], s[22:23] op_sel_hi:[1,0]
	v_pk_mul_f32 v[72:73], v[72:73], s[22:23] op_sel_hi:[1,0]
	v_pk_mul_f32 v[70:71], v[70:71], s[22:23] op_sel_hi:[1,0]
	v_pk_mul_f32 v[64:65], v[68:69], s[22:23] op_sel_hi:[1,0]
	v_pk_mul_f32 v[60:61], v[66:67], s[22:23] op_sel_hi:[1,0]
	v_pk_mul_f32 v[46:47], v[136:137], s[22:23] op_sel_hi:[1,0]
	v_pk_mul_f32 v[42:43], v[134:135], s[22:23] op_sel_hi:[1,0]
	v_pk_mul_f32 v[30:31], v[132:133], s[22:23] op_sel_hi:[1,0]
	v_pk_mul_f32 v[26:27], v[130:131], s[22:23] op_sel_hi:[1,0]
	v_pk_mul_f32 v[48:49], v[56:57], s[22:23] op_sel_hi:[1,0]
	v_pk_mul_f32 v[44:45], v[54:55], s[22:23] op_sel_hi:[1,0]
	v_pk_mul_f32 v[32:33], v[52:53], s[22:23] op_sel_hi:[1,0]
	v_pk_mul_f32 v[28:29], v[50:51], s[22:23] op_sel_hi:[1,0]
	v_pk_mul_f32 v[22:23], v[120:121], s[22:23] op_sel_hi:[1,0]
	v_pk_mul_f32 v[18:19], v[118:119], s[22:23] op_sel_hi:[1,0]
	v_pk_mul_f32 v[14:15], v[116:117], s[22:23] op_sel_hi:[1,0]
	v_pk_mul_f32 v[10:11], v[114:115], s[22:23] op_sel_hi:[1,0]
	v_pk_mul_f32 v[24:25], v[40:41], s[22:23] op_sel_hi:[1,0]
	v_pk_mul_f32 v[20:21], v[38:39], s[22:23] op_sel_hi:[1,0]
	v_pk_mul_f32 v[16:17], v[36:37], s[22:23] op_sel_hi:[1,0]
	v_pk_mul_f32 v[12:13], v[34:35], s[22:23] op_sel_hi:[1,0]
	v_pk_mul_f32 v[8:9], v[92:93], s[22:23] op_sel_hi:[1,0]
	v_pk_mul_f32 v[6:7], v[90:91], s[22:23] op_sel_hi:[1,0]
	v_pk_mul_f32 v[4:5], v[88:89], s[22:23] op_sel_hi:[1,0]
	v_pk_mul_f32 v[2:3], v[86:87], s[22:23] op_sel_hi:[1,0]
	s_and_b64 vcc, exec, s[20:21]
	s_cbranch_vccz .LBB0_1593
